# weight-conversion stores (P0, and the idle-slot conversions in FFN1-in / FFN2-in) made write-through so the following grid barriers find clean L2; plus conv-phase load hoist and write-through XA
# speedup vs baseline: 1.0010x; 1.0001x over previous
.LBB0_17:
	v_mul_u32_u24_e32 v3, 0x84, v8
	v_add3_u32 v9, s63, v2, v3
	v_add_u32_e32 v3, 0x400, v9
	s_waitcnt vmcnt(62)
	ds_write2_b32 v9, v6, v7 offset1:66
	s_waitcnt vmcnt(60)
	ds_write2_b32 v9, v10, v12 offset0:132 offset1:198
	s_waitcnt vmcnt(58)
	ds_write2_b32 v3, v11, v27 offset0:8 offset1:74
	s_waitcnt vmcnt(56)
	ds_write2_b32 v3, v28, v29 offset0:140 offset1:206
	v_add_u32_e32 v3, 0x800, v9
	s_waitcnt vmcnt(54)
	ds_write2_b32 v3, v38, v39 offset0:16 offset1:82
	s_waitcnt vmcnt(52)
	ds_write2_b32 v3, v40, v42 offset0:148 offset1:214
	v_add_u32_e32 v3, 0xc00, v9
	s_waitcnt vmcnt(50)
	ds_write2_b32 v3, v41, v43 offset0:24 offset1:90
	s_waitcnt vmcnt(48)
	ds_write2_b32 v3, v44, v45 offset0:156 offset1:222
	v_add_u32_e32 v3, 0x1000, v9
	s_waitcnt vmcnt(46)
	ds_write2_b32 v3, v54, v55 offset0:32 offset1:98
	s_waitcnt vmcnt(44)
	ds_write2_b32 v3, v56, v58 offset0:164 offset1:230
	v_add_u32_e32 v3, 0x1400, v9
	s_waitcnt vmcnt(42)
	ds_write2_b32 v3, v57, v59 offset0:40 offset1:106
	s_waitcnt vmcnt(40)
	ds_write2_b32 v3, v60, v61 offset0:172 offset1:238
	v_add_u32_e32 v3, 0x1800, v9
	s_waitcnt vmcnt(38)
	ds_write2_b32 v3, v62, v63 offset0:48 offset1:114
	s_waitcnt vmcnt(36)
	ds_write2_b32 v3, v64, v66 offset0:180 offset1:246
	v_add_u32_e32 v3, 0x1c00, v9
	s_waitcnt vmcnt(34)
	ds_write2_b32 v3, v65, v67 offset0:56 offset1:122
	s_waitcnt vmcnt(32)
	ds_write2_b32 v3, v68, v69 offset0:188 offset1:254
	v_lshlrev_b32_e32 v3, 3, v0
	v_lshrrev_b32_e32 v10, 3, v1
	v_and_b32_e32 v3, 56, v3
	s_waitcnt lgkmcnt(0)
	v_mul_u32_u24_e32 v11, 0x84, v3
	v_lshlrev_b32_e32 v6, 1, v3
	v_lshlrev_b32_e32 v3, 2, v10
	v_add3_u32 v11, s63, v11, v3
	s_ashr_i32 s31, s30, 31
	ds_read2_b32 v[28:29], v11 offset0:33 offset1:41
	ds_read2_b32 v[42:43], v11 offset1:8
	ds_read2_b32 v[44:45], v11 offset0:66 offset1:74
	ds_read2_b32 v[54:55], v11 offset0:99 offset1:107
	ds_read2_b32 v[56:57], v11 offset0:132 offset1:140
	ds_read2_b32 v[58:59], v11 offset0:165 offset1:173
	ds_read2_b32 v[60:61], v11 offset0:198 offset1:206
	ds_read2_b32 v[62:63], v11 offset0:231 offset1:239
	s_lshl_b64 s[8:9], s[30:31], 1
	s_add_u32 s8, s2, s8
	v_add_u32_e32 v66, s7, v10
	s_addc_u32 s9, s3, s9
	v_mov_b32_e32 v7, 0
	v_ashrrev_i32_e32 v67, 31, v66
	v_lshl_add_u64 v[64:65], s[8:9], 0, v[6:7]
	v_lshlrev_b64 v[66:67], 11, v[66:67]
	v_or_b32_e32 v12, 8, v10
	s_waitcnt lgkmcnt(6)
	v_cvt_pk_bf16_f32 v38, v42, v28
	s_waitcnt lgkmcnt(4)
	v_cvt_pk_bf16_f32 v39, v44, v54
	s_waitcnt lgkmcnt(2)
	v_cvt_pk_bf16_f32 v40, v56, v58
	s_waitcnt lgkmcnt(0)
	v_cvt_pk_bf16_f32 v41, v60, v62
	v_lshl_add_u64 v[66:67], v[64:65], 0, v[66:67]
	v_add_u32_e32 v28, s7, v12
	global_store_dwordx4 v[66:67], v[38:41], off sc1
	v_or_b32_e32 v27, 16, v10
	v_add_u32_e32 v66, s7, v27
	v_cvt_pk_bf16_f32 v38, v43, v29
	v_ashrrev_i32_e32 v29, 31, v28
	v_lshlrev_b64 v[28:29], 11, v[28:29]
	v_cvt_pk_bf16_f32 v39, v45, v55
	v_cvt_pk_bf16_f32 v40, v57, v59
	v_cvt_pk_bf16_f32 v41, v61, v63
	v_lshl_add_u64 v[28:29], v[64:65], 0, v[28:29]
	global_store_dwordx4 v[28:29], v[38:41], off sc1
	ds_read2_b32 v[28:29], v11 offset0:49 offset1:57
	ds_read2_b32 v[42:43], v11 offset0:16 offset1:24
	ds_read2_b32 v[44:45], v11 offset0:82 offset1:90
	ds_read2_b32 v[54:55], v11 offset0:115 offset1:123
	ds_read2_b32 v[56:57], v11 offset0:148 offset1:156
	ds_read2_b32 v[58:59], v11 offset0:181 offset1:189
	ds_read2_b32 v[60:61], v11 offset0:214 offset1:222
	ds_read2_b32 v[62:63], v11 offset0:247 offset1:255
	v_ashrrev_i32_e32 v67, 31, v66
	s_waitcnt lgkmcnt(6)
	v_cvt_pk_bf16_f32 v38, v42, v28
	v_lshlrev_b64 v[66:67], 11, v[66:67]
	v_or_b32_e32 v28, 24, v10
	s_waitcnt lgkmcnt(4)
	v_cvt_pk_bf16_f32 v39, v44, v54
	s_waitcnt lgkmcnt(2)
	v_cvt_pk_bf16_f32 v40, v56, v58
	s_waitcnt lgkmcnt(0)
	v_cvt_pk_bf16_f32 v41, v60, v62
	v_lshl_add_u64 v[66:67], v[64:65], 0, v[66:67]
	v_add_u32_e32 v42, s7, v28
	global_store_dwordx4 v[66:67], v[38:41], off sc1
	s_andn2_b64 vcc, exec, s[28:29]
	s_nop 0
	v_cvt_pk_bf16_f32 v38, v43, v29
	v_ashrrev_i32_e32 v43, 31, v42
	v_lshlrev_b64 v[42:43], 11, v[42:43]
	v_cvt_pk_bf16_f32 v39, v45, v55
	v_cvt_pk_bf16_f32 v40, v57, v59
	v_cvt_pk_bf16_f32 v41, v61, v63
	v_lshl_add_u64 v[42:43], v[64:65], 0, v[42:43]
	global_store_dwordx4 v[42:43], v[38:41], off sc1
	s_waitcnt lgkmcnt(0)
	s_cbranch_vccnz .LBB0_23
	s_lshl_b32 s8, s5, 6
	s_cmpk_gt_i32 s5, 0x57
	s_cbranch_scc0 .LBB0_20
	s_add_i32 s5, s8, 0x7fffea00
	s_and_b32 s5, s5, 0x7fffff00
	s_and_b32 s7, s6, 0x60
	s_or_b32 s5, s7, s5
	s_or_b32 s7, s5, 0x80
	s_cbranch_execz .LBB0_21
	s_branch .LBB0_22

.LBB0_22:
	v_add_u32_e32 v3, 0x400, v9
	s_waitcnt vmcnt(34)
	ds_write2_b32 v9, v4, v5 offset1:66
	s_waitcnt vmcnt(32)
	ds_write2_b32 v9, v13, v15 offset0:132 offset1:198
	s_waitcnt vmcnt(30)
	ds_write2_b32 v3, v14, v16 offset0:8 offset1:74
	s_waitcnt vmcnt(28)
	ds_write2_b32 v3, v17, v18 offset0:140 offset1:206
	v_add_u32_e32 v3, 0x800, v9
	s_waitcnt vmcnt(26)
	ds_write2_b32 v3, v19, v20 offset0:16 offset1:82
	s_waitcnt vmcnt(24)
	ds_write2_b32 v3, v21, v23 offset0:148 offset1:214
	v_add_u32_e32 v3, 0xc00, v9
	s_waitcnt vmcnt(22)
	ds_write2_b32 v3, v22, v24 offset0:24 offset1:90
	s_waitcnt vmcnt(20)
	ds_write2_b32 v3, v25, v26 offset0:156 offset1:222
	v_add_u32_e32 v3, 0x1000, v9
	s_waitcnt vmcnt(18)
	ds_write2_b32 v3, v30, v31 offset0:32 offset1:98
	s_waitcnt vmcnt(16)
	ds_write2_b32 v3, v32, v34 offset0:164 offset1:230
	v_add_u32_e32 v3, 0x1400, v9
	s_waitcnt vmcnt(14)
	ds_write2_b32 v3, v33, v35 offset0:40 offset1:106
	s_waitcnt vmcnt(12)
	ds_write2_b32 v3, v36, v37 offset0:172 offset1:238
	v_add_u32_e32 v3, 0x1800, v9
	s_waitcnt vmcnt(10)
	ds_write2_b32 v3, v46, v47 offset0:48 offset1:114
	s_waitcnt vmcnt(8)
	ds_write2_b32 v3, v48, v50 offset0:180 offset1:246
	v_add_u32_e32 v3, 0x1c00, v9
	s_waitcnt vmcnt(6)
	ds_write2_b32 v3, v49, v51 offset0:56 offset1:122
	s_waitcnt vmcnt(4)
	ds_write2_b32 v3, v52, v53 offset0:188 offset1:254
	s_waitcnt lgkmcnt(0)
	s_ashr_i32 s5, s4, 31
	ds_read2_b32 v[4:5], v11 offset0:33 offset1:41
	ds_read2_b32 v[18:19], v11 offset1:8
	ds_read2_b32 v[20:21], v11 offset0:66 offset1:74
	ds_read2_b32 v[22:23], v11 offset0:99 offset1:107
	ds_read2_b32 v[24:25], v11 offset0:132 offset1:140
	ds_read2_b32 v[30:31], v11 offset0:165 offset1:173
	ds_read2_b32 v[32:33], v11 offset0:198 offset1:206
	ds_read2_b32 v[34:35], v11 offset0:231 offset1:239
	s_lshl_b64 s[4:5], s[4:5], 1
	s_add_u32 s4, s2, s4
	v_add_u32_e32 v38, s7, v10
	s_addc_u32 s5, s3, s5
	v_mov_b32_e32 v7, 0
	v_ashrrev_i32_e32 v39, 31, v38
	v_lshl_add_u64 v[36:37], s[4:5], 0, v[6:7]
	v_lshlrev_b64 v[38:39], 11, v[38:39]
	s_waitcnt lgkmcnt(6)
	v_cvt_pk_bf16_f32 v14, v18, v4
	s_waitcnt lgkmcnt(4)
	v_cvt_pk_bf16_f32 v15, v20, v22
	s_waitcnt lgkmcnt(2)
	v_cvt_pk_bf16_f32 v16, v24, v30
	s_waitcnt lgkmcnt(0)
	v_cvt_pk_bf16_f32 v17, v32, v34
	v_lshl_add_u64 v[38:39], v[36:37], 0, v[38:39]
	v_add_u32_e32 v4, s7, v12
	global_store_dwordx4 v[38:39], v[14:17], off sc1
	s_nop 1
	v_cvt_pk_bf16_f32 v14, v19, v5
	v_ashrrev_i32_e32 v5, 31, v4
	v_cvt_pk_bf16_f32 v15, v21, v23
	v_cvt_pk_bf16_f32 v16, v25, v31
	v_cvt_pk_bf16_f32 v17, v33, v35
	v_lshlrev_b64 v[4:5], 11, v[4:5]
	ds_read2_b32 v[18:19], v11 offset0:49 offset1:57
	ds_read2_b32 v[20:21], v11 offset0:16 offset1:24
	ds_read2_b32 v[22:23], v11 offset0:82 offset1:90
	ds_read2_b32 v[24:25], v11 offset0:115 offset1:123
	ds_read2_b32 v[30:31], v11 offset0:148 offset1:156
	ds_read2_b32 v[32:33], v11 offset0:181 offset1:189
	ds_read2_b32 v[34:35], v11 offset0:214 offset1:222
	ds_read2_b32 v[38:39], v11 offset0:247 offset1:255
	v_lshl_add_u64 v[4:5], v[36:37], 0, v[4:5]
	global_store_dwordx4 v[4:5], v[14:17], off sc1
	v_add_u32_e32 v4, s7, v27
	v_ashrrev_i32_e32 v5, 31, v4
	v_lshlrev_b64 v[4:5], 11, v[4:5]
	s_waitcnt lgkmcnt(6)
	v_cvt_pk_bf16_f32 v14, v20, v18
	s_waitcnt lgkmcnt(4)
	v_cvt_pk_bf16_f32 v15, v22, v24
	s_waitcnt lgkmcnt(2)
	v_cvt_pk_bf16_f32 v16, v30, v32
	s_waitcnt lgkmcnt(0)
	v_cvt_pk_bf16_f32 v17, v34, v38
	v_lshl_add_u64 v[4:5], v[36:37], 0, v[4:5]
	global_store_dwordx4 v[4:5], v[14:17], off sc1
	v_add_u32_e32 v4, s7, v28
	v_ashrrev_i32_e32 v5, 31, v4
	v_lshlrev_b64 v[4:5], 11, v[4:5]
	v_cvt_pk_bf16_f32 v14, v21, v19
	v_cvt_pk_bf16_f32 v15, v23, v25
	v_cvt_pk_bf16_f32 v16, v31, v33
	v_cvt_pk_bf16_f32 v17, v35, v39
	v_lshl_add_u64 v[4:5], v[36:37], 0, v[4:5]
	global_store_dwordx4 v[4:5], v[14:17], off sc1
	s_waitcnt lgkmcnt(0)

.LBB0_25:
	s_lshl_b32 s4, s7, 6
	s_waitcnt vmcnt(20)
	v_or_b32_e32 v26, s4, v8
	s_ashr_i32 s7, s6, 31
	v_lshl_add_u64 v[18:19], s[6:7], 2, v[4:5]
	v_or_b32_e32 v29, 6, v26
	s_waitcnt vmcnt(18)
	v_mad_i64_i32 v[30:31], s[6:7], v29, s14, v[18:19]
	v_or_b32_e32 v29, 8, v26
	s_waitcnt vmcnt(15)
	v_mad_i64_i32 v[32:33], s[6:7], v29, s14, v[18:19]
	v_or_b32_e32 v29, 10, v26
	s_waitcnt vmcnt(14)
	v_mad_i64_i32 v[34:35], s[6:7], v29, s14, v[18:19]
	v_or_b32_e32 v29, 12, v26
	v_or_b32_e32 v22, 2, v26
	v_or_b32_e32 v24, 4, v26
	s_waitcnt vmcnt(12)
	v_mad_i64_i32 v[36:37], s[6:7], v29, s14, v[18:19]
	v_or_b32_e32 v29, 14, v26
	v_mad_i64_i32 v[20:21], s[6:7], v26, s14, v[18:19]
	v_mad_i64_i32 v[22:23], s[6:7], v22, s14, v[18:19]
	v_mad_i64_i32 v[24:25], s[6:7], v24, s14, v[18:19]
	v_mad_i64_i32 v[38:39], s[6:7], v29, s14, v[18:19]
	global_load_dword v29, v[20:21], off nt
	global_load_dword v40, v[22:23], off nt
	global_load_dword v41, v[24:25], off nt
	global_load_dword v42, v[30:31], off nt
	global_load_dword v43, v[32:33], off nt
	global_load_dword v44, v[34:35], off nt
	global_load_dword v45, v[36:37], off nt
	global_load_dword v46, v[38:39], off nt
	v_or_b32_e32 v20, 16, v26
	v_or_b32_e32 v22, 18, v26
	v_or_b32_e32 v24, 20, v26
	v_or_b32_e32 v30, 22, v26
	v_or_b32_e32 v32, 24, v26
	v_or_b32_e32 v34, 26, v26
	v_or_b32_e32 v36, 28, v26
	v_or_b32_e32 v38, 30, v26
	v_mad_i64_i32 v[20:21], s[6:7], v20, s14, v[18:19]
	v_mad_i64_i32 v[22:23], s[6:7], v22, s14, v[18:19]
	v_mad_i64_i32 v[24:25], s[6:7], v24, s14, v[18:19]
	v_mad_i64_i32 v[30:31], s[6:7], v30, s14, v[18:19]
	v_mad_i64_i32 v[32:33], s[6:7], v32, s14, v[18:19]
	v_mad_i64_i32 v[34:35], s[6:7], v34, s14, v[18:19]
	v_mad_i64_i32 v[36:37], s[6:7], v36, s14, v[18:19]
	v_mad_i64_i32 v[38:39], s[6:7], v38, s14, v[18:19]
	global_load_dword v47, v[20:21], off nt
	global_load_dword v48, v[22:23], off nt
	global_load_dword v49, v[24:25], off nt
	global_load_dword v50, v[30:31], off nt
	global_load_dword v51, v[32:33], off nt
	global_load_dword v52, v[34:35], off nt
	global_load_dword v53, v[36:37], off nt
	global_load_dword v54, v[38:39], off nt
	v_or_b32_e32 v20, 32, v26
	v_or_b32_e32 v22, 34, v26
	v_or_b32_e32 v24, 36, v26
	v_or_b32_e32 v30, 38, v26
	v_or_b32_e32 v32, 40, v26
	v_or_b32_e32 v34, 42, v26
	v_or_b32_e32 v36, 44, v26
	v_or_b32_e32 v38, 46, v26
	v_mad_i64_i32 v[20:21], s[6:7], v20, s14, v[18:19]
	v_mad_i64_i32 v[22:23], s[6:7], v22, s14, v[18:19]
	v_mad_i64_i32 v[24:25], s[6:7], v24, s14, v[18:19]
	v_mad_i64_i32 v[30:31], s[6:7], v30, s14, v[18:19]
	v_mad_i64_i32 v[32:33], s[6:7], v32, s14, v[18:19]
	v_mad_i64_i32 v[34:35], s[6:7], v34, s14, v[18:19]
	v_mad_i64_i32 v[36:37], s[6:7], v36, s14, v[18:19]
	v_mad_i64_i32 v[38:39], s[6:7], v38, s14, v[18:19]
	global_load_dword v55, v[20:21], off nt
	global_load_dword v56, v[22:23], off nt
	global_load_dword v57, v[24:25], off nt
	global_load_dword v58, v[30:31], off nt
	global_load_dword v59, v[32:33], off nt
	global_load_dword v60, v[34:35], off nt
	global_load_dword v61, v[36:37], off nt
	s_nop 0
	global_load_dword v38, v[38:39], off nt
	v_or_b32_e32 v20, 48, v26
	v_or_b32_e32 v22, 50, v26
	v_or_b32_e32 v24, 52, v26
	v_or_b32_e32 v30, 54, v26
	v_or_b32_e32 v32, 56, v26
	v_or_b32_e32 v34, 58, v26
	v_or_b32_e32 v36, 60, v26
	v_or_b32_e32 v26, 62, v26
	v_mad_i64_i32 v[20:21], s[6:7], v20, s14, v[18:19]
	v_mad_i64_i32 v[22:23], s[6:7], v22, s14, v[18:19]
	v_mad_i64_i32 v[24:25], s[6:7], v24, s14, v[18:19]
	v_mad_i64_i32 v[30:31], s[6:7], v30, s14, v[18:19]
	v_mad_i64_i32 v[32:33], s[6:7], v32, s14, v[18:19]
	v_mad_i64_i32 v[34:35], s[6:7], v34, s14, v[18:19]
	v_mad_i64_i32 v[36:37], s[6:7], v36, s14, v[18:19]
	v_mad_i64_i32 v[18:19], s[6:7], v26, s14, v[18:19]
	global_load_dword v20, v[20:21], off nt
	s_nop 0
	global_load_dword v21, v[22:23], off nt
	s_nop 0
	global_load_dword v22, v[24:25], off nt
	global_load_dword v23, v[30:31], off nt
	s_nop 0
	global_load_dword v24, v[32:33], off nt
	global_load_dword v25, v[34:35], off nt
	global_load_dword v26, v[36:37], off nt
	s_nop 0
	global_load_dword v18, v[18:19], off nt
	s_waitcnt vmcnt(30)
	ds_write2_b32 v9, v29, v40 offset1:66
	s_waitcnt vmcnt(28)
	ds_write2_b32 v9, v41, v42 offset0:132 offset1:198
	s_waitcnt vmcnt(26)
	ds_write2_b32 v6, v43, v44 offset0:8 offset1:74
	s_waitcnt vmcnt(24)
	ds_write2_b32 v6, v45, v46 offset0:140 offset1:206
	s_waitcnt vmcnt(22)
	ds_write2_b32 v7, v47, v48 offset0:16 offset1:82
	s_waitcnt vmcnt(20)
	ds_write2_b32 v7, v49, v50 offset0:148 offset1:214
	s_waitcnt vmcnt(18)
	ds_write2_b32 v13, v51, v52 offset0:24 offset1:90
	s_waitcnt vmcnt(16)
	ds_write2_b32 v13, v53, v54 offset0:156 offset1:222
	s_waitcnt vmcnt(14)
	ds_write2_b32 v14, v55, v56 offset0:32 offset1:98
	s_waitcnt vmcnt(12)
	ds_write2_b32 v14, v57, v58 offset0:164 offset1:230
	s_waitcnt vmcnt(10)
	ds_write2_b32 v15, v59, v60 offset0:40 offset1:106
	s_waitcnt vmcnt(8)
	ds_write2_b32 v15, v61, v38 offset0:172 offset1:238
	s_waitcnt vmcnt(6)
	ds_write2_b32 v16, v20, v21 offset0:48 offset1:114
	s_waitcnt vmcnt(4)
	ds_write2_b32 v16, v22, v23 offset0:180 offset1:246
	s_waitcnt vmcnt(2)
	ds_write2_b32 v17, v24, v25 offset0:56 offset1:122
	s_waitcnt vmcnt(0)
	ds_write2_b32 v17, v26, v18 offset0:188 offset1:254
	s_waitcnt lgkmcnt(0)
	ds_read2_b32 v[22:23], v11 offset0:33 offset1:41
	ds_read2_b32 v[24:25], v11 offset1:8
	ds_read2_b32 v[30:31], v11 offset0:66 offset1:74
	ds_read2_b32 v[32:33], v11 offset0:99 offset1:107
	ds_read2_b32 v[34:35], v11 offset0:132 offset1:140
	ds_read2_b32 v[36:37], v11 offset0:165 offset1:173
	ds_read2_b32 v[38:39], v11 offset0:198 offset1:206
	ds_read2_b32 v[40:41], v11 offset0:231 offset1:239
	v_add_u32_e32 v44, s15, v10
	s_ashr_i32 s5, s4, 31
	v_ashrrev_i32_e32 v45, 31, v44
	v_lshl_add_u64 v[42:43], s[4:5], 1, v[2:3]
	v_lshlrev_b64 v[44:45], 11, v[44:45]
	s_waitcnt lgkmcnt(6)
	v_cvt_pk_bf16_f32 v18, v24, v22
	s_waitcnt lgkmcnt(4)
	v_cvt_pk_bf16_f32 v19, v30, v32
	s_waitcnt lgkmcnt(2)
	v_cvt_pk_bf16_f32 v20, v34, v36
	s_waitcnt lgkmcnt(0)
	v_cvt_pk_bf16_f32 v21, v38, v40
	v_lshl_add_u64 v[44:45], v[42:43], 0, v[44:45]
	v_add_u32_e32 v22, s15, v12
	global_store_dwordx4 v[44:45], v[18:21], off sc1
	s_add_i32 s8, s8, s68
	s_add_i32 s9, s9, s11
	v_cvt_pk_bf16_f32 v18, v25, v23
	v_ashrrev_i32_e32 v23, 31, v22
	v_cvt_pk_bf16_f32 v19, v31, v33
	v_cvt_pk_bf16_f32 v20, v35, v37
	v_cvt_pk_bf16_f32 v21, v39, v41
	v_lshlrev_b64 v[22:23], 11, v[22:23]
	ds_read2_b32 v[24:25], v11 offset0:49 offset1:57
	ds_read2_b32 v[30:31], v11 offset0:16 offset1:24
	ds_read2_b32 v[32:33], v11 offset0:82 offset1:90
	ds_read2_b32 v[34:35], v11 offset0:115 offset1:123
	ds_read2_b32 v[36:37], v11 offset0:148 offset1:156
	ds_read2_b32 v[38:39], v11 offset0:181 offset1:189
	ds_read2_b32 v[40:41], v11 offset0:214 offset1:222
	ds_read2_b32 v[44:45], v11 offset0:247 offset1:255
	v_lshl_add_u64 v[22:23], v[42:43], 0, v[22:23]
	global_store_dwordx4 v[22:23], v[18:21], off sc1
	v_add_u32_e32 v22, s15, v27
	v_ashrrev_i32_e32 v23, 31, v22
	v_lshlrev_b64 v[22:23], 11, v[22:23]
	s_waitcnt lgkmcnt(6)
	v_cvt_pk_bf16_f32 v18, v30, v24
	s_waitcnt lgkmcnt(4)
	v_cvt_pk_bf16_f32 v19, v32, v34
	s_waitcnt lgkmcnt(2)
	v_cvt_pk_bf16_f32 v20, v36, v38
	s_waitcnt lgkmcnt(0)
	v_cvt_pk_bf16_f32 v21, v40, v44
	v_lshl_add_u64 v[22:23], v[42:43], 0, v[22:23]
	global_store_dwordx4 v[22:23], v[18:21], off sc1
	v_add_u32_e32 v22, s15, v28
	v_ashrrev_i32_e32 v23, 31, v22
	v_lshlrev_b64 v[22:23], 11, v[22:23]
	v_cvt_pk_bf16_f32 v18, v31, v25
	v_cvt_pk_bf16_f32 v19, v33, v35
	v_cvt_pk_bf16_f32 v20, v37, v39
	v_cvt_pk_bf16_f32 v21, v41, v45
	v_lshl_add_u64 v[22:23], v[42:43], 0, v[22:23]
	global_store_dwordx4 v[22:23], v[18:21], off sc1
	s_waitcnt lgkmcnt(0)
	s_add_i32 s12, s12, s13
	s_cmpk_lt_i32 s8, 0xb00
	s_cbranch_scc0 .LBB0_30

.LBB0_39:
	v_mul_u32_u24_e32 v2, 0x84, v135
	v_add3_u32 v2, s63, v130, v2
	v_add_u32_e32 v3, 0x400, v2
	s_waitcnt vmcnt(30)
	ds_write2_b32 v2, v131, v133 offset1:66
	s_waitcnt vmcnt(28)
	ds_write2_b32 v2, v136, v138 offset0:132 offset1:198
	s_waitcnt vmcnt(26)
	ds_write2_b32 v3, v137, v139 offset0:8 offset1:74
	s_waitcnt vmcnt(24)
	ds_write2_b32 v3, v140, v141 offset0:140 offset1:206
	v_add_u32_e32 v3, 0x800, v2
	s_waitcnt vmcnt(22)
	ds_write2_b32 v3, v143, v144 offset0:16 offset1:82
	s_waitcnt vmcnt(20)
	ds_write2_b32 v3, v145, v147 offset0:148 offset1:214
	v_add_u32_e32 v3, 0xc00, v2
	s_waitcnt vmcnt(18)
	ds_write2_b32 v3, v146, v148 offset0:24 offset1:90
	s_waitcnt vmcnt(16)
	ds_write2_b32 v3, v149, v150 offset0:156 offset1:222
	v_add_u32_e32 v3, 0x1000, v2
	s_waitcnt vmcnt(14)
	ds_write2_b32 v3, v151, v152 offset0:32 offset1:98
	s_waitcnt vmcnt(12)
	ds_write2_b32 v3, v153, v155 offset0:164 offset1:230
	v_add_u32_e32 v3, 0x1400, v2
	s_waitcnt vmcnt(10)
	ds_write2_b32 v3, v154, v156 offset0:40 offset1:106
	s_waitcnt vmcnt(8)
	ds_write2_b32 v3, v157, v158 offset0:172 offset1:238
	v_add_u32_e32 v3, 0x1800, v2
	v_add_u32_e32 v2, 0x1c00, v2
	s_waitcnt vmcnt(6)
	ds_write2_b32 v3, v159, v160 offset0:48 offset1:114
	s_waitcnt vmcnt(4)
	ds_write2_b32 v3, v161, v163 offset0:180 offset1:246
	s_waitcnt vmcnt(2)
	ds_write2_b32 v2, v162, v164 offset0:56 offset1:122
	s_waitcnt vmcnt(0)
	ds_write2_b32 v2, v165, v166 offset0:188 offset1:254
	v_lshlrev_b32_e32 v2, 3, v0
	v_lshrrev_b32_e32 v24, 3, v1
	v_and_b32_e32 v2, 56, v2
	s_waitcnt lgkmcnt(0)
	v_mul_u32_u24_e32 v4, 0x84, v2
	v_lshlrev_b32_e32 v5, 2, v24
	v_add3_u32 v28, s63, v4, v5
	s_ashr_i32 s5, s4, 31
	ds_read2_b32 v[6:7], v28 offset0:33 offset1:41
	ds_read2_b32 v[8:9], v28 offset1:8
	ds_read2_b32 v[10:11], v28 offset0:66 offset1:74
	ds_read2_b32 v[12:13], v28 offset0:99 offset1:107
	ds_read2_b32 v[14:15], v28 offset0:132 offset1:140
	ds_read2_b32 v[16:17], v28 offset0:165 offset1:173
	ds_read2_b32 v[18:19], v28 offset0:198 offset1:206
	ds_read2_b32 v[20:21], v28 offset0:231 offset1:239
	s_lshl_b64 s[4:5], s[4:5], 1
	s_add_u32 s2, s2, s4
	v_add_u32_e32 v24, s7, v24
	s_addc_u32 s3, s3, s5
	v_lshlrev_b32_e32 v2, 1, v2
	v_mov_b32_e32 v3, 0
	v_ashrrev_i32_e32 v25, 31, v24
	v_lshl_add_u64 v[22:23], s[2:3], 0, v[2:3]
	v_lshlrev_b64 v[26:27], 11, v[24:25]
	s_waitcnt lgkmcnt(6)
	v_cvt_pk_bf16_f32 v2, v8, v6
	s_waitcnt lgkmcnt(4)
	v_cvt_pk_bf16_f32 v3, v10, v12
	s_waitcnt lgkmcnt(2)
	v_cvt_pk_bf16_f32 v4, v14, v16
	s_waitcnt lgkmcnt(0)
	v_cvt_pk_bf16_f32 v5, v18, v20
	v_lshl_add_u64 v[26:27], v[22:23], 0, v[26:27]
	v_add_u32_e32 v6, 8, v24
	global_store_dwordx4 v[26:27], v[2:5], off sc1
	s_nop 1
	v_cvt_pk_bf16_f32 v2, v9, v7
	v_ashrrev_i32_e32 v7, 31, v6
	v_cvt_pk_bf16_f32 v3, v11, v13
	v_cvt_pk_bf16_f32 v4, v15, v17
	v_cvt_pk_bf16_f32 v5, v19, v21
	v_lshlrev_b64 v[6:7], 11, v[6:7]
	ds_read2_b32 v[8:9], v28 offset0:49 offset1:57
	ds_read2_b32 v[10:11], v28 offset0:16 offset1:24
	ds_read2_b32 v[12:13], v28 offset0:82 offset1:90
	ds_read2_b32 v[14:15], v28 offset0:115 offset1:123
	ds_read2_b32 v[16:17], v28 offset0:148 offset1:156
	ds_read2_b32 v[18:19], v28 offset0:181 offset1:189
	ds_read2_b32 v[20:21], v28 offset0:214 offset1:222
	ds_read2_b32 v[26:27], v28 offset0:247 offset1:255
	v_lshl_add_u64 v[6:7], v[22:23], 0, v[6:7]
	global_store_dwordx4 v[6:7], v[2:5], off sc1
	v_add_u32_e32 v6, 16, v24
	v_ashrrev_i32_e32 v7, 31, v6
	v_lshlrev_b64 v[6:7], 11, v[6:7]
	s_waitcnt lgkmcnt(6)
	v_cvt_pk_bf16_f32 v2, v10, v8
	s_waitcnt lgkmcnt(4)
	v_cvt_pk_bf16_f32 v3, v12, v14
	s_waitcnt lgkmcnt(2)
	v_cvt_pk_bf16_f32 v4, v16, v18
	s_waitcnt lgkmcnt(0)
	v_cvt_pk_bf16_f32 v5, v20, v26
	v_lshl_add_u64 v[6:7], v[22:23], 0, v[6:7]
	global_store_dwordx4 v[6:7], v[2:5], off sc1
	v_add_u32_e32 v6, 24, v24
	v_ashrrev_i32_e32 v7, 31, v6
	v_lshlrev_b64 v[6:7], 11, v[6:7]
	v_cvt_pk_bf16_f32 v2, v11, v9
	v_cvt_pk_bf16_f32 v3, v13, v15
	v_cvt_pk_bf16_f32 v4, v17, v19
	v_cvt_pk_bf16_f32 v5, v21, v27
	v_lshl_add_u64 v[6:7], v[22:23], 0, v[6:7]
	global_store_dwordx4 v[6:7], v[2:5], off sc1
	s_waitcnt lgkmcnt(0)
	s_cmp_lt_i32 s61, 2
	s_cbranch_scc1 .LBB0_75

.LBB0_135:
	v_readlane_b32 s80, v254, 2
	s_and_b64 s[2:3], s[2:3], exec
	v_readlane_b32 s90, v254, 12
	v_readlane_b32 s91, v254, 13
	s_cselect_b32 s2, s70, 0x300000
	s_mov_b64 s[22:23], s[90:91]
	s_cselect_b32 s3, s51, s23
	s_cselect_b32 s6, s50, s22
	s_add_u32 s7, s58, s2
	s_addc_u32 s8, s59, 0
	s_lshl_b32 s2, s5, 6
	s_ashr_i32 s5, s4, 31
	s_lshl_b64 s[4:5], s[4:5], 2
	s_add_u32 s4, s6, s4
	v_or_b32_e32 v21, s2, v24
	s_addc_u32 s5, s3, s5
	v_lshl_add_u64 v[22:23], s[4:5], 0, v[2:3]
	v_or_b32_e32 v40, 2, v21
	v_or_b32_e32 v42, 4, v21
	v_or_b32_e32 v44, 6, v21
	v_or_b32_e32 v46, 8, v21
	v_or_b32_e32 v48, 10, v21
	v_or_b32_e32 v50, 12, v21
	v_or_b32_e32 v52, 14, v21
	v_mad_i64_i32 v[38:39], s[4:5], v21, s71, v[22:23]
	v_mad_i64_i32 v[40:41], s[4:5], v40, s71, v[22:23]
	v_mad_i64_i32 v[42:43], s[4:5], v42, s71, v[22:23]
	v_mad_i64_i32 v[44:45], s[4:5], v44, s71, v[22:23]
	v_mad_i64_i32 v[46:47], s[4:5], v46, s71, v[22:23]
	v_mad_i64_i32 v[48:49], s[4:5], v48, s71, v[22:23]
	v_mad_i64_i32 v[50:51], s[4:5], v50, s71, v[22:23]
	v_mad_i64_i32 v[52:53], s[4:5], v52, s71, v[22:23]
	global_load_dword v54, v[38:39], off nt
	global_load_dword v55, v[40:41], off nt
	global_load_dword v56, v[42:43], off nt
	global_load_dword v57, v[44:45], off nt
	global_load_dword v58, v[46:47], off nt
	global_load_dword v59, v[48:49], off nt
	global_load_dword v60, v[50:51], off nt
	global_load_dword v61, v[52:53], off nt
	v_or_b32_e32 v38, 16, v21
	v_or_b32_e32 v40, 18, v21
	v_or_b32_e32 v42, 20, v21
	v_or_b32_e32 v44, 22, v21
	v_or_b32_e32 v46, 24, v21
	v_or_b32_e32 v48, 26, v21
	v_or_b32_e32 v50, 28, v21
	v_or_b32_e32 v52, 30, v21
	v_mad_i64_i32 v[38:39], s[4:5], v38, s71, v[22:23]
	v_mad_i64_i32 v[40:41], s[4:5], v40, s71, v[22:23]
	v_mad_i64_i32 v[42:43], s[4:5], v42, s71, v[22:23]
	v_mad_i64_i32 v[44:45], s[4:5], v44, s71, v[22:23]
	v_mad_i64_i32 v[46:47], s[4:5], v46, s71, v[22:23]
	v_mad_i64_i32 v[48:49], s[4:5], v48, s71, v[22:23]
	v_mad_i64_i32 v[50:51], s[4:5], v50, s71, v[22:23]
	v_mad_i64_i32 v[52:53], s[4:5], v52, s71, v[22:23]
	global_load_dword v62, v[38:39], off nt
	global_load_dword v63, v[40:41], off nt
	global_load_dword v64, v[42:43], off nt
	global_load_dword v65, v[44:45], off nt
	global_load_dword v66, v[46:47], off nt
	global_load_dword v67, v[48:49], off nt
	global_load_dword v68, v[50:51], off nt
	global_load_dword v69, v[52:53], off nt
	v_or_b32_e32 v38, 32, v21
	v_or_b32_e32 v40, 34, v21
	v_or_b32_e32 v42, 36, v21
	v_or_b32_e32 v44, 38, v21
	v_or_b32_e32 v46, 40, v21
	v_or_b32_e32 v48, 42, v21
	v_or_b32_e32 v50, 44, v21
	v_or_b32_e32 v52, 46, v21
	v_mad_i64_i32 v[38:39], s[4:5], v38, s71, v[22:23]
	v_mad_i64_i32 v[40:41], s[4:5], v40, s71, v[22:23]
	v_mad_i64_i32 v[42:43], s[4:5], v42, s71, v[22:23]
	v_mad_i64_i32 v[44:45], s[4:5], v44, s71, v[22:23]
	v_mad_i64_i32 v[46:47], s[4:5], v46, s71, v[22:23]
	v_mad_i64_i32 v[48:49], s[4:5], v48, s71, v[22:23]
	v_mad_i64_i32 v[50:51], s[4:5], v50, s71, v[22:23]
	v_mad_i64_i32 v[52:53], s[4:5], v52, s71, v[22:23]
	global_load_dword v70, v[38:39], off nt
	global_load_dword v71, v[40:41], off nt
	global_load_dword v72, v[42:43], off nt
	global_load_dword v73, v[44:45], off nt
	global_load_dword v74, v[46:47], off nt
	global_load_dword v75, v[48:49], off nt
	global_load_dword v76, v[50:51], off nt
	s_nop 0
	global_load_dword v52, v[52:53], off nt
	v_or_b32_e32 v38, 48, v21
	v_or_b32_e32 v40, 50, v21
	v_or_b32_e32 v42, 52, v21
	v_or_b32_e32 v44, 54, v21
	v_or_b32_e32 v46, 56, v21
	v_or_b32_e32 v48, 58, v21
	v_or_b32_e32 v50, 60, v21
	v_or_b32_e32 v21, 62, v21
	v_mad_i64_i32 v[38:39], s[4:5], v38, s71, v[22:23]
	v_mad_i64_i32 v[40:41], s[4:5], v40, s71, v[22:23]
	v_mad_i64_i32 v[42:43], s[4:5], v42, s71, v[22:23]
	v_mad_i64_i32 v[44:45], s[4:5], v44, s71, v[22:23]
	v_mad_i64_i32 v[46:47], s[4:5], v46, s71, v[22:23]
	v_mad_i64_i32 v[48:49], s[4:5], v48, s71, v[22:23]
	v_mad_i64_i32 v[50:51], s[4:5], v50, s71, v[22:23]
	v_mad_i64_i32 v[22:23], s[4:5], v21, s71, v[22:23]
	global_load_dword v21, v[38:39], off nt
	s_nop 0
	global_load_dword v38, v[40:41], off nt
	global_load_dword v39, v[42:43], off nt
	s_nop 0
	global_load_dword v40, v[44:45], off nt
	global_load_dword v41, v[46:47], off nt
	global_load_dword v42, v[48:49], off nt
	global_load_dword v43, v[50:51], off nt
	s_nop 0
	global_load_dword v22, v[22:23], off nt
	s_waitcnt vmcnt(30)
	ds_write2_b32 v25, v54, v55 offset1:66
	s_waitcnt vmcnt(28)
	ds_write2_b32 v25, v56, v57 offset0:132 offset1:198
	s_waitcnt vmcnt(26)
	ds_write2_b32 v31, v58, v59 offset0:8 offset1:74
	s_waitcnt vmcnt(24)
	ds_write2_b32 v31, v60, v61 offset0:140 offset1:206
	s_waitcnt vmcnt(22)
	ds_write2_b32 v32, v62, v63 offset0:16 offset1:82
	s_waitcnt vmcnt(20)
	ds_write2_b32 v32, v64, v65 offset0:148 offset1:214
	s_waitcnt vmcnt(18)
	ds_write2_b32 v33, v66, v67 offset0:24 offset1:90
	s_waitcnt vmcnt(16)
	ds_write2_b32 v33, v68, v69 offset0:156 offset1:222
	s_waitcnt vmcnt(14)
	ds_write2_b32 v34, v70, v71 offset0:32 offset1:98
	s_waitcnt vmcnt(12)
	ds_write2_b32 v34, v72, v73 offset0:164 offset1:230
	s_waitcnt vmcnt(10)
	ds_write2_b32 v35, v74, v75 offset0:40 offset1:106
	s_waitcnt vmcnt(8)
	ds_write2_b32 v35, v76, v52 offset0:172 offset1:238
	s_waitcnt vmcnt(6)
	ds_write2_b32 v36, v21, v38 offset0:48 offset1:114
	s_waitcnt vmcnt(4)
	ds_write2_b32 v36, v39, v40 offset0:180 offset1:246
	s_waitcnt vmcnt(2)
	ds_write2_b32 v37, v41, v42 offset0:56 offset1:122
	s_waitcnt vmcnt(0)
	ds_write2_b32 v37, v43, v22 offset0:188 offset1:254
	s_waitcnt lgkmcnt(0)
	s_ashr_i32 s3, s2, 31
	ds_read2_b32 v[22:23], v27 offset0:33 offset1:41
	ds_read2_b32 v[42:43], v27 offset1:8
	ds_read2_b32 v[44:45], v27 offset0:66 offset1:74
	ds_read2_b32 v[46:47], v27 offset0:99 offset1:107
	ds_read2_b32 v[48:49], v27 offset0:132 offset1:140
	ds_read2_b32 v[50:51], v27 offset0:165 offset1:173
	ds_read2_b32 v[52:53], v27 offset0:198 offset1:206
	ds_read2_b32 v[54:55], v27 offset0:231 offset1:239
	s_lshl_b64 s[2:3], s[2:3], 1
	s_add_u32 s2, s7, s2
	v_add_u32_e32 v58, s0, v26
	s_addc_u32 s3, s8, s3
	v_mov_b32_e32 v21, v3
	v_ashrrev_i32_e32 v59, 31, v58
	v_lshl_add_u64 v[56:57], s[2:3], 0, v[20:21]
	v_lshlrev_b64 v[58:59], 11, v[58:59]
	s_waitcnt lgkmcnt(6)
	v_cvt_pk_bf16_f32 v38, v42, v22
	s_waitcnt lgkmcnt(4)
	v_cvt_pk_bf16_f32 v39, v44, v46
	s_waitcnt lgkmcnt(2)
	v_cvt_pk_bf16_f32 v40, v48, v50
	s_waitcnt lgkmcnt(0)
	v_cvt_pk_bf16_f32 v41, v52, v54
	v_lshl_add_u64 v[58:59], v[56:57], 0, v[58:59]
	v_add_u32_e32 v22, s0, v28
	global_store_dwordx4 v[58:59], v[38:41], off sc1
	v_readlane_b32 s81, v254, 3
	v_readlane_b32 s82, v254, 4
	v_cvt_pk_bf16_f32 v38, v43, v23
	v_ashrrev_i32_e32 v23, 31, v22
	v_cvt_pk_bf16_f32 v39, v45, v47
	v_cvt_pk_bf16_f32 v40, v49, v51
	v_cvt_pk_bf16_f32 v41, v53, v55
	v_lshlrev_b64 v[22:23], 11, v[22:23]
	ds_read2_b32 v[42:43], v27 offset0:49 offset1:57
	ds_read2_b32 v[44:45], v27 offset0:16 offset1:24
	ds_read2_b32 v[46:47], v27 offset0:82 offset1:90
	ds_read2_b32 v[48:49], v27 offset0:115 offset1:123
	ds_read2_b32 v[50:51], v27 offset0:148 offset1:156
	ds_read2_b32 v[52:53], v27 offset0:181 offset1:189
	ds_read2_b32 v[54:55], v27 offset0:214 offset1:222
	ds_read2_b32 v[58:59], v27 offset0:247 offset1:255
	v_lshl_add_u64 v[22:23], v[56:57], 0, v[22:23]
	global_store_dwordx4 v[22:23], v[38:41], off sc1
	v_add_u32_e32 v22, s0, v29
	v_ashrrev_i32_e32 v23, 31, v22
	v_lshlrev_b64 v[22:23], 11, v[22:23]
	s_waitcnt lgkmcnt(6)
	v_cvt_pk_bf16_f32 v38, v44, v42
	s_waitcnt lgkmcnt(4)
	v_cvt_pk_bf16_f32 v39, v46, v48
	s_waitcnt lgkmcnt(2)
	v_cvt_pk_bf16_f32 v40, v50, v52
	s_waitcnt lgkmcnt(0)
	v_cvt_pk_bf16_f32 v41, v54, v58
	v_lshl_add_u64 v[22:23], v[56:57], 0, v[22:23]
	global_store_dwordx4 v[22:23], v[38:41], off sc1
	v_add_u32_e32 v22, s0, v30
	v_ashrrev_i32_e32 v23, 31, v22
	v_lshlrev_b64 v[22:23], 11, v[22:23]
	v_cvt_pk_bf16_f32 v38, v45, v43
	v_cvt_pk_bf16_f32 v39, v47, v49
	v_cvt_pk_bf16_f32 v40, v51, v53
	v_cvt_pk_bf16_f32 v41, v55, v59
	v_lshl_add_u64 v[22:23], v[56:57], 0, v[22:23]
	global_store_dwordx4 v[22:23], v[38:41], off sc1
	s_waitcnt lgkmcnt(0)
	v_readlane_b32 s83, v254, 5
	v_readlane_b32 s84, v254, 6
	v_readlane_b32 s85, v254, 7
	v_readlane_b32 s86, v254, 8
	v_readlane_b32 s87, v254, 9
	v_readlane_b32 s88, v254, 10
	v_readlane_b32 s89, v254, 11
	v_readlane_b32 s92, v254, 14
	v_readlane_b32 s93, v254, 15
	v_readlane_b32 s94, v254, 16
	v_readlane_b32 s95, v254, 17

.LBB0_139:
	s_cmpk_gt_u32 s72, 0x107f
	s_cbranch_scc0 .LBB0_147
	s_cmpk_gt_u32 s72, 0x167f
	s_cbranch_scc0 .LBB0_142
	s_lshl_b32 s0, s72, 1
	s_and_b32 s0, s0, 0x7fffffc0
	s_add_i32 s6, s0, 0xffffd300
	s_and_b32 s8, s21, 0x3e0
	v_or_b32_e32 v22, s6, v24
	s_lshl_b32 s0, s8, 2
	v_mov_b32_e32 v23, v3
	v_or_b32_e32 v42, 2, v22
	v_mov_b32_e32 v43, v3
	v_or_b32_e32 v44, 4, v22
	v_mov_b32_e32 v45, v3
	v_or_b32_e32 v46, 6, v22
	v_mov_b32_e32 v47, v3
	v_or_b32_e32 v48, 8, v22
	v_mov_b32_e32 v49, v3
	v_or_b32_e32 v50, 10, v22
	v_mov_b32_e32 v51, v3
	v_or_b32_e32 v52, 12, v22
	v_mov_b32_e32 v53, v3
	v_or_b32_e32 v54, 14, v22
	v_mov_b32_e32 v55, v3
	v_lshl_add_u64 v[38:39], v[4:5], 0, s[0:1]
	v_lshlrev_b64 v[40:41], 12, v[22:23]
	v_lshlrev_b64 v[42:43], 12, v[42:43]
	v_lshlrev_b64 v[44:45], 12, v[44:45]
	v_lshlrev_b64 v[46:47], 12, v[46:47]
	v_lshlrev_b64 v[48:49], 12, v[48:49]
	v_lshlrev_b64 v[50:51], 12, v[50:51]
	v_lshlrev_b64 v[52:53], 12, v[52:53]
	v_lshlrev_b64 v[54:55], 12, v[54:55]
	v_lshl_add_u64 v[40:41], v[38:39], 0, v[40:41]
	v_lshl_add_u64 v[42:43], v[38:39], 0, v[42:43]
	v_lshl_add_u64 v[44:45], v[38:39], 0, v[44:45]
	v_lshl_add_u64 v[46:47], v[38:39], 0, v[46:47]
	v_lshl_add_u64 v[48:49], v[38:39], 0, v[48:49]
	v_lshl_add_u64 v[50:51], v[38:39], 0, v[50:51]
	v_lshl_add_u64 v[52:53], v[38:39], 0, v[52:53]
	v_lshl_add_u64 v[54:55], v[38:39], 0, v[54:55]
	global_load_dword v21, v[40:41], off nt
	global_load_dword v56, v[42:43], off nt
	global_load_dword v57, v[44:45], off nt
	global_load_dword v58, v[46:47], off nt
	global_load_dword v59, v[48:49], off nt
	global_load_dword v60, v[50:51], off nt
	global_load_dword v61, v[52:53], off nt
	global_load_dword v62, v[54:55], off nt
	v_or_b32_e32 v40, 16, v22
	v_mov_b32_e32 v41, v3
	v_or_b32_e32 v42, 18, v22
	v_mov_b32_e32 v43, v3
	v_or_b32_e32 v44, 20, v22
	v_mov_b32_e32 v45, v3
	v_or_b32_e32 v46, 22, v22
	v_mov_b32_e32 v47, v3
	v_or_b32_e32 v48, 24, v22
	v_mov_b32_e32 v49, v3
	v_or_b32_e32 v50, 26, v22
	v_mov_b32_e32 v51, v3
	v_or_b32_e32 v52, 28, v22
	v_mov_b32_e32 v53, v3
	v_or_b32_e32 v54, 30, v22
	v_mov_b32_e32 v55, v3
	v_lshlrev_b64 v[40:41], 12, v[40:41]
	v_lshlrev_b64 v[42:43], 12, v[42:43]
	v_lshlrev_b64 v[44:45], 12, v[44:45]
	v_lshlrev_b64 v[46:47], 12, v[46:47]
	v_lshlrev_b64 v[48:49], 12, v[48:49]
	v_lshlrev_b64 v[50:51], 12, v[50:51]
	v_lshlrev_b64 v[52:53], 12, v[52:53]
	v_lshlrev_b64 v[54:55], 12, v[54:55]
	v_lshl_add_u64 v[40:41], v[38:39], 0, v[40:41]
	v_lshl_add_u64 v[42:43], v[38:39], 0, v[42:43]
	v_lshl_add_u64 v[44:45], v[38:39], 0, v[44:45]
	v_lshl_add_u64 v[46:47], v[38:39], 0, v[46:47]
	v_lshl_add_u64 v[48:49], v[38:39], 0, v[48:49]
	v_lshl_add_u64 v[50:51], v[38:39], 0, v[50:51]
	v_lshl_add_u64 v[52:53], v[38:39], 0, v[52:53]
	v_lshl_add_u64 v[54:55], v[38:39], 0, v[54:55]
	global_load_dword v63, v[40:41], off nt
	global_load_dword v64, v[42:43], off nt
	global_load_dword v65, v[44:45], off nt
	global_load_dword v66, v[46:47], off nt
	global_load_dword v67, v[48:49], off nt
	global_load_dword v68, v[50:51], off nt
	global_load_dword v69, v[52:53], off nt
	global_load_dword v70, v[54:55], off nt
	v_or_b32_e32 v40, 32, v22
	v_mov_b32_e32 v41, v3
	v_or_b32_e32 v42, 34, v22
	v_mov_b32_e32 v43, v3
	v_or_b32_e32 v44, 36, v22
	v_mov_b32_e32 v45, v3
	v_or_b32_e32 v46, 38, v22
	v_mov_b32_e32 v47, v3
	v_or_b32_e32 v48, 40, v22
	v_mov_b32_e32 v49, v3
	v_or_b32_e32 v50, 42, v22
	v_mov_b32_e32 v51, v3
	v_or_b32_e32 v52, 44, v22
	v_mov_b32_e32 v53, v3
	v_or_b32_e32 v54, 46, v22
	v_mov_b32_e32 v55, v3
	v_lshlrev_b64 v[40:41], 12, v[40:41]
	v_lshlrev_b64 v[42:43], 12, v[42:43]
	v_lshlrev_b64 v[44:45], 12, v[44:45]
	v_lshlrev_b64 v[46:47], 12, v[46:47]
	v_lshlrev_b64 v[48:49], 12, v[48:49]
	v_lshlrev_b64 v[50:51], 12, v[50:51]
	v_lshlrev_b64 v[52:53], 12, v[52:53]
	v_lshlrev_b64 v[54:55], 12, v[54:55]
	v_lshl_add_u64 v[40:41], v[38:39], 0, v[40:41]
	v_lshl_add_u64 v[42:43], v[38:39], 0, v[42:43]
	v_lshl_add_u64 v[44:45], v[38:39], 0, v[44:45]
	v_lshl_add_u64 v[46:47], v[38:39], 0, v[46:47]
	v_lshl_add_u64 v[48:49], v[38:39], 0, v[48:49]
	v_lshl_add_u64 v[50:51], v[38:39], 0, v[50:51]
	v_lshl_add_u64 v[52:53], v[38:39], 0, v[52:53]
	v_lshl_add_u64 v[54:55], v[38:39], 0, v[54:55]
	global_load_dword v71, v[40:41], off nt
	global_load_dword v72, v[42:43], off nt
	global_load_dword v73, v[44:45], off nt
	global_load_dword v74, v[46:47], off nt
	global_load_dword v75, v[48:49], off nt
	global_load_dword v76, v[50:51], off nt
	global_load_dword v77, v[52:53], off nt
	s_nop 0
	global_load_dword v54, v[54:55], off nt
	v_or_b32_e32 v40, 48, v22
	v_mov_b32_e32 v41, v3
	v_or_b32_e32 v42, 50, v22
	v_mov_b32_e32 v43, v3
	v_or_b32_e32 v44, 52, v22
	v_mov_b32_e32 v45, v3
	v_or_b32_e32 v46, 54, v22
	v_or_b32_e32 v48, 56, v22
	v_or_b32_e32 v50, 58, v22
	v_or_b32_e32 v52, 60, v22
	v_or_b32_e32 v22, 62, v22
	v_lshlrev_b64 v[40:41], 12, v[40:41]
	v_lshlrev_b64 v[42:43], 12, v[42:43]
	v_lshlrev_b64 v[44:45], 12, v[44:45]
	v_mov_b32_e32 v47, v3
	v_mov_b32_e32 v49, v3
	v_mov_b32_e32 v51, v3
	v_mov_b32_e32 v53, v3
	v_lshlrev_b64 v[22:23], 12, v[22:23]
	v_lshl_add_u64 v[40:41], v[38:39], 0, v[40:41]
	v_lshl_add_u64 v[42:43], v[38:39], 0, v[42:43]
	v_lshl_add_u64 v[44:45], v[38:39], 0, v[44:45]
	v_lshlrev_b64 v[46:47], 12, v[46:47]
	v_lshlrev_b64 v[48:49], 12, v[48:49]
	v_lshlrev_b64 v[50:51], 12, v[50:51]
	v_lshlrev_b64 v[52:53], 12, v[52:53]
	v_lshl_add_u64 v[22:23], v[38:39], 0, v[22:23]
	v_lshl_add_u64 v[46:47], v[38:39], 0, v[46:47]
	v_lshl_add_u64 v[48:49], v[38:39], 0, v[48:49]
	v_lshl_add_u64 v[50:51], v[38:39], 0, v[50:51]
	v_lshl_add_u64 v[52:53], v[38:39], 0, v[52:53]
	global_load_dword v38, v[40:41], off nt
	global_load_dword v39, v[42:43], off nt
	s_nop 0
	global_load_dword v40, v[44:45], off nt
	global_load_dword v41, v[46:47], off nt
	global_load_dword v42, v[48:49], off nt
	global_load_dword v43, v[50:51], off nt
	s_nop 0
	global_load_dword v44, v[52:53], off nt
	s_nop 0
	global_load_dword v22, v[22:23], off nt
	s_waitcnt vmcnt(30)
	ds_write2_b32 v25, v21, v56 offset1:66
	s_waitcnt vmcnt(28)
	ds_write2_b32 v25, v57, v58 offset0:132 offset1:198
	s_waitcnt vmcnt(26)
	ds_write2_b32 v31, v59, v60 offset0:8 offset1:74
	s_waitcnt vmcnt(24)
	ds_write2_b32 v31, v61, v62 offset0:140 offset1:206
	s_waitcnt vmcnt(22)
	ds_write2_b32 v32, v63, v64 offset0:16 offset1:82
	s_waitcnt vmcnt(20)
	ds_write2_b32 v32, v65, v66 offset0:148 offset1:214
	s_waitcnt vmcnt(18)
	ds_write2_b32 v33, v67, v68 offset0:24 offset1:90
	s_waitcnt vmcnt(16)
	ds_write2_b32 v33, v69, v70 offset0:156 offset1:222
	s_waitcnt vmcnt(14)
	ds_write2_b32 v34, v71, v72 offset0:32 offset1:98
	s_waitcnt vmcnt(12)
	ds_write2_b32 v34, v73, v74 offset0:164 offset1:230
	s_waitcnt vmcnt(10)
	ds_write2_b32 v35, v75, v76 offset0:40 offset1:106
	s_waitcnt vmcnt(8)
	ds_write2_b32 v35, v77, v54 offset0:172 offset1:238
	s_waitcnt vmcnt(6)
	ds_write2_b32 v36, v38, v39 offset0:48 offset1:114
	s_waitcnt vmcnt(4)
	ds_write2_b32 v36, v40, v41 offset0:180 offset1:246
	s_waitcnt vmcnt(2)
	ds_write2_b32 v37, v42, v43 offset0:56 offset1:122
	s_waitcnt vmcnt(0)
	ds_write2_b32 v37, v44, v22 offset0:188 offset1:254
	s_waitcnt lgkmcnt(0)
	ds_read2_b32 v[22:23], v27 offset0:33 offset1:41
	ds_read2_b32 v[42:43], v27 offset1:8
	ds_read2_b32 v[44:45], v27 offset0:66 offset1:74
	ds_read2_b32 v[46:47], v27 offset0:99 offset1:107
	ds_read2_b32 v[48:49], v27 offset0:132 offset1:140
	ds_read2_b32 v[50:51], v27 offset0:165 offset1:173
	ds_read2_b32 v[52:53], v27 offset0:198 offset1:206
	ds_read2_b32 v[54:55], v27 offset0:231 offset1:239
	s_mov_b32 s7, s1
	v_or_b32_e32 v21, s8, v26
	v_lshl_add_u64 v[56:57], s[6:7], 1, v[12:13]
	v_lshlrev_b32_e32 v58, 11, v21
	v_mov_b32_e32 v59, v3
	s_waitcnt lgkmcnt(6)
	v_cvt_pk_bf16_f32 v38, v42, v22
	s_waitcnt lgkmcnt(4)
	v_cvt_pk_bf16_f32 v39, v44, v46
	s_waitcnt lgkmcnt(2)
	v_cvt_pk_bf16_f32 v40, v48, v50
	s_waitcnt lgkmcnt(0)
	v_cvt_pk_bf16_f32 v41, v52, v54
	v_lshl_add_u64 v[58:59], v[56:57], 0, v[58:59]
	global_store_dwordx4 v[58:59], v[38:41], off sc1
	v_or_b32_e32 v21, s8, v28
	v_lshlrev_b32_e32 v22, 11, v21
	v_cvt_pk_bf16_f32 v38, v43, v23
	v_cvt_pk_bf16_f32 v39, v45, v47
	v_cvt_pk_bf16_f32 v40, v49, v51
	v_cvt_pk_bf16_f32 v41, v53, v55
	ds_read2_b32 v[42:43], v27 offset0:49 offset1:57
	ds_read2_b32 v[44:45], v27 offset0:16 offset1:24
	ds_read2_b32 v[46:47], v27 offset0:82 offset1:90
	ds_read2_b32 v[48:49], v27 offset0:115 offset1:123
	ds_read2_b32 v[50:51], v27 offset0:148 offset1:156
	ds_read2_b32 v[52:53], v27 offset0:181 offset1:189
	ds_read2_b32 v[54:55], v27 offset0:214 offset1:222
	ds_read2_b32 v[58:59], v27 offset0:247 offset1:255
	v_mov_b32_e32 v23, v3
	v_lshl_add_u64 v[22:23], v[56:57], 0, v[22:23]
	v_or_b32_e32 v21, s8, v29
	global_store_dwordx4 v[22:23], v[38:41], off sc1
	v_lshlrev_b32_e32 v22, 11, v21
	v_mov_b32_e32 v23, v3
	s_waitcnt lgkmcnt(6)
	v_cvt_pk_bf16_f32 v38, v44, v42
	s_waitcnt lgkmcnt(4)
	v_cvt_pk_bf16_f32 v39, v46, v48
	s_waitcnt lgkmcnt(2)
	v_cvt_pk_bf16_f32 v40, v50, v52
	s_waitcnt lgkmcnt(0)
	v_cvt_pk_bf16_f32 v41, v54, v58
	v_lshl_add_u64 v[22:23], v[56:57], 0, v[22:23]
	v_or_b32_e32 v21, s8, v30
	global_store_dwordx4 v[22:23], v[38:41], off sc1
	v_lshlrev_b32_e32 v22, 11, v21
	v_mov_b32_e32 v23, v3
	v_cvt_pk_bf16_f32 v38, v45, v43
	v_cvt_pk_bf16_f32 v39, v47, v49
	v_cvt_pk_bf16_f32 v40, v51, v53
	v_cvt_pk_bf16_f32 v41, v55, v59
	v_lshl_add_u64 v[22:23], v[56:57], 0, v[22:23]
	global_store_dwordx4 v[22:23], v[38:41], off sc1
	s_waitcnt lgkmcnt(0)
	s_mov_b64 s[6:7], 0

.LBB0_145:
	s_lshl_b32 s0, s0, 6
	s_and_b32 s7, s0, 0xffc0
	v_or_b32_e32 v21, s7, v24
	s_lshl_b32 s0, s8, 2
	v_mul_u32_u24_e32 v21, 0xc10, v21
	v_lshl_add_u64 v[22:23], v[6:7], 0, s[0:1]
	v_lshlrev_b32_e32 v38, 2, v21
	v_mov_b32_e32 v39, v3
	v_lshl_add_u64 v[22:23], v[22:23], 0, v[38:39]
	v_add_co_u32_e32 v38, vcc, 0x6000, v22
	s_lshl_b32 s0, s7, 1
	s_nop 0
	v_addc_co_u32_e32 v39, vcc, 0, v23, vcc
	v_add_co_u32_e32 v40, vcc, 0xc000, v22
	s_nop 1
	v_addc_co_u32_e32 v41, vcc, 0, v23, vcc
	v_add_co_u32_e32 v42, vcc, 0x12000, v22
	s_nop 1
	v_addc_co_u32_e32 v43, vcc, 0, v23, vcc
	v_add_co_u32_e32 v44, vcc, 0x18000, v22
	s_nop 1
	v_addc_co_u32_e32 v45, vcc, 0, v23, vcc
	v_add_co_u32_e32 v46, vcc, 0x1e000, v22
	s_nop 1
	v_addc_co_u32_e32 v47, vcc, 0, v23, vcc
	v_add_co_u32_e32 v48, vcc, 0x24000, v22
	s_nop 1
	v_addc_co_u32_e32 v49, vcc, 0, v23, vcc
	v_add_co_u32_e32 v50, vcc, 0x2a000, v22
	s_nop 1
	v_addc_co_u32_e32 v51, vcc, 0, v23, vcc
	global_load_dword v21, v[22:23], off nt
	global_load_dword v54, v[38:39], off offset:128 nt
	global_load_dword v55, v[40:41], off offset:256 nt
	global_load_dword v56, v[42:43], off offset:384 nt
	global_load_dword v57, v[44:45], off offset:512 nt
	global_load_dword v58, v[46:47], off offset:640 nt
	global_load_dword v59, v[48:49], off offset:768 nt
	global_load_dword v60, v[50:51], off offset:896 nt
	v_add_co_u32_e32 v38, vcc, 0x30000, v22
	s_nop 1
	v_addc_co_u32_e32 v39, vcc, 0, v23, vcc
	v_add_co_u32_e32 v40, vcc, 0x36000, v22
	s_nop 1
	v_addc_co_u32_e32 v41, vcc, 0, v23, vcc
	v_add_co_u32_e32 v42, vcc, 0x3c000, v22
	s_nop 1
	v_addc_co_u32_e32 v43, vcc, 0, v23, vcc
	v_add_co_u32_e32 v44, vcc, 0x42000, v22
	s_nop 1
	v_addc_co_u32_e32 v45, vcc, 0, v23, vcc
	v_add_co_u32_e32 v46, vcc, 0x48000, v22
	s_nop 1
	v_addc_co_u32_e32 v47, vcc, 0, v23, vcc
	v_add_co_u32_e32 v48, vcc, 0x4e000, v22
	s_nop 1
	v_addc_co_u32_e32 v49, vcc, 0, v23, vcc
	v_add_co_u32_e32 v50, vcc, 0x54000, v22
	s_nop 1
	v_addc_co_u32_e32 v51, vcc, 0, v23, vcc
	v_add_co_u32_e32 v52, vcc, 0x5a000, v22
	s_nop 1
	v_addc_co_u32_e32 v53, vcc, 0, v23, vcc
	global_load_dword v61, v[38:39], off offset:1024 nt
	global_load_dword v62, v[40:41], off offset:1152 nt
	global_load_dword v63, v[42:43], off offset:1280 nt
	global_load_dword v64, v[44:45], off offset:1408 nt
	global_load_dword v65, v[46:47], off offset:1536 nt
	global_load_dword v66, v[48:49], off offset:1664 nt
	global_load_dword v67, v[50:51], off offset:1792 nt
	global_load_dword v68, v[52:53], off offset:1920 nt
	v_add_co_u32_e32 v38, vcc, 0x60000, v22
	s_nop 1
	v_addc_co_u32_e32 v39, vcc, 0, v23, vcc
	v_add_co_u32_e32 v40, vcc, 0x66000, v22
	s_nop 1
	v_addc_co_u32_e32 v41, vcc, 0, v23, vcc
	v_add_co_u32_e32 v42, vcc, 0x6c000, v22
	s_nop 1
	v_addc_co_u32_e32 v43, vcc, 0, v23, vcc
	v_add_co_u32_e32 v44, vcc, 0x72000, v22
	s_nop 1
	v_addc_co_u32_e32 v45, vcc, 0, v23, vcc
	v_add_co_u32_e32 v46, vcc, 0x78000, v22
	s_nop 1
	v_addc_co_u32_e32 v47, vcc, 0, v23, vcc
	v_add_co_u32_e32 v48, vcc, 0x7e000, v22
	s_nop 1
	v_addc_co_u32_e32 v49, vcc, 0, v23, vcc
	v_add_co_u32_e32 v50, vcc, 0x84000, v22
	s_nop 1
	v_addc_co_u32_e32 v51, vcc, 0, v23, vcc
	v_add_co_u32_e32 v52, vcc, 0x8a000, v22
	s_nop 1
	v_addc_co_u32_e32 v53, vcc, 0, v23, vcc
	global_load_dword v69, v[38:39], off offset:2048 nt
	global_load_dword v70, v[40:41], off offset:2176 nt
	global_load_dword v71, v[42:43], off offset:2304 nt
	global_load_dword v72, v[44:45], off offset:2432 nt
	global_load_dword v73, v[46:47], off offset:2560 nt
	global_load_dword v74, v[48:49], off offset:2688 nt
	global_load_dword v75, v[50:51], off offset:2816 nt
	s_nop 0
	global_load_dword v52, v[52:53], off offset:2944 nt
	v_add_co_u32_e32 v38, vcc, 0x90000, v22
	s_nop 1
	v_addc_co_u32_e32 v39, vcc, 0, v23, vcc
	v_add_co_u32_e32 v40, vcc, 0x96000, v22
	s_nop 1
	v_addc_co_u32_e32 v41, vcc, 0, v23, vcc
	v_add_co_u32_e32 v42, vcc, 0x9c000, v22
	s_nop 1
	v_addc_co_u32_e32 v43, vcc, 0, v23, vcc
	v_add_co_u32_e32 v44, vcc, 0xa2000, v22
	s_nop 1
	v_addc_co_u32_e32 v45, vcc, 0, v23, vcc
	v_add_co_u32_e32 v46, vcc, 0xa8000, v22
	s_nop 1
	v_addc_co_u32_e32 v47, vcc, 0, v23, vcc
	v_add_co_u32_e32 v48, vcc, 0xae000, v22
	s_nop 1
	v_addc_co_u32_e32 v49, vcc, 0, v23, vcc
	v_add_co_u32_e32 v50, vcc, 0xb4000, v22
	s_nop 1
	v_addc_co_u32_e32 v51, vcc, 0, v23, vcc
	v_add_co_u32_e32 v22, vcc, 0xba000, v22
	s_nop 1
	v_addc_co_u32_e32 v23, vcc, 0, v23, vcc
	global_load_dword v38, v[38:39], off offset:3072 nt
	s_nop 0
	global_load_dword v39, v[40:41], off offset:3200 nt
	s_nop 0
	global_load_dword v40, v[42:43], off offset:3328 nt
	global_load_dword v41, v[44:45], off offset:3456 nt
	s_nop 0
	global_load_dword v42, v[46:47], off offset:3584 nt
	global_load_dword v43, v[48:49], off offset:3712 nt
	global_load_dword v44, v[50:51], off offset:3840 nt
	s_nop 0
	global_load_dword v22, v[22:23], off offset:3968 nt
	s_waitcnt vmcnt(30)
	ds_write2_b32 v25, v21, v54 offset1:66
	s_waitcnt vmcnt(28)
	ds_write2_b32 v25, v55, v56 offset0:132 offset1:198
	s_waitcnt vmcnt(26)
	ds_write2_b32 v31, v57, v58 offset0:8 offset1:74
	s_waitcnt vmcnt(24)
	ds_write2_b32 v31, v59, v60 offset0:140 offset1:206
	s_waitcnt vmcnt(22)
	ds_write2_b32 v32, v61, v62 offset0:16 offset1:82
	s_waitcnt vmcnt(20)
	ds_write2_b32 v32, v63, v64 offset0:148 offset1:214
	s_waitcnt vmcnt(18)
	ds_write2_b32 v33, v65, v66 offset0:24 offset1:90
	s_waitcnt vmcnt(16)
	ds_write2_b32 v33, v67, v68 offset0:156 offset1:222
	s_waitcnt vmcnt(14)
	ds_write2_b32 v34, v69, v70 offset0:32 offset1:98
	s_waitcnt vmcnt(12)
	ds_write2_b32 v34, v71, v72 offset0:164 offset1:230
	s_waitcnt vmcnt(10)
	ds_write2_b32 v35, v73, v74 offset0:40 offset1:106
	s_waitcnt vmcnt(8)
	ds_write2_b32 v35, v75, v52 offset0:172 offset1:238
	s_waitcnt vmcnt(6)
	ds_write2_b32 v36, v38, v39 offset0:48 offset1:114
	s_waitcnt vmcnt(4)
	ds_write2_b32 v36, v40, v41 offset0:180 offset1:246
	s_waitcnt vmcnt(2)
	ds_write2_b32 v37, v42, v43 offset0:56 offset1:122
	s_waitcnt vmcnt(0)
	ds_write2_b32 v37, v44, v22 offset0:188 offset1:254
	s_waitcnt lgkmcnt(0)
	ds_read2_b32 v[22:23], v27 offset0:33 offset1:41
	ds_read2_b32 v[42:43], v27 offset1:8
	ds_read2_b32 v[44:45], v27 offset0:66 offset1:74
	ds_read2_b32 v[46:47], v27 offset0:99 offset1:107
	ds_read2_b32 v[48:49], v27 offset0:132 offset1:140
	ds_read2_b32 v[50:51], v27 offset0:165 offset1:173
	ds_read2_b32 v[52:53], v27 offset0:198 offset1:206
	ds_read2_b32 v[54:55], v27 offset0:231 offset1:239
	v_add_u32_e32 v58, s6, v26
	v_mov_b32_e32 v59, v3
	v_lshl_add_u64 v[56:57], v[14:15], 0, s[0:1]
	v_lshlrev_b64 v[58:59], 11, v[58:59]
	s_waitcnt lgkmcnt(6)
	v_cvt_pk_bf16_f32 v38, v42, v22
	s_waitcnt lgkmcnt(4)
	v_cvt_pk_bf16_f32 v39, v44, v46
	s_waitcnt lgkmcnt(2)
	v_cvt_pk_bf16_f32 v40, v48, v50
	s_waitcnt lgkmcnt(0)
	v_cvt_pk_bf16_f32 v41, v52, v54
	v_lshl_add_u64 v[58:59], v[56:57], 0, v[58:59]
	global_store_dwordx4 v[58:59], v[38:41], off sc1
	v_add_u32_e32 v22, s6, v28
	s_nop 0
	v_cvt_pk_bf16_f32 v38, v43, v23
	v_cvt_pk_bf16_f32 v39, v45, v47
	v_cvt_pk_bf16_f32 v40, v49, v51
	v_cvt_pk_bf16_f32 v41, v53, v55
	v_mov_b32_e32 v23, v3
	ds_read2_b32 v[42:43], v27 offset0:49 offset1:57
	ds_read2_b32 v[44:45], v27 offset0:16 offset1:24
	ds_read2_b32 v[46:47], v27 offset0:82 offset1:90
	ds_read2_b32 v[48:49], v27 offset0:115 offset1:123
	ds_read2_b32 v[50:51], v27 offset0:148 offset1:156
	ds_read2_b32 v[52:53], v27 offset0:181 offset1:189
	ds_read2_b32 v[54:55], v27 offset0:214 offset1:222
	ds_read2_b32 v[58:59], v27 offset0:247 offset1:255
	v_lshlrev_b64 v[22:23], 11, v[22:23]
	v_lshl_add_u64 v[22:23], v[56:57], 0, v[22:23]
	global_store_dwordx4 v[22:23], v[38:41], off sc1
	v_add_u32_e32 v22, s6, v29
	v_mov_b32_e32 v23, v3
	v_lshlrev_b64 v[22:23], 11, v[22:23]
	s_waitcnt lgkmcnt(6)
	v_cvt_pk_bf16_f32 v38, v44, v42
	s_waitcnt lgkmcnt(4)
	v_cvt_pk_bf16_f32 v39, v46, v48
	s_waitcnt lgkmcnt(2)
	v_cvt_pk_bf16_f32 v40, v50, v52
	s_waitcnt lgkmcnt(0)
	v_cvt_pk_bf16_f32 v41, v54, v58
	v_lshl_add_u64 v[22:23], v[56:57], 0, v[22:23]
	global_store_dwordx4 v[22:23], v[38:41], off sc1
	v_add_u32_e32 v22, s6, v30
	v_mov_b32_e32 v23, v3
	v_lshlrev_b64 v[22:23], 11, v[22:23]
	v_cvt_pk_bf16_f32 v38, v45, v43
	v_cvt_pk_bf16_f32 v39, v47, v49
	v_cvt_pk_bf16_f32 v40, v51, v53
	v_cvt_pk_bf16_f32 v41, v55, v59
	v_lshl_add_u64 v[22:23], v[56:57], 0, v[22:23]
	global_store_dwordx4 v[22:23], v[38:41], off sc1
	s_waitcnt lgkmcnt(0)

.LBB0_147:
	s_andn2_b64 vcc, exec, s[6:7]
	s_cbranch_vccnz .LBB0_152
	s_lshl_b32 s0, s72, 1
	s_and_b32 s0, s0, 0x3fc0
	s_add_i32 s6, s0, 0xffffea00
	s_and_b32 s8, s21, 0x3e0
	v_or_b32_e32 v22, s6, v24
	s_mov_b64 s[14:15], -1
	s_and_b64 vcc, exec, s[4:5]
	v_or_b32_e32 v40, s8, v26
	v_or_b32_e32 v39, s8, v28
	v_or_b32_e32 v38, s8, v29
	v_or_b32_e32 v21, s8, v30
	s_cbranch_vccz .LBB0_150
	s_lshl_b32 s0, s8, 2
	v_mov_b32_e32 v23, v3
	v_or_b32_e32 v46, 2, v22
	v_mov_b32_e32 v47, v3
	v_or_b32_e32 v48, 4, v22
	v_mov_b32_e32 v49, v3
	v_or_b32_e32 v50, 6, v22
	v_mov_b32_e32 v51, v3
	v_or_b32_e32 v52, 8, v22
	v_mov_b32_e32 v53, v3
	v_or_b32_e32 v54, 10, v22
	v_mov_b32_e32 v55, v3
	v_or_b32_e32 v56, 12, v22
	v_mov_b32_e32 v57, v3
	v_or_b32_e32 v58, 14, v22
	v_mov_b32_e32 v59, v3
	v_lshl_add_u64 v[42:43], v[8:9], 0, s[0:1]
	v_lshlrev_b64 v[44:45], 12, v[22:23]
	v_lshlrev_b64 v[46:47], 12, v[46:47]
	v_lshlrev_b64 v[48:49], 12, v[48:49]
	v_lshlrev_b64 v[50:51], 12, v[50:51]
	v_lshlrev_b64 v[52:53], 12, v[52:53]
	v_lshlrev_b64 v[54:55], 12, v[54:55]
	v_lshlrev_b64 v[56:57], 12, v[56:57]
	v_lshlrev_b64 v[58:59], 12, v[58:59]
	v_lshl_add_u64 v[44:45], v[42:43], 0, v[44:45]
	v_lshl_add_u64 v[46:47], v[42:43], 0, v[46:47]
	v_lshl_add_u64 v[48:49], v[42:43], 0, v[48:49]
	v_lshl_add_u64 v[50:51], v[42:43], 0, v[50:51]
	v_lshl_add_u64 v[52:53], v[42:43], 0, v[52:53]
	v_lshl_add_u64 v[54:55], v[42:43], 0, v[54:55]
	v_lshl_add_u64 v[56:57], v[42:43], 0, v[56:57]
	v_lshl_add_u64 v[58:59], v[42:43], 0, v[58:59]
	global_load_dword v23, v[44:45], off nt
	global_load_dword v41, v[46:47], off nt
	global_load_dword v60, v[48:49], off nt
	global_load_dword v61, v[50:51], off nt
	global_load_dword v62, v[52:53], off nt
	global_load_dword v63, v[54:55], off nt
	global_load_dword v64, v[56:57], off nt
	global_load_dword v65, v[58:59], off nt
	v_or_b32_e32 v44, 16, v22
	v_mov_b32_e32 v45, v3
	v_or_b32_e32 v46, 18, v22
	v_mov_b32_e32 v47, v3
	v_or_b32_e32 v48, 20, v22
	v_mov_b32_e32 v49, v3
	v_or_b32_e32 v50, 22, v22
	v_mov_b32_e32 v51, v3
	v_or_b32_e32 v52, 24, v22
	v_mov_b32_e32 v53, v3
	v_or_b32_e32 v54, 26, v22
	v_mov_b32_e32 v55, v3
	v_or_b32_e32 v56, 28, v22
	v_mov_b32_e32 v57, v3
	v_or_b32_e32 v58, 30, v22
	v_mov_b32_e32 v59, v3
	v_lshlrev_b64 v[44:45], 12, v[44:45]
	v_lshlrev_b64 v[46:47], 12, v[46:47]
	v_lshlrev_b64 v[48:49], 12, v[48:49]
	v_lshlrev_b64 v[50:51], 12, v[50:51]
	v_lshlrev_b64 v[52:53], 12, v[52:53]
	v_lshlrev_b64 v[54:55], 12, v[54:55]
	v_lshlrev_b64 v[56:57], 12, v[56:57]
	v_lshlrev_b64 v[58:59], 12, v[58:59]
	v_lshl_add_u64 v[44:45], v[42:43], 0, v[44:45]
	v_lshl_add_u64 v[46:47], v[42:43], 0, v[46:47]
	v_lshl_add_u64 v[48:49], v[42:43], 0, v[48:49]
	v_lshl_add_u64 v[50:51], v[42:43], 0, v[50:51]
	v_lshl_add_u64 v[52:53], v[42:43], 0, v[52:53]
	v_lshl_add_u64 v[54:55], v[42:43], 0, v[54:55]
	v_lshl_add_u64 v[56:57], v[42:43], 0, v[56:57]
	v_lshl_add_u64 v[58:59], v[42:43], 0, v[58:59]
	global_load_dword v66, v[44:45], off nt
	global_load_dword v67, v[46:47], off nt
	global_load_dword v68, v[48:49], off nt
	global_load_dword v69, v[50:51], off nt
	global_load_dword v70, v[52:53], off nt
	global_load_dword v71, v[54:55], off nt
	global_load_dword v72, v[56:57], off nt
	global_load_dword v73, v[58:59], off nt
	v_or_b32_e32 v44, 32, v22
	v_mov_b32_e32 v45, v3
	v_or_b32_e32 v46, 34, v22
	v_mov_b32_e32 v47, v3
	v_or_b32_e32 v48, 36, v22
	v_mov_b32_e32 v49, v3
	v_or_b32_e32 v50, 38, v22
	v_mov_b32_e32 v51, v3
	v_or_b32_e32 v52, 40, v22
	v_mov_b32_e32 v53, v3
	v_or_b32_e32 v54, 42, v22
	v_mov_b32_e32 v55, v3
	v_or_b32_e32 v56, 44, v22
	v_mov_b32_e32 v57, v3
	v_or_b32_e32 v58, 46, v22
	v_mov_b32_e32 v59, v3
	v_lshlrev_b64 v[44:45], 12, v[44:45]
	v_lshlrev_b64 v[46:47], 12, v[46:47]
	v_lshlrev_b64 v[48:49], 12, v[48:49]
	v_lshlrev_b64 v[50:51], 12, v[50:51]
	v_lshlrev_b64 v[52:53], 12, v[52:53]
	v_lshlrev_b64 v[54:55], 12, v[54:55]
	v_lshlrev_b64 v[56:57], 12, v[56:57]
	v_lshlrev_b64 v[58:59], 12, v[58:59]
	v_lshl_add_u64 v[44:45], v[42:43], 0, v[44:45]
	v_lshl_add_u64 v[46:47], v[42:43], 0, v[46:47]
	v_lshl_add_u64 v[48:49], v[42:43], 0, v[48:49]
	v_lshl_add_u64 v[50:51], v[42:43], 0, v[50:51]
	v_lshl_add_u64 v[52:53], v[42:43], 0, v[52:53]
	v_lshl_add_u64 v[54:55], v[42:43], 0, v[54:55]
	v_lshl_add_u64 v[56:57], v[42:43], 0, v[56:57]
	v_lshl_add_u64 v[58:59], v[42:43], 0, v[58:59]
	global_load_dword v74, v[44:45], off nt
	global_load_dword v75, v[46:47], off nt
	global_load_dword v76, v[48:49], off nt
	global_load_dword v77, v[50:51], off nt
	global_load_dword v78, v[52:53], off nt
	global_load_dword v79, v[54:55], off nt
	global_load_dword v80, v[56:57], off nt
	global_load_dword v81, v[58:59], off nt
	v_or_b32_e32 v44, 48, v22
	v_mov_b32_e32 v45, v3
	v_or_b32_e32 v46, 50, v22
	v_mov_b32_e32 v47, v3
	v_or_b32_e32 v48, 52, v22
	v_mov_b32_e32 v49, v3
	v_or_b32_e32 v50, 54, v22
	v_mov_b32_e32 v51, v3
	v_or_b32_e32 v52, 56, v22
	v_mov_b32_e32 v53, v3
	v_or_b32_e32 v54, 58, v22
	v_mov_b32_e32 v55, v3
	v_or_b32_e32 v56, 60, v22
	v_mov_b32_e32 v57, v3
	v_or_b32_e32 v58, 62, v22
	v_mov_b32_e32 v59, v3
	v_lshlrev_b64 v[44:45], 12, v[44:45]
	v_lshlrev_b64 v[46:47], 12, v[46:47]
	v_lshlrev_b64 v[48:49], 12, v[48:49]
	v_lshlrev_b64 v[50:51], 12, v[50:51]
	v_lshlrev_b64 v[52:53], 12, v[52:53]
	v_lshlrev_b64 v[54:55], 12, v[54:55]
	v_lshlrev_b64 v[56:57], 12, v[56:57]
	v_lshlrev_b64 v[58:59], 12, v[58:59]
	v_lshl_add_u64 v[44:45], v[42:43], 0, v[44:45]
	v_lshl_add_u64 v[46:47], v[42:43], 0, v[46:47]
	v_lshl_add_u64 v[48:49], v[42:43], 0, v[48:49]
	v_lshl_add_u64 v[50:51], v[42:43], 0, v[50:51]
	v_lshl_add_u64 v[52:53], v[42:43], 0, v[52:53]
	v_lshl_add_u64 v[54:55], v[42:43], 0, v[54:55]
	v_lshl_add_u64 v[56:57], v[42:43], 0, v[56:57]
	v_lshl_add_u64 v[42:43], v[42:43], 0, v[58:59]
	global_load_dword v44, v[44:45], off nt
	s_nop 0
	global_load_dword v45, v[46:47], off nt
	s_nop 0
	global_load_dword v46, v[48:49], off nt
	global_load_dword v47, v[50:51], off nt
	s_nop 0
	global_load_dword v48, v[52:53], off nt
	global_load_dword v49, v[54:55], off nt
	global_load_dword v50, v[56:57], off nt
	s_nop 0
	global_load_dword v42, v[42:43], off nt
	s_waitcnt vmcnt(30)
	ds_write2_b32 v25, v23, v41 offset1:66
	s_waitcnt vmcnt(28)
	ds_write2_b32 v25, v60, v61 offset0:132 offset1:198
	s_waitcnt vmcnt(26)
	ds_write2_b32 v31, v62, v63 offset0:8 offset1:74
	s_waitcnt vmcnt(24)
	ds_write2_b32 v31, v64, v65 offset0:140 offset1:206
	s_waitcnt vmcnt(22)
	ds_write2_b32 v32, v66, v67 offset0:16 offset1:82
	s_waitcnt vmcnt(20)
	ds_write2_b32 v32, v68, v69 offset0:148 offset1:214
	s_waitcnt vmcnt(18)
	ds_write2_b32 v33, v70, v71 offset0:24 offset1:90
	s_waitcnt vmcnt(16)
	ds_write2_b32 v33, v72, v73 offset0:156 offset1:222
	s_waitcnt vmcnt(14)
	ds_write2_b32 v34, v74, v75 offset0:32 offset1:98
	s_waitcnt vmcnt(12)
	ds_write2_b32 v34, v76, v77 offset0:164 offset1:230
	s_waitcnt vmcnt(10)
	ds_write2_b32 v35, v78, v79 offset0:40 offset1:106
	s_waitcnt vmcnt(8)
	ds_write2_b32 v35, v80, v81 offset0:172 offset1:238
	s_waitcnt vmcnt(6)
	ds_write2_b32 v36, v44, v45 offset0:48 offset1:114
	s_waitcnt vmcnt(4)
	ds_write2_b32 v36, v46, v47 offset0:180 offset1:246
	s_waitcnt vmcnt(2)
	ds_write2_b32 v37, v48, v49 offset0:56 offset1:122
	s_waitcnt vmcnt(0)
	ds_write2_b32 v37, v50, v42 offset0:188 offset1:254
	s_waitcnt lgkmcnt(0)
	ds_read2_b32 v[46:47], v27 offset0:33 offset1:41
	ds_read2_b32 v[48:49], v27 offset1:8
	ds_read2_b32 v[50:51], v27 offset0:66 offset1:74
	ds_read2_b32 v[52:53], v27 offset0:99 offset1:107
	ds_read2_b32 v[54:55], v27 offset0:132 offset1:140
	ds_read2_b32 v[56:57], v27 offset0:165 offset1:173
	ds_read2_b32 v[58:59], v27 offset0:198 offset1:206
	ds_read2_b32 v[60:61], v27 offset0:231 offset1:239
	s_mov_b32 s7, s1
	v_mul_u32_u24_e32 v23, 0xb00, v40
	v_lshl_add_u64 v[62:63], s[6:7], 1, v[16:17]
	v_lshlrev_b32_e32 v64, 1, v23
	v_mov_b32_e32 v65, v3
	s_waitcnt lgkmcnt(6)
	v_cvt_pk_bf16_f32 v42, v48, v46
	s_waitcnt lgkmcnt(4)
	v_cvt_pk_bf16_f32 v43, v50, v52
	s_waitcnt lgkmcnt(2)
	v_cvt_pk_bf16_f32 v44, v54, v56
	s_waitcnt lgkmcnt(0)
	v_cvt_pk_bf16_f32 v45, v58, v60
	v_lshl_add_u64 v[64:65], v[62:63], 0, v[64:65]
	global_store_dwordx4 v[64:65], v[42:45], off sc1
	v_mul_u32_u24_e32 v23, 0xb00, v39
	v_lshlrev_b32_e32 v46, 1, v23
	v_cvt_pk_bf16_f32 v42, v49, v47
	v_cvt_pk_bf16_f32 v43, v51, v53
	v_cvt_pk_bf16_f32 v44, v55, v57
	v_cvt_pk_bf16_f32 v45, v59, v61
	ds_read2_b32 v[48:49], v27 offset0:16 offset1:24
	ds_read2_b32 v[50:51], v27 offset0:49 offset1:57
	ds_read2_b32 v[52:53], v27 offset0:82 offset1:90
	ds_read2_b32 v[54:55], v27 offset0:115 offset1:123
	ds_read2_b32 v[56:57], v27 offset0:148 offset1:156
	ds_read2_b32 v[58:59], v27 offset0:181 offset1:189
	ds_read2_b32 v[60:61], v27 offset0:214 offset1:222
	ds_read2_b32 v[64:65], v27 offset0:247 offset1:255
	v_mov_b32_e32 v47, v3
	v_lshl_add_u64 v[46:47], v[62:63], 0, v[46:47]
	v_mul_u32_u24_e32 v23, 0xb00, v38
	global_store_dwordx4 v[46:47], v[42:45], off sc1
	v_lshlrev_b32_e32 v46, 1, v23
	v_mov_b32_e32 v47, v3
	s_waitcnt lgkmcnt(6)
	v_cvt_pk_bf16_f32 v42, v48, v50
	s_waitcnt lgkmcnt(4)
	v_cvt_pk_bf16_f32 v43, v52, v54
	s_waitcnt lgkmcnt(2)
	v_cvt_pk_bf16_f32 v44, v56, v58
	s_waitcnt lgkmcnt(0)
	v_cvt_pk_bf16_f32 v45, v60, v64
	v_lshl_add_u64 v[46:47], v[62:63], 0, v[46:47]
	v_mul_u32_u24_e32 v23, 0xb00, v21
	global_store_dwordx4 v[46:47], v[42:45], off sc1
	v_lshlrev_b32_e32 v46, 1, v23
	v_mov_b32_e32 v47, v3
	v_cvt_pk_bf16_f32 v42, v49, v51
	v_cvt_pk_bf16_f32 v43, v53, v55
	v_cvt_pk_bf16_f32 v44, v57, v59
	v_cvt_pk_bf16_f32 v45, v61, v65
	v_lshl_add_u64 v[46:47], v[62:63], 0, v[46:47]
	global_store_dwordx4 v[46:47], v[42:45], off sc1
	s_waitcnt lgkmcnt(0)
	s_mov_b64 s[14:15], 0
.LBB0_150:
	s_andn2_b64 vcc, exec, s[14:15]
	s_cbranch_vccnz .LBB0_152
	s_lshl_b32 s0, s8, 2
	v_lshl_add_u64 v[42:43], v[10:11], 0, s[0:1]
	v_lshlrev_b32_e32 v22, 10, v22
	v_mov_b32_e32 v23, v3
	v_lshl_add_u64 v[22:23], v[22:23], 2, v[42:43]
	v_add_co_u32_e32 v42, vcc, 0x2000, v22
	s_mov_b32 s7, s1
	s_nop 0
	v_addc_co_u32_e32 v43, vcc, 0, v23, vcc
	v_add_co_u32_e32 v44, vcc, 0x4000, v22
	v_mul_u32_u24_e32 v40, 0xb00, v40
	s_nop 0
	v_addc_co_u32_e32 v45, vcc, 0, v23, vcc
	v_add_co_u32_e32 v46, vcc, s29, v22
	v_mul_u32_u24_e32 v38, 0xb00, v38
	s_nop 0
	v_addc_co_u32_e32 v47, vcc, 0, v23, vcc
	v_add_co_u32_e32 v48, vcc, 0x8000, v22
	s_nop 1
	v_addc_co_u32_e32 v49, vcc, 0, v23, vcc
	v_add_co_u32_e32 v50, vcc, 0xa000, v22
	s_nop 1
	v_addc_co_u32_e32 v51, vcc, 0, v23, vcc
	v_add_co_u32_e32 v52, vcc, s30, v22
	s_nop 1
	v_addc_co_u32_e32 v53, vcc, 0, v23, vcc
	v_add_co_u32_e32 v54, vcc, 0xe000, v22
	s_nop 1
	v_addc_co_u32_e32 v55, vcc, 0, v23, vcc
	global_load_dword v41, v[22:23], off nt
	global_load_dword v58, v[42:43], off nt
	global_load_dword v59, v[44:45], off nt
	global_load_dword v60, v[46:47], off nt
	global_load_dword v61, v[48:49], off nt
	global_load_dword v62, v[50:51], off nt
	global_load_dword v63, v[52:53], off nt
	global_load_dword v64, v[54:55], off nt
	v_add_co_u32_e32 v42, vcc, 0x10000, v22
	s_nop 1
	v_addc_co_u32_e32 v43, vcc, 0, v23, vcc
	v_add_co_u32_e32 v44, vcc, s31, v22
	s_nop 1
	v_addc_co_u32_e32 v45, vcc, 0, v23, vcc
	v_add_co_u32_e32 v46, vcc, 0x14000, v22
	s_nop 1
	v_addc_co_u32_e32 v47, vcc, 0, v23, vcc
	v_add_co_u32_e32 v48, vcc, 0x16000, v22
	s_nop 1
	v_addc_co_u32_e32 v49, vcc, 0, v23, vcc
	v_add_co_u32_e32 v50, vcc, s63, v22
	s_nop 1
	v_addc_co_u32_e32 v51, vcc, 0, v23, vcc
	v_add_co_u32_e32 v52, vcc, 0x1a000, v22
	s_nop 1
	v_addc_co_u32_e32 v53, vcc, 0, v23, vcc
	v_add_co_u32_e32 v54, vcc, 0x1c000, v22
	s_nop 1
	v_addc_co_u32_e32 v55, vcc, 0, v23, vcc
	v_add_co_u32_e32 v56, vcc, s64, v22
	s_nop 1
	v_addc_co_u32_e32 v57, vcc, 0, v23, vcc
	global_load_dword v65, v[42:43], off nt
	global_load_dword v66, v[44:45], off nt
	global_load_dword v67, v[46:47], off nt
	global_load_dword v68, v[48:49], off nt
	global_load_dword v69, v[50:51], off nt
	global_load_dword v70, v[52:53], off nt
	global_load_dword v71, v[54:55], off nt
	global_load_dword v72, v[56:57], off nt
	v_add_co_u32_e32 v42, vcc, 0x20000, v22
	s_nop 1
	v_addc_co_u32_e32 v43, vcc, 0, v23, vcc
	v_add_co_u32_e32 v44, vcc, 0x22000, v22
	s_nop 1
	v_addc_co_u32_e32 v45, vcc, 0, v23, vcc
	v_add_co_u32_e32 v46, vcc, s65, v22
	s_nop 1
	v_addc_co_u32_e32 v47, vcc, 0, v23, vcc
	v_add_co_u32_e32 v48, vcc, 0x26000, v22
	s_nop 1
	v_addc_co_u32_e32 v49, vcc, 0, v23, vcc
	v_add_co_u32_e32 v50, vcc, 0x28000, v22
	s_nop 1
	v_addc_co_u32_e32 v51, vcc, 0, v23, vcc
	v_add_co_u32_e32 v52, vcc, s66, v22
	s_nop 1
	v_addc_co_u32_e32 v53, vcc, 0, v23, vcc
	v_add_co_u32_e32 v54, vcc, 0x2c000, v22
	s_nop 1
	v_addc_co_u32_e32 v55, vcc, 0, v23, vcc
	v_add_co_u32_e32 v56, vcc, 0x2e000, v22
	s_nop 1
	v_addc_co_u32_e32 v57, vcc, 0, v23, vcc
	global_load_dword v73, v[42:43], off nt
	global_load_dword v74, v[44:45], off nt
	global_load_dword v75, v[46:47], off nt
	global_load_dword v76, v[48:49], off nt
	global_load_dword v77, v[50:51], off nt
	global_load_dword v78, v[52:53], off nt
	global_load_dword v79, v[54:55], off nt
	s_nop 0
	global_load_dword v56, v[56:57], off nt
	v_add_co_u32_e32 v42, vcc, s67, v22
	s_nop 1
	v_addc_co_u32_e32 v43, vcc, 0, v23, vcc
	v_add_co_u32_e32 v44, vcc, 0x32000, v22
	s_nop 1
	v_addc_co_u32_e32 v45, vcc, 0, v23, vcc
	v_add_co_u32_e32 v46, vcc, 0x34000, v22
	s_nop 1
	v_addc_co_u32_e32 v47, vcc, 0, v23, vcc
	v_add_co_u32_e32 v48, vcc, s68, v22
	s_nop 1
	v_addc_co_u32_e32 v49, vcc, 0, v23, vcc
	v_add_co_u32_e32 v50, vcc, 0x38000, v22
	s_nop 1
	v_addc_co_u32_e32 v51, vcc, 0, v23, vcc
	v_add_co_u32_e32 v52, vcc, 0x3a000, v22
	s_nop 1
	v_addc_co_u32_e32 v53, vcc, 0, v23, vcc
	v_add_co_u32_e32 v54, vcc, s69, v22
	s_nop 1
	v_addc_co_u32_e32 v55, vcc, 0, v23, vcc
	v_add_co_u32_e32 v22, vcc, 0x3e000, v22
	s_nop 1
	v_addc_co_u32_e32 v23, vcc, 0, v23, vcc
	global_load_dword v42, v[42:43], off nt
	s_nop 0
	global_load_dword v43, v[44:45], off nt
	s_nop 0
	global_load_dword v44, v[46:47], off nt
	global_load_dword v45, v[48:49], off nt
	s_nop 0
	global_load_dword v46, v[50:51], off nt
	global_load_dword v47, v[52:53], off nt
	global_load_dword v48, v[54:55], off nt
	s_nop 0
	global_load_dword v22, v[22:23], off nt
	s_waitcnt vmcnt(30)
	ds_write2_b32 v25, v41, v58 offset1:66
	s_waitcnt vmcnt(28)
	ds_write2_b32 v25, v59, v60 offset0:132 offset1:198
	s_waitcnt vmcnt(26)
	ds_write2_b32 v31, v61, v62 offset0:8 offset1:74
	s_waitcnt vmcnt(24)
	ds_write2_b32 v31, v63, v64 offset0:140 offset1:206
	s_waitcnt vmcnt(22)
	ds_write2_b32 v32, v65, v66 offset0:16 offset1:82
	s_waitcnt vmcnt(20)
	ds_write2_b32 v32, v67, v68 offset0:148 offset1:214
	s_waitcnt vmcnt(18)
	ds_write2_b32 v33, v69, v70 offset0:24 offset1:90
	s_waitcnt vmcnt(16)
	ds_write2_b32 v33, v71, v72 offset0:156 offset1:222
	s_waitcnt vmcnt(14)
	ds_write2_b32 v34, v73, v74 offset0:32 offset1:98
	s_waitcnt vmcnt(12)
	ds_write2_b32 v34, v75, v76 offset0:164 offset1:230
	s_waitcnt vmcnt(10)
	ds_write2_b32 v35, v77, v78 offset0:40 offset1:106
	s_waitcnt vmcnt(8)
	ds_write2_b32 v35, v79, v56 offset0:172 offset1:238
	s_waitcnt vmcnt(6)
	ds_write2_b32 v36, v42, v43 offset0:48 offset1:114
	s_waitcnt vmcnt(4)
	ds_write2_b32 v36, v44, v45 offset0:180 offset1:246
	s_waitcnt vmcnt(2)
	ds_write2_b32 v37, v46, v47 offset0:56 offset1:122
	s_waitcnt vmcnt(0)
	ds_write2_b32 v37, v48, v22 offset0:188 offset1:254
	s_waitcnt lgkmcnt(0)
	ds_read2_b32 v[42:43], v27 offset0:33 offset1:41
	ds_read2_b32 v[44:45], v27 offset0:66 offset1:74
	ds_read2_b32 v[46:47], v27 offset0:99 offset1:107
	ds_read2_b32 v[48:49], v27 offset1:8
	ds_read2_b32 v[50:51], v27 offset0:132 offset1:140
	ds_read2_b32 v[52:53], v27 offset0:165 offset1:173
	ds_read2_b32 v[54:55], v27 offset0:198 offset1:206
	ds_read2_b32 v[56:57], v27 offset0:231 offset1:239
	s_waitcnt lgkmcnt(4)
	v_mul_f32_e32 v41, 0x42800000, v48
	v_mul_f32_e32 v42, 0x42800000, v42
	v_mov_b32_e32 v58, v3
	v_cvt_pk_fp8_f32 v58, v41, v42
	v_mul_f32_e32 v41, 0x42800000, v44
	v_mul_f32_e32 v42, 0x42800000, v46
	s_waitcnt lgkmcnt(3)
	v_mul_f32_e32 v44, 0x42800000, v50
	s_waitcnt lgkmcnt(2)
	v_mul_f32_e32 v46, 0x42800000, v52
	v_mov_b32_e32 v59, v3
	v_cvt_pk_fp8_f32 v59, v44, v46
	v_cvt_pk_fp8_f32 v58, v41, v42 op_sel:[0,0,1]
	s_waitcnt lgkmcnt(1)
	v_mul_f32_e32 v41, 0x42800000, v54
	s_waitcnt lgkmcnt(0)
	v_mul_f32_e32 v42, 0x42800000, v56
	v_cvt_pk_fp8_f32 v59, v41, v42 op_sel:[0,0,1]
	v_lshl_add_u64 v[22:23], v[18:19], 0, s[6:7]
	v_mov_b32_e32 v41, v3
	v_lshl_add_u64 v[40:41], v[22:23], 0, v[40:41]
	global_store_dwordx2 v[40:41], v[58:59], off sc1
	v_mul_f32_e32 v41, 0x42800000, v49
	v_mul_f32_e32 v42, 0x42800000, v43
	v_mov_b32_e32 v40, v3
	v_cvt_pk_fp8_f32 v40, v41, v42
	v_mul_f32_e32 v42, 0x42800000, v45
	v_mul_f32_e32 v44, 0x42800000, v51
	v_mul_f32_e32 v45, 0x42800000, v53
	v_mov_b32_e32 v41, v3
	v_cvt_pk_fp8_f32 v41, v44, v45
	v_mul_f32_e32 v43, 0x42800000, v47
	v_cvt_pk_fp8_f32 v40, v42, v43 op_sel:[0,0,1]
	v_mul_f32_e32 v42, 0x42800000, v55
	v_mul_f32_e32 v43, 0x42800000, v57
	v_cvt_pk_fp8_f32 v41, v42, v43 op_sel:[0,0,1]
	v_mul_u32_u24_e32 v42, 0xb00, v39
	v_mov_b32_e32 v43, v3
	v_lshl_add_u64 v[42:43], v[22:23], 0, v[42:43]
	global_store_dwordx2 v[42:43], v[40:41], off sc1
	ds_read2_b32 v[40:41], v27 offset0:16 offset1:24
	ds_read2_b32 v[42:43], v27 offset0:49 offset1:57
	ds_read2_b32 v[44:45], v27 offset0:82 offset1:90
	ds_read2_b32 v[46:47], v27 offset0:115 offset1:123
	ds_read2_b32 v[48:49], v27 offset0:148 offset1:156
	ds_read2_b32 v[50:51], v27 offset0:181 offset1:189
	ds_read2_b32 v[52:53], v27 offset0:214 offset1:222
	ds_read2_b32 v[54:55], v27 offset0:247 offset1:255
	s_waitcnt lgkmcnt(7)
	v_mul_f32_e32 v39, 0x42800000, v40
	s_waitcnt lgkmcnt(6)
	v_mul_f32_e32 v40, 0x42800000, v42
	v_mov_b32_e32 v56, v3
	v_cvt_pk_fp8_f32 v56, v39, v40
	s_waitcnt lgkmcnt(5)
	v_mul_f32_e32 v39, 0x42800000, v44
	s_waitcnt lgkmcnt(3)
	v_mul_f32_e32 v42, 0x42800000, v48
	s_waitcnt lgkmcnt(2)
	v_mul_f32_e32 v44, 0x42800000, v50
	v_mov_b32_e32 v57, v3
	v_cvt_pk_fp8_f32 v57, v42, v44
	v_mul_f32_e32 v40, 0x42800000, v46
	v_cvt_pk_fp8_f32 v56, v39, v40 op_sel:[0,0,1]
	s_waitcnt lgkmcnt(1)
	v_mul_f32_e32 v39, 0x42800000, v52
	s_waitcnt lgkmcnt(0)
	v_mul_f32_e32 v40, 0x42800000, v54
	v_cvt_pk_fp8_f32 v57, v39, v40 op_sel:[0,0,1]
	v_mov_b32_e32 v39, v3
	v_lshl_add_u64 v[38:39], v[22:23], 0, v[38:39]
	v_mul_f32_e32 v40, 0x42800000, v43
	global_store_dwordx2 v[38:39], v[56:57], off sc1
	v_mul_f32_e32 v39, 0x42800000, v41
	v_mov_b32_e32 v38, v3
	v_cvt_pk_fp8_f32 v38, v39, v40
	v_mul_f32_e32 v42, 0x42800000, v49
	v_mul_f32_e32 v43, 0x42800000, v51
	v_mov_b32_e32 v39, v3
	v_cvt_pk_fp8_f32 v39, v42, v43
	v_mul_f32_e32 v40, 0x42800000, v45
	v_mul_f32_e32 v41, 0x42800000, v47
	v_cvt_pk_fp8_f32 v38, v40, v41 op_sel:[0,0,1]
	v_mul_f32_e32 v40, 0x42800000, v53
	v_mul_f32_e32 v41, 0x42800000, v55
	v_cvt_pk_fp8_f32 v39, v40, v41 op_sel:[0,0,1]
	v_mul_u32_u24_e32 v40, 0xb00, v21
	v_mov_b32_e32 v41, v3
	v_lshl_add_u64 v[22:23], v[22:23], 0, v[40:41]
	global_store_dwordx2 v[22:23], v[38:39], off sc1
	s_waitcnt lgkmcnt(0)

.LBB0_159:
	v_readlane_b32 s80, v254, 2
	s_and_b64 s[2:3], s[2:3], exec
	v_readlane_b32 s90, v254, 12
	v_readlane_b32 s91, v254, 13
	s_cselect_b32 s2, s68, 0x300000
	s_mov_b64 s[22:23], s[90:91]
	s_cselect_b32 s3, s51, s23
	s_cselect_b32 s6, s50, s22
	s_add_u32 s7, s58, s2
	s_addc_u32 s8, s59, 0
	s_lshl_b32 s2, s5, 6
	s_ashr_i32 s5, s4, 31
	s_lshl_b64 s[4:5], s[4:5], 2
	s_add_u32 s4, s6, s4
	v_or_b32_e32 v21, s2, v24
	s_addc_u32 s5, s3, s5
	v_lshl_add_u64 v[22:23], s[4:5], 0, v[2:3]
	v_or_b32_e32 v40, 2, v21
	v_or_b32_e32 v42, 4, v21
	v_or_b32_e32 v44, 6, v21
	v_or_b32_e32 v46, 8, v21
	v_or_b32_e32 v48, 10, v21
	v_or_b32_e32 v50, 12, v21
	v_or_b32_e32 v52, 14, v21
	v_mad_i64_i32 v[38:39], s[4:5], v21, s69, v[22:23]
	v_mad_i64_i32 v[40:41], s[4:5], v40, s69, v[22:23]
	v_mad_i64_i32 v[42:43], s[4:5], v42, s69, v[22:23]
	v_mad_i64_i32 v[44:45], s[4:5], v44, s69, v[22:23]
	v_mad_i64_i32 v[46:47], s[4:5], v46, s69, v[22:23]
	v_mad_i64_i32 v[48:49], s[4:5], v48, s69, v[22:23]
	v_mad_i64_i32 v[50:51], s[4:5], v50, s69, v[22:23]
	v_mad_i64_i32 v[52:53], s[4:5], v52, s69, v[22:23]
	global_load_dword v54, v[38:39], off nt
	global_load_dword v55, v[40:41], off nt
	global_load_dword v56, v[42:43], off nt
	global_load_dword v57, v[44:45], off nt
	global_load_dword v58, v[46:47], off nt
	global_load_dword v59, v[48:49], off nt
	global_load_dword v60, v[50:51], off nt
	global_load_dword v61, v[52:53], off nt
	v_or_b32_e32 v38, 16, v21
	v_or_b32_e32 v40, 18, v21
	v_or_b32_e32 v42, 20, v21
	v_or_b32_e32 v44, 22, v21
	v_or_b32_e32 v46, 24, v21
	v_or_b32_e32 v48, 26, v21
	v_or_b32_e32 v50, 28, v21
	v_or_b32_e32 v52, 30, v21
	v_mad_i64_i32 v[38:39], s[4:5], v38, s69, v[22:23]
	v_mad_i64_i32 v[40:41], s[4:5], v40, s69, v[22:23]
	v_mad_i64_i32 v[42:43], s[4:5], v42, s69, v[22:23]
	v_mad_i64_i32 v[44:45], s[4:5], v44, s69, v[22:23]
	v_mad_i64_i32 v[46:47], s[4:5], v46, s69, v[22:23]
	v_mad_i64_i32 v[48:49], s[4:5], v48, s69, v[22:23]
	v_mad_i64_i32 v[50:51], s[4:5], v50, s69, v[22:23]
	v_mad_i64_i32 v[52:53], s[4:5], v52, s69, v[22:23]
	global_load_dword v62, v[38:39], off nt
	global_load_dword v63, v[40:41], off nt
	global_load_dword v64, v[42:43], off nt
	global_load_dword v65, v[44:45], off nt
	global_load_dword v66, v[46:47], off nt
	global_load_dword v67, v[48:49], off nt
	global_load_dword v68, v[50:51], off nt
	global_load_dword v69, v[52:53], off nt
	v_or_b32_e32 v38, 32, v21
	v_or_b32_e32 v40, 34, v21
	v_or_b32_e32 v42, 36, v21
	v_or_b32_e32 v44, 38, v21
	v_or_b32_e32 v46, 40, v21
	v_or_b32_e32 v48, 42, v21
	v_or_b32_e32 v50, 44, v21
	v_or_b32_e32 v52, 46, v21
	v_mad_i64_i32 v[38:39], s[4:5], v38, s69, v[22:23]
	v_mad_i64_i32 v[40:41], s[4:5], v40, s69, v[22:23]
	v_mad_i64_i32 v[42:43], s[4:5], v42, s69, v[22:23]
	v_mad_i64_i32 v[44:45], s[4:5], v44, s69, v[22:23]
	v_mad_i64_i32 v[46:47], s[4:5], v46, s69, v[22:23]
	v_mad_i64_i32 v[48:49], s[4:5], v48, s69, v[22:23]
	v_mad_i64_i32 v[50:51], s[4:5], v50, s69, v[22:23]
	v_mad_i64_i32 v[52:53], s[4:5], v52, s69, v[22:23]
	global_load_dword v70, v[38:39], off nt
	global_load_dword v71, v[40:41], off nt
	global_load_dword v72, v[42:43], off nt
	global_load_dword v73, v[44:45], off nt
	global_load_dword v74, v[46:47], off nt
	global_load_dword v75, v[48:49], off nt
	global_load_dword v76, v[50:51], off nt
	s_nop 0
	global_load_dword v52, v[52:53], off nt
	v_or_b32_e32 v38, 48, v21
	v_or_b32_e32 v40, 50, v21
	v_or_b32_e32 v42, 52, v21
	v_or_b32_e32 v44, 54, v21
	v_or_b32_e32 v46, 56, v21
	v_or_b32_e32 v48, 58, v21
	v_or_b32_e32 v50, 60, v21
	v_or_b32_e32 v21, 62, v21
	v_mad_i64_i32 v[38:39], s[4:5], v38, s69, v[22:23]
	v_mad_i64_i32 v[40:41], s[4:5], v40, s69, v[22:23]
	v_mad_i64_i32 v[42:43], s[4:5], v42, s69, v[22:23]
	v_mad_i64_i32 v[44:45], s[4:5], v44, s69, v[22:23]
	v_mad_i64_i32 v[46:47], s[4:5], v46, s69, v[22:23]
	v_mad_i64_i32 v[48:49], s[4:5], v48, s69, v[22:23]
	v_mad_i64_i32 v[50:51], s[4:5], v50, s69, v[22:23]
	v_mad_i64_i32 v[22:23], s[4:5], v21, s69, v[22:23]
	global_load_dword v21, v[38:39], off nt
	s_nop 0
	global_load_dword v38, v[40:41], off nt
	global_load_dword v39, v[42:43], off nt
	s_nop 0
	global_load_dword v40, v[44:45], off nt
	global_load_dword v41, v[46:47], off nt
	global_load_dword v42, v[48:49], off nt
	global_load_dword v43, v[50:51], off nt
	s_nop 0
	global_load_dword v22, v[22:23], off nt
	s_waitcnt vmcnt(30)
	ds_write2_b32 v25, v54, v55 offset1:66
	s_waitcnt vmcnt(28)
	ds_write2_b32 v25, v56, v57 offset0:132 offset1:198
	s_waitcnt vmcnt(26)
	ds_write2_b32 v31, v58, v59 offset0:8 offset1:74
	s_waitcnt vmcnt(24)
	ds_write2_b32 v31, v60, v61 offset0:140 offset1:206
	s_waitcnt vmcnt(22)
	ds_write2_b32 v32, v62, v63 offset0:16 offset1:82
	s_waitcnt vmcnt(20)
	ds_write2_b32 v32, v64, v65 offset0:148 offset1:214
	s_waitcnt vmcnt(18)
	ds_write2_b32 v33, v66, v67 offset0:24 offset1:90
	s_waitcnt vmcnt(16)
	ds_write2_b32 v33, v68, v69 offset0:156 offset1:222
	s_waitcnt vmcnt(14)
	ds_write2_b32 v34, v70, v71 offset0:32 offset1:98
	s_waitcnt vmcnt(12)
	ds_write2_b32 v34, v72, v73 offset0:164 offset1:230
	s_waitcnt vmcnt(10)
	ds_write2_b32 v35, v74, v75 offset0:40 offset1:106
	s_waitcnt vmcnt(8)
	ds_write2_b32 v35, v76, v52 offset0:172 offset1:238
	s_waitcnt vmcnt(6)
	ds_write2_b32 v36, v21, v38 offset0:48 offset1:114
	s_waitcnt vmcnt(4)
	ds_write2_b32 v36, v39, v40 offset0:180 offset1:246
	s_waitcnt vmcnt(2)
	ds_write2_b32 v37, v41, v42 offset0:56 offset1:122
	s_waitcnt vmcnt(0)
	ds_write2_b32 v37, v43, v22 offset0:188 offset1:254
	s_waitcnt lgkmcnt(0)
	s_ashr_i32 s3, s2, 31
	ds_read2_b32 v[22:23], v27 offset0:33 offset1:41
	ds_read2_b32 v[42:43], v27 offset1:8
	ds_read2_b32 v[44:45], v27 offset0:66 offset1:74
	ds_read2_b32 v[46:47], v27 offset0:99 offset1:107
	ds_read2_b32 v[48:49], v27 offset0:132 offset1:140
	ds_read2_b32 v[50:51], v27 offset0:165 offset1:173
	ds_read2_b32 v[52:53], v27 offset0:198 offset1:206
	ds_read2_b32 v[54:55], v27 offset0:231 offset1:239
	s_lshl_b64 s[2:3], s[2:3], 1
	s_add_u32 s2, s7, s2
	v_add_u32_e32 v58, s0, v26
	s_addc_u32 s3, s8, s3
	v_mov_b32_e32 v21, v3
	v_ashrrev_i32_e32 v59, 31, v58
	v_lshl_add_u64 v[56:57], s[2:3], 0, v[20:21]
	v_lshlrev_b64 v[58:59], 11, v[58:59]
	s_waitcnt lgkmcnt(6)
	v_cvt_pk_bf16_f32 v38, v42, v22
	s_waitcnt lgkmcnt(4)
	v_cvt_pk_bf16_f32 v39, v44, v46
	s_waitcnt lgkmcnt(2)
	v_cvt_pk_bf16_f32 v40, v48, v50
	s_waitcnt lgkmcnt(0)
	v_cvt_pk_bf16_f32 v41, v52, v54
	v_lshl_add_u64 v[58:59], v[56:57], 0, v[58:59]
	v_add_u32_e32 v22, s0, v28
	global_store_dwordx4 v[58:59], v[38:41], off sc1
	v_readlane_b32 s81, v254, 3
	v_readlane_b32 s82, v254, 4
	v_cvt_pk_bf16_f32 v38, v43, v23
	v_ashrrev_i32_e32 v23, 31, v22
	v_cvt_pk_bf16_f32 v39, v45, v47
	v_cvt_pk_bf16_f32 v40, v49, v51
	v_cvt_pk_bf16_f32 v41, v53, v55
	v_lshlrev_b64 v[22:23], 11, v[22:23]
	ds_read2_b32 v[42:43], v27 offset0:49 offset1:57
	ds_read2_b32 v[44:45], v27 offset0:16 offset1:24
	ds_read2_b32 v[46:47], v27 offset0:82 offset1:90
	ds_read2_b32 v[48:49], v27 offset0:115 offset1:123
	ds_read2_b32 v[50:51], v27 offset0:148 offset1:156
	ds_read2_b32 v[52:53], v27 offset0:181 offset1:189
	ds_read2_b32 v[54:55], v27 offset0:214 offset1:222
	ds_read2_b32 v[58:59], v27 offset0:247 offset1:255
	v_lshl_add_u64 v[22:23], v[56:57], 0, v[22:23]
	global_store_dwordx4 v[22:23], v[38:41], off sc1
	v_add_u32_e32 v22, s0, v29
	v_ashrrev_i32_e32 v23, 31, v22
	v_lshlrev_b64 v[22:23], 11, v[22:23]
	s_waitcnt lgkmcnt(6)
	v_cvt_pk_bf16_f32 v38, v44, v42
	s_waitcnt lgkmcnt(4)
	v_cvt_pk_bf16_f32 v39, v46, v48
	s_waitcnt lgkmcnt(2)
	v_cvt_pk_bf16_f32 v40, v50, v52
	s_waitcnt lgkmcnt(0)
	v_cvt_pk_bf16_f32 v41, v54, v58
	v_lshl_add_u64 v[22:23], v[56:57], 0, v[22:23]
	global_store_dwordx4 v[22:23], v[38:41], off sc1
	v_add_u32_e32 v22, s0, v30
	v_ashrrev_i32_e32 v23, 31, v22
	v_lshlrev_b64 v[22:23], 11, v[22:23]
	v_cvt_pk_bf16_f32 v38, v45, v43
	v_cvt_pk_bf16_f32 v39, v47, v49
	v_cvt_pk_bf16_f32 v40, v51, v53
	v_cvt_pk_bf16_f32 v41, v55, v59
	v_lshl_add_u64 v[22:23], v[56:57], 0, v[22:23]
	global_store_dwordx4 v[22:23], v[38:41], off sc1
	s_waitcnt lgkmcnt(0)
	v_readlane_b32 s83, v254, 5
	v_readlane_b32 s84, v254, 6
	v_readlane_b32 s85, v254, 7
	v_readlane_b32 s86, v254, 8
	v_readlane_b32 s87, v254, 9
	v_readlane_b32 s88, v254, 10
	v_readlane_b32 s89, v254, 11
	v_readlane_b32 s92, v254, 14
	v_readlane_b32 s93, v254, 15
	v_readlane_b32 s94, v254, 16
	v_readlane_b32 s95, v254, 17

.LBB0_163:
	s_cmpk_gt_u32 s70, 0x107f
	s_cbranch_scc0 .LBB0_171
	s_cmpk_gt_u32 s70, 0x167f
	s_cbranch_scc0 .LBB0_166
	s_lshl_b32 s0, s70, 1
	s_and_b32 s0, s0, 0x7fffffc0
	s_add_i32 s6, s0, 0xffffd300
	s_and_b32 s8, s19, 0x3e0
	v_or_b32_e32 v22, s6, v24
	s_lshl_b32 s0, s8, 2
	v_mov_b32_e32 v23, v3
	v_or_b32_e32 v42, 2, v22
	v_mov_b32_e32 v43, v3
	v_or_b32_e32 v44, 4, v22
	v_mov_b32_e32 v45, v3
	v_or_b32_e32 v46, 6, v22
	v_mov_b32_e32 v47, v3
	v_or_b32_e32 v48, 8, v22
	v_mov_b32_e32 v49, v3
	v_or_b32_e32 v50, 10, v22
	v_mov_b32_e32 v51, v3
	v_or_b32_e32 v52, 12, v22
	v_mov_b32_e32 v53, v3
	v_or_b32_e32 v54, 14, v22
	v_mov_b32_e32 v55, v3
	v_lshl_add_u64 v[38:39], v[4:5], 0, s[0:1]
	v_lshlrev_b64 v[40:41], 12, v[22:23]
	v_lshlrev_b64 v[42:43], 12, v[42:43]
	v_lshlrev_b64 v[44:45], 12, v[44:45]
	v_lshlrev_b64 v[46:47], 12, v[46:47]
	v_lshlrev_b64 v[48:49], 12, v[48:49]
	v_lshlrev_b64 v[50:51], 12, v[50:51]
	v_lshlrev_b64 v[52:53], 12, v[52:53]
	v_lshlrev_b64 v[54:55], 12, v[54:55]
	v_lshl_add_u64 v[40:41], v[38:39], 0, v[40:41]
	v_lshl_add_u64 v[42:43], v[38:39], 0, v[42:43]
	v_lshl_add_u64 v[44:45], v[38:39], 0, v[44:45]
	v_lshl_add_u64 v[46:47], v[38:39], 0, v[46:47]
	v_lshl_add_u64 v[48:49], v[38:39], 0, v[48:49]
	v_lshl_add_u64 v[50:51], v[38:39], 0, v[50:51]
	v_lshl_add_u64 v[52:53], v[38:39], 0, v[52:53]
	v_lshl_add_u64 v[54:55], v[38:39], 0, v[54:55]
	global_load_dword v21, v[40:41], off nt
	global_load_dword v56, v[42:43], off nt
	global_load_dword v57, v[44:45], off nt
	global_load_dword v58, v[46:47], off nt
	global_load_dword v59, v[48:49], off nt
	global_load_dword v60, v[50:51], off nt
	global_load_dword v61, v[52:53], off nt
	global_load_dword v62, v[54:55], off nt
	v_or_b32_e32 v40, 16, v22
	v_mov_b32_e32 v41, v3
	v_or_b32_e32 v42, 18, v22
	v_mov_b32_e32 v43, v3
	v_or_b32_e32 v44, 20, v22
	v_mov_b32_e32 v45, v3
	v_or_b32_e32 v46, 22, v22
	v_mov_b32_e32 v47, v3
	v_or_b32_e32 v48, 24, v22
	v_mov_b32_e32 v49, v3
	v_or_b32_e32 v50, 26, v22
	v_mov_b32_e32 v51, v3
	v_or_b32_e32 v52, 28, v22
	v_mov_b32_e32 v53, v3
	v_or_b32_e32 v54, 30, v22
	v_mov_b32_e32 v55, v3
	v_lshlrev_b64 v[40:41], 12, v[40:41]
	v_lshlrev_b64 v[42:43], 12, v[42:43]
	v_lshlrev_b64 v[44:45], 12, v[44:45]
	v_lshlrev_b64 v[46:47], 12, v[46:47]
	v_lshlrev_b64 v[48:49], 12, v[48:49]
	v_lshlrev_b64 v[50:51], 12, v[50:51]
	v_lshlrev_b64 v[52:53], 12, v[52:53]
	v_lshlrev_b64 v[54:55], 12, v[54:55]
	v_lshl_add_u64 v[40:41], v[38:39], 0, v[40:41]
	v_lshl_add_u64 v[42:43], v[38:39], 0, v[42:43]
	v_lshl_add_u64 v[44:45], v[38:39], 0, v[44:45]
	v_lshl_add_u64 v[46:47], v[38:39], 0, v[46:47]
	v_lshl_add_u64 v[48:49], v[38:39], 0, v[48:49]
	v_lshl_add_u64 v[50:51], v[38:39], 0, v[50:51]
	v_lshl_add_u64 v[52:53], v[38:39], 0, v[52:53]
	v_lshl_add_u64 v[54:55], v[38:39], 0, v[54:55]
	global_load_dword v63, v[40:41], off nt
	global_load_dword v64, v[42:43], off nt
	global_load_dword v65, v[44:45], off nt
	global_load_dword v66, v[46:47], off nt
	global_load_dword v67, v[48:49], off nt
	global_load_dword v68, v[50:51], off nt
	global_load_dword v69, v[52:53], off nt
	global_load_dword v70, v[54:55], off nt
	v_or_b32_e32 v40, 32, v22
	v_mov_b32_e32 v41, v3
	v_or_b32_e32 v42, 34, v22
	v_mov_b32_e32 v43, v3
	v_or_b32_e32 v44, 36, v22
	v_mov_b32_e32 v45, v3
	v_or_b32_e32 v46, 38, v22
	v_mov_b32_e32 v47, v3
	v_or_b32_e32 v48, 40, v22
	v_mov_b32_e32 v49, v3
	v_or_b32_e32 v50, 42, v22
	v_mov_b32_e32 v51, v3
	v_or_b32_e32 v52, 44, v22
	v_mov_b32_e32 v53, v3
	v_or_b32_e32 v54, 46, v22
	v_mov_b32_e32 v55, v3
	v_lshlrev_b64 v[40:41], 12, v[40:41]
	v_lshlrev_b64 v[42:43], 12, v[42:43]
	v_lshlrev_b64 v[44:45], 12, v[44:45]
	v_lshlrev_b64 v[46:47], 12, v[46:47]
	v_lshlrev_b64 v[48:49], 12, v[48:49]
	v_lshlrev_b64 v[50:51], 12, v[50:51]
	v_lshlrev_b64 v[52:53], 12, v[52:53]
	v_lshlrev_b64 v[54:55], 12, v[54:55]
	v_lshl_add_u64 v[40:41], v[38:39], 0, v[40:41]
	v_lshl_add_u64 v[42:43], v[38:39], 0, v[42:43]
	v_lshl_add_u64 v[44:45], v[38:39], 0, v[44:45]
	v_lshl_add_u64 v[46:47], v[38:39], 0, v[46:47]
	v_lshl_add_u64 v[48:49], v[38:39], 0, v[48:49]
	v_lshl_add_u64 v[50:51], v[38:39], 0, v[50:51]
	v_lshl_add_u64 v[52:53], v[38:39], 0, v[52:53]
	v_lshl_add_u64 v[54:55], v[38:39], 0, v[54:55]
	global_load_dword v71, v[40:41], off nt
	global_load_dword v72, v[42:43], off nt
	global_load_dword v73, v[44:45], off nt
	global_load_dword v74, v[46:47], off nt
	global_load_dword v75, v[48:49], off nt
	global_load_dword v76, v[50:51], off nt
	global_load_dword v77, v[52:53], off nt
	s_nop 0
	global_load_dword v54, v[54:55], off nt
	v_or_b32_e32 v40, 48, v22
	v_mov_b32_e32 v41, v3
	v_or_b32_e32 v42, 50, v22
	v_mov_b32_e32 v43, v3
	v_or_b32_e32 v44, 52, v22
	v_mov_b32_e32 v45, v3
	v_or_b32_e32 v46, 54, v22
	v_or_b32_e32 v48, 56, v22
	v_or_b32_e32 v50, 58, v22
	v_or_b32_e32 v52, 60, v22
	v_or_b32_e32 v22, 62, v22
	v_lshlrev_b64 v[40:41], 12, v[40:41]
	v_lshlrev_b64 v[42:43], 12, v[42:43]
	v_lshlrev_b64 v[44:45], 12, v[44:45]
	v_mov_b32_e32 v47, v3
	v_mov_b32_e32 v49, v3
	v_mov_b32_e32 v51, v3
	v_mov_b32_e32 v53, v3
	v_lshlrev_b64 v[22:23], 12, v[22:23]
	v_lshl_add_u64 v[40:41], v[38:39], 0, v[40:41]
	v_lshl_add_u64 v[42:43], v[38:39], 0, v[42:43]
	v_lshl_add_u64 v[44:45], v[38:39], 0, v[44:45]
	v_lshlrev_b64 v[46:47], 12, v[46:47]
	v_lshlrev_b64 v[48:49], 12, v[48:49]
	v_lshlrev_b64 v[50:51], 12, v[50:51]
	v_lshlrev_b64 v[52:53], 12, v[52:53]
	v_lshl_add_u64 v[22:23], v[38:39], 0, v[22:23]
	v_lshl_add_u64 v[46:47], v[38:39], 0, v[46:47]
	v_lshl_add_u64 v[48:49], v[38:39], 0, v[48:49]
	v_lshl_add_u64 v[50:51], v[38:39], 0, v[50:51]
	v_lshl_add_u64 v[52:53], v[38:39], 0, v[52:53]
	global_load_dword v38, v[40:41], off nt
	global_load_dword v39, v[42:43], off nt
	s_nop 0
	global_load_dword v40, v[44:45], off nt
	global_load_dword v41, v[46:47], off nt
	global_load_dword v42, v[48:49], off nt
	global_load_dword v43, v[50:51], off nt
	s_nop 0
	global_load_dword v44, v[52:53], off nt
	s_nop 0
	global_load_dword v22, v[22:23], off nt
	s_waitcnt vmcnt(30)
	ds_write2_b32 v25, v21, v56 offset1:66
	s_waitcnt vmcnt(28)
	ds_write2_b32 v25, v57, v58 offset0:132 offset1:198
	s_waitcnt vmcnt(26)
	ds_write2_b32 v31, v59, v60 offset0:8 offset1:74
	s_waitcnt vmcnt(24)
	ds_write2_b32 v31, v61, v62 offset0:140 offset1:206
	s_waitcnt vmcnt(22)
	ds_write2_b32 v32, v63, v64 offset0:16 offset1:82
	s_waitcnt vmcnt(20)
	ds_write2_b32 v32, v65, v66 offset0:148 offset1:214
	s_waitcnt vmcnt(18)
	ds_write2_b32 v33, v67, v68 offset0:24 offset1:90
	s_waitcnt vmcnt(16)
	ds_write2_b32 v33, v69, v70 offset0:156 offset1:222
	s_waitcnt vmcnt(14)
	ds_write2_b32 v34, v71, v72 offset0:32 offset1:98
	s_waitcnt vmcnt(12)
	ds_write2_b32 v34, v73, v74 offset0:164 offset1:230
	s_waitcnt vmcnt(10)
	ds_write2_b32 v35, v75, v76 offset0:40 offset1:106
	s_waitcnt vmcnt(8)
	ds_write2_b32 v35, v77, v54 offset0:172 offset1:238
	s_waitcnt vmcnt(6)
	ds_write2_b32 v36, v38, v39 offset0:48 offset1:114
	s_waitcnt vmcnt(4)
	ds_write2_b32 v36, v40, v41 offset0:180 offset1:246
	s_waitcnt vmcnt(2)
	ds_write2_b32 v37, v42, v43 offset0:56 offset1:122
	s_waitcnt vmcnt(0)
	ds_write2_b32 v37, v44, v22 offset0:188 offset1:254
	s_waitcnt lgkmcnt(0)
	ds_read2_b32 v[22:23], v27 offset0:33 offset1:41
	ds_read2_b32 v[42:43], v27 offset1:8
	ds_read2_b32 v[44:45], v27 offset0:66 offset1:74
	ds_read2_b32 v[46:47], v27 offset0:99 offset1:107
	ds_read2_b32 v[48:49], v27 offset0:132 offset1:140
	ds_read2_b32 v[50:51], v27 offset0:165 offset1:173
	ds_read2_b32 v[52:53], v27 offset0:198 offset1:206
	ds_read2_b32 v[54:55], v27 offset0:231 offset1:239
	s_mov_b32 s7, s1
	v_or_b32_e32 v21, s8, v26
	v_lshl_add_u64 v[56:57], s[6:7], 1, v[12:13]
	v_lshlrev_b32_e32 v58, 11, v21
	v_mov_b32_e32 v59, v3
	s_waitcnt lgkmcnt(6)
	v_cvt_pk_bf16_f32 v38, v42, v22
	s_waitcnt lgkmcnt(4)
	v_cvt_pk_bf16_f32 v39, v44, v46
	s_waitcnt lgkmcnt(2)
	v_cvt_pk_bf16_f32 v40, v48, v50
	s_waitcnt lgkmcnt(0)
	v_cvt_pk_bf16_f32 v41, v52, v54
	v_lshl_add_u64 v[58:59], v[56:57], 0, v[58:59]
	global_store_dwordx4 v[58:59], v[38:41], off sc1
	v_or_b32_e32 v21, s8, v28
	v_lshlrev_b32_e32 v22, 11, v21
	v_cvt_pk_bf16_f32 v38, v43, v23
	v_cvt_pk_bf16_f32 v39, v45, v47
	v_cvt_pk_bf16_f32 v40, v49, v51
	v_cvt_pk_bf16_f32 v41, v53, v55
	ds_read2_b32 v[42:43], v27 offset0:49 offset1:57
	ds_read2_b32 v[44:45], v27 offset0:16 offset1:24
	ds_read2_b32 v[46:47], v27 offset0:82 offset1:90
	ds_read2_b32 v[48:49], v27 offset0:115 offset1:123
	ds_read2_b32 v[50:51], v27 offset0:148 offset1:156
	ds_read2_b32 v[52:53], v27 offset0:181 offset1:189
	ds_read2_b32 v[54:55], v27 offset0:214 offset1:222
	ds_read2_b32 v[58:59], v27 offset0:247 offset1:255
	v_mov_b32_e32 v23, v3
	v_lshl_add_u64 v[22:23], v[56:57], 0, v[22:23]
	v_or_b32_e32 v21, s8, v29
	global_store_dwordx4 v[22:23], v[38:41], off sc1
	v_lshlrev_b32_e32 v22, 11, v21
	v_mov_b32_e32 v23, v3
	s_waitcnt lgkmcnt(6)
	v_cvt_pk_bf16_f32 v38, v44, v42
	s_waitcnt lgkmcnt(4)
	v_cvt_pk_bf16_f32 v39, v46, v48
	s_waitcnt lgkmcnt(2)
	v_cvt_pk_bf16_f32 v40, v50, v52
	s_waitcnt lgkmcnt(0)
	v_cvt_pk_bf16_f32 v41, v54, v58
	v_lshl_add_u64 v[22:23], v[56:57], 0, v[22:23]
	v_or_b32_e32 v21, s8, v30
	global_store_dwordx4 v[22:23], v[38:41], off sc1
	v_lshlrev_b32_e32 v22, 11, v21
	v_mov_b32_e32 v23, v3
	v_cvt_pk_bf16_f32 v38, v45, v43
	v_cvt_pk_bf16_f32 v39, v47, v49
	v_cvt_pk_bf16_f32 v40, v51, v53
	v_cvt_pk_bf16_f32 v41, v55, v59
	v_lshl_add_u64 v[22:23], v[56:57], 0, v[22:23]
	global_store_dwordx4 v[22:23], v[38:41], off sc1
	s_waitcnt lgkmcnt(0)
	s_mov_b64 s[6:7], 0

.LBB0_171:
	s_andn2_b64 vcc, exec, s[6:7]
	s_cbranch_vccnz .LBB0_176
	s_lshl_b32 s0, s70, 1
	s_and_b32 s0, s0, 0x3fc0
	s_add_i32 s6, s0, 0xffffea00
	s_and_b32 s8, s19, 0x3e0
	v_or_b32_e32 v22, s6, v24
	s_mov_b64 s[14:15], -1
	s_and_b64 vcc, exec, s[4:5]
	v_or_b32_e32 v40, s8, v26
	v_or_b32_e32 v39, s8, v28
	v_or_b32_e32 v38, s8, v29
	v_or_b32_e32 v21, s8, v30
	s_cbranch_vccz .LBB0_174
	s_lshl_b32 s0, s8, 2
	v_mov_b32_e32 v23, v3
	v_or_b32_e32 v46, 2, v22
	v_mov_b32_e32 v47, v3
	v_or_b32_e32 v48, 4, v22
	v_mov_b32_e32 v49, v3
	v_or_b32_e32 v50, 6, v22
	v_mov_b32_e32 v51, v3
	v_or_b32_e32 v52, 8, v22
	v_mov_b32_e32 v53, v3
	v_or_b32_e32 v54, 10, v22
	v_mov_b32_e32 v55, v3
	v_or_b32_e32 v56, 12, v22
	v_mov_b32_e32 v57, v3
	v_or_b32_e32 v58, 14, v22
	v_mov_b32_e32 v59, v3
	v_lshl_add_u64 v[42:43], v[8:9], 0, s[0:1]
	v_lshlrev_b64 v[44:45], 12, v[22:23]
	v_lshlrev_b64 v[46:47], 12, v[46:47]
	v_lshlrev_b64 v[48:49], 12, v[48:49]
	v_lshlrev_b64 v[50:51], 12, v[50:51]
	v_lshlrev_b64 v[52:53], 12, v[52:53]
	v_lshlrev_b64 v[54:55], 12, v[54:55]
	v_lshlrev_b64 v[56:57], 12, v[56:57]
	v_lshlrev_b64 v[58:59], 12, v[58:59]
	v_lshl_add_u64 v[44:45], v[42:43], 0, v[44:45]
	v_lshl_add_u64 v[46:47], v[42:43], 0, v[46:47]
	v_lshl_add_u64 v[48:49], v[42:43], 0, v[48:49]
	v_lshl_add_u64 v[50:51], v[42:43], 0, v[50:51]
	v_lshl_add_u64 v[52:53], v[42:43], 0, v[52:53]
	v_lshl_add_u64 v[54:55], v[42:43], 0, v[54:55]
	v_lshl_add_u64 v[56:57], v[42:43], 0, v[56:57]
	v_lshl_add_u64 v[58:59], v[42:43], 0, v[58:59]
	global_load_dword v23, v[44:45], off nt
	global_load_dword v41, v[46:47], off nt
	global_load_dword v60, v[48:49], off nt
	global_load_dword v61, v[50:51], off nt
	global_load_dword v62, v[52:53], off nt
	global_load_dword v63, v[54:55], off nt
	global_load_dword v64, v[56:57], off nt
	global_load_dword v65, v[58:59], off nt
	v_or_b32_e32 v44, 16, v22
	v_mov_b32_e32 v45, v3
	v_or_b32_e32 v46, 18, v22
	v_mov_b32_e32 v47, v3
	v_or_b32_e32 v48, 20, v22
	v_mov_b32_e32 v49, v3
	v_or_b32_e32 v50, 22, v22
	v_mov_b32_e32 v51, v3
	v_or_b32_e32 v52, 24, v22
	v_mov_b32_e32 v53, v3
	v_or_b32_e32 v54, 26, v22
	v_mov_b32_e32 v55, v3
	v_or_b32_e32 v56, 28, v22
	v_mov_b32_e32 v57, v3
	v_or_b32_e32 v58, 30, v22
	v_mov_b32_e32 v59, v3
	v_lshlrev_b64 v[44:45], 12, v[44:45]
	v_lshlrev_b64 v[46:47], 12, v[46:47]
	v_lshlrev_b64 v[48:49], 12, v[48:49]
	v_lshlrev_b64 v[50:51], 12, v[50:51]
	v_lshlrev_b64 v[52:53], 12, v[52:53]
	v_lshlrev_b64 v[54:55], 12, v[54:55]
	v_lshlrev_b64 v[56:57], 12, v[56:57]
	v_lshlrev_b64 v[58:59], 12, v[58:59]
	v_lshl_add_u64 v[44:45], v[42:43], 0, v[44:45]
	v_lshl_add_u64 v[46:47], v[42:43], 0, v[46:47]
	v_lshl_add_u64 v[48:49], v[42:43], 0, v[48:49]
	v_lshl_add_u64 v[50:51], v[42:43], 0, v[50:51]
	v_lshl_add_u64 v[52:53], v[42:43], 0, v[52:53]
	v_lshl_add_u64 v[54:55], v[42:43], 0, v[54:55]
	v_lshl_add_u64 v[56:57], v[42:43], 0, v[56:57]
	v_lshl_add_u64 v[58:59], v[42:43], 0, v[58:59]
	global_load_dword v66, v[44:45], off nt
	global_load_dword v67, v[46:47], off nt
	global_load_dword v68, v[48:49], off nt
	global_load_dword v69, v[50:51], off nt
	global_load_dword v70, v[52:53], off nt
	global_load_dword v71, v[54:55], off nt
	global_load_dword v72, v[56:57], off nt
	global_load_dword v73, v[58:59], off nt
	v_or_b32_e32 v44, 32, v22
	v_mov_b32_e32 v45, v3
	v_or_b32_e32 v46, 34, v22
	v_mov_b32_e32 v47, v3
	v_or_b32_e32 v48, 36, v22
	v_mov_b32_e32 v49, v3
	v_or_b32_e32 v50, 38, v22
	v_mov_b32_e32 v51, v3
	v_or_b32_e32 v52, 40, v22
	v_mov_b32_e32 v53, v3
	v_or_b32_e32 v54, 42, v22
	v_mov_b32_e32 v55, v3
	v_or_b32_e32 v56, 44, v22
	v_mov_b32_e32 v57, v3
	v_or_b32_e32 v58, 46, v22
	v_mov_b32_e32 v59, v3
	v_lshlrev_b64 v[44:45], 12, v[44:45]
	v_lshlrev_b64 v[46:47], 12, v[46:47]
	v_lshlrev_b64 v[48:49], 12, v[48:49]
	v_lshlrev_b64 v[50:51], 12, v[50:51]
	v_lshlrev_b64 v[52:53], 12, v[52:53]
	v_lshlrev_b64 v[54:55], 12, v[54:55]
	v_lshlrev_b64 v[56:57], 12, v[56:57]
	v_lshlrev_b64 v[58:59], 12, v[58:59]
	v_lshl_add_u64 v[44:45], v[42:43], 0, v[44:45]
	v_lshl_add_u64 v[46:47], v[42:43], 0, v[46:47]
	v_lshl_add_u64 v[48:49], v[42:43], 0, v[48:49]
	v_lshl_add_u64 v[50:51], v[42:43], 0, v[50:51]
	v_lshl_add_u64 v[52:53], v[42:43], 0, v[52:53]
	v_lshl_add_u64 v[54:55], v[42:43], 0, v[54:55]
	v_lshl_add_u64 v[56:57], v[42:43], 0, v[56:57]
	v_lshl_add_u64 v[58:59], v[42:43], 0, v[58:59]
	global_load_dword v74, v[44:45], off nt
	global_load_dword v75, v[46:47], off nt
	global_load_dword v76, v[48:49], off nt
	global_load_dword v77, v[50:51], off nt
	global_load_dword v78, v[52:53], off nt
	global_load_dword v79, v[54:55], off nt
	global_load_dword v80, v[56:57], off nt
	global_load_dword v81, v[58:59], off nt
	v_or_b32_e32 v44, 48, v22
	v_mov_b32_e32 v45, v3
	v_or_b32_e32 v46, 50, v22
	v_mov_b32_e32 v47, v3
	v_or_b32_e32 v48, 52, v22
	v_mov_b32_e32 v49, v3
	v_or_b32_e32 v50, 54, v22
	v_mov_b32_e32 v51, v3
	v_or_b32_e32 v52, 56, v22
	v_mov_b32_e32 v53, v3
	v_or_b32_e32 v54, 58, v22
	v_mov_b32_e32 v55, v3
	v_or_b32_e32 v56, 60, v22
	v_mov_b32_e32 v57, v3
	v_or_b32_e32 v58, 62, v22
	v_mov_b32_e32 v59, v3
	v_lshlrev_b64 v[44:45], 12, v[44:45]
	v_lshlrev_b64 v[46:47], 12, v[46:47]
	v_lshlrev_b64 v[48:49], 12, v[48:49]
	v_lshlrev_b64 v[50:51], 12, v[50:51]
	v_lshlrev_b64 v[52:53], 12, v[52:53]
	v_lshlrev_b64 v[54:55], 12, v[54:55]
	v_lshlrev_b64 v[56:57], 12, v[56:57]
	v_lshlrev_b64 v[58:59], 12, v[58:59]
	v_lshl_add_u64 v[44:45], v[42:43], 0, v[44:45]
	v_lshl_add_u64 v[46:47], v[42:43], 0, v[46:47]
	v_lshl_add_u64 v[48:49], v[42:43], 0, v[48:49]
	v_lshl_add_u64 v[50:51], v[42:43], 0, v[50:51]
	v_lshl_add_u64 v[52:53], v[42:43], 0, v[52:53]
	v_lshl_add_u64 v[54:55], v[42:43], 0, v[54:55]
	v_lshl_add_u64 v[56:57], v[42:43], 0, v[56:57]
	v_lshl_add_u64 v[42:43], v[42:43], 0, v[58:59]
	global_load_dword v44, v[44:45], off nt
	s_nop 0
	global_load_dword v45, v[46:47], off nt
	s_nop 0
	global_load_dword v46, v[48:49], off nt
	global_load_dword v47, v[50:51], off nt
	s_nop 0
	global_load_dword v48, v[52:53], off nt
	global_load_dword v49, v[54:55], off nt
	global_load_dword v50, v[56:57], off nt
	s_nop 0
	global_load_dword v42, v[42:43], off nt
	s_waitcnt vmcnt(30)
	ds_write2_b32 v25, v23, v41 offset1:66
	s_waitcnt vmcnt(28)
	ds_write2_b32 v25, v60, v61 offset0:132 offset1:198
	s_waitcnt vmcnt(26)
	ds_write2_b32 v31, v62, v63 offset0:8 offset1:74
	s_waitcnt vmcnt(24)
	ds_write2_b32 v31, v64, v65 offset0:140 offset1:206
	s_waitcnt vmcnt(22)
	ds_write2_b32 v32, v66, v67 offset0:16 offset1:82
	s_waitcnt vmcnt(20)
	ds_write2_b32 v32, v68, v69 offset0:148 offset1:214
	s_waitcnt vmcnt(18)
	ds_write2_b32 v33, v70, v71 offset0:24 offset1:90
	s_waitcnt vmcnt(16)
	ds_write2_b32 v33, v72, v73 offset0:156 offset1:222
	s_waitcnt vmcnt(14)
	ds_write2_b32 v34, v74, v75 offset0:32 offset1:98
	s_waitcnt vmcnt(12)
	ds_write2_b32 v34, v76, v77 offset0:164 offset1:230
	s_waitcnt vmcnt(10)
	ds_write2_b32 v35, v78, v79 offset0:40 offset1:106
	s_waitcnt vmcnt(8)
	ds_write2_b32 v35, v80, v81 offset0:172 offset1:238
	s_waitcnt vmcnt(6)
	ds_write2_b32 v36, v44, v45 offset0:48 offset1:114
	s_waitcnt vmcnt(4)
	ds_write2_b32 v36, v46, v47 offset0:180 offset1:246
	s_waitcnt vmcnt(2)
	ds_write2_b32 v37, v48, v49 offset0:56 offset1:122
	s_waitcnt vmcnt(0)
	ds_write2_b32 v37, v50, v42 offset0:188 offset1:254
	s_waitcnt lgkmcnt(0)
	ds_read2_b32 v[46:47], v27 offset0:33 offset1:41
	ds_read2_b32 v[48:49], v27 offset1:8
	ds_read2_b32 v[50:51], v27 offset0:66 offset1:74
	ds_read2_b32 v[52:53], v27 offset0:99 offset1:107
	ds_read2_b32 v[54:55], v27 offset0:132 offset1:140
	ds_read2_b32 v[56:57], v27 offset0:165 offset1:173
	ds_read2_b32 v[58:59], v27 offset0:198 offset1:206
	ds_read2_b32 v[60:61], v27 offset0:231 offset1:239
	s_mov_b32 s7, s1
	v_mul_u32_u24_e32 v23, 0xb00, v40
	v_lshl_add_u64 v[62:63], s[6:7], 1, v[16:17]
	v_lshlrev_b32_e32 v64, 1, v23
	v_mov_b32_e32 v65, v3
	s_waitcnt lgkmcnt(6)
	v_cvt_pk_bf16_f32 v42, v48, v46
	s_waitcnt lgkmcnt(4)
	v_cvt_pk_bf16_f32 v43, v50, v52
	s_waitcnt lgkmcnt(2)
	v_cvt_pk_bf16_f32 v44, v54, v56
	s_waitcnt lgkmcnt(0)
	v_cvt_pk_bf16_f32 v45, v58, v60
	v_lshl_add_u64 v[64:65], v[62:63], 0, v[64:65]
	global_store_dwordx4 v[64:65], v[42:45], off sc1
	v_mul_u32_u24_e32 v23, 0xb00, v39
	v_lshlrev_b32_e32 v46, 1, v23
	v_cvt_pk_bf16_f32 v42, v49, v47
	v_cvt_pk_bf16_f32 v43, v51, v53
	v_cvt_pk_bf16_f32 v44, v55, v57
	v_cvt_pk_bf16_f32 v45, v59, v61
	ds_read2_b32 v[48:49], v27 offset0:16 offset1:24
	ds_read2_b32 v[50:51], v27 offset0:49 offset1:57
	ds_read2_b32 v[52:53], v27 offset0:82 offset1:90
	ds_read2_b32 v[54:55], v27 offset0:115 offset1:123
	ds_read2_b32 v[56:57], v27 offset0:148 offset1:156
	ds_read2_b32 v[58:59], v27 offset0:181 offset1:189
	ds_read2_b32 v[60:61], v27 offset0:214 offset1:222
	ds_read2_b32 v[64:65], v27 offset0:247 offset1:255
	v_mov_b32_e32 v47, v3
	v_lshl_add_u64 v[46:47], v[62:63], 0, v[46:47]
	v_mul_u32_u24_e32 v23, 0xb00, v38
	global_store_dwordx4 v[46:47], v[42:45], off sc1
	v_lshlrev_b32_e32 v46, 1, v23
	v_mov_b32_e32 v47, v3
	s_waitcnt lgkmcnt(6)
	v_cvt_pk_bf16_f32 v42, v48, v50
	s_waitcnt lgkmcnt(4)
	v_cvt_pk_bf16_f32 v43, v52, v54
	s_waitcnt lgkmcnt(2)
	v_cvt_pk_bf16_f32 v44, v56, v58
	s_waitcnt lgkmcnt(0)
	v_cvt_pk_bf16_f32 v45, v60, v64
	v_lshl_add_u64 v[46:47], v[62:63], 0, v[46:47]
	v_mul_u32_u24_e32 v23, 0xb00, v21
	global_store_dwordx4 v[46:47], v[42:45], off sc1
	v_lshlrev_b32_e32 v46, 1, v23
	v_mov_b32_e32 v47, v3
	v_cvt_pk_bf16_f32 v42, v49, v51
	v_cvt_pk_bf16_f32 v43, v53, v55
	v_cvt_pk_bf16_f32 v44, v57, v59
	v_cvt_pk_bf16_f32 v45, v61, v65
	v_lshl_add_u64 v[46:47], v[62:63], 0, v[46:47]
	global_store_dwordx4 v[46:47], v[42:45], off sc1
	s_waitcnt lgkmcnt(0)
	s_mov_b64 s[14:15], 0
.LBB0_174:
	s_andn2_b64 vcc, exec, s[14:15]
	s_cbranch_vccnz .LBB0_176
	s_lshl_b32 s0, s8, 2
	v_lshl_add_u64 v[42:43], v[10:11], 0, s[0:1]
	v_lshlrev_b32_e32 v22, 10, v22
	v_mov_b32_e32 v23, v3
	v_lshl_add_u64 v[22:23], v[22:23], 2, v[42:43]
	v_add_co_u32_e32 v42, vcc, 0x2000, v22
	s_mov_b32 s7, s1
	s_nop 0
	v_addc_co_u32_e32 v43, vcc, 0, v23, vcc
	v_add_co_u32_e32 v44, vcc, 0x4000, v22
	v_mul_u32_u24_e32 v40, 0xb00, v40
	s_nop 0
	v_addc_co_u32_e32 v45, vcc, 0, v23, vcc
	v_add_co_u32_e32 v46, vcc, s21, v22
	v_mul_u32_u24_e32 v38, 0xb00, v38
	s_nop 0
	v_addc_co_u32_e32 v47, vcc, 0, v23, vcc
	v_add_co_u32_e32 v48, vcc, 0x8000, v22
	s_nop 1
	v_addc_co_u32_e32 v49, vcc, 0, v23, vcc
	v_add_co_u32_e32 v50, vcc, 0xa000, v22
	s_nop 1
	v_addc_co_u32_e32 v51, vcc, 0, v23, vcc
	v_add_co_u32_e32 v52, vcc, s28, v22
	s_nop 1
	v_addc_co_u32_e32 v53, vcc, 0, v23, vcc
	v_add_co_u32_e32 v54, vcc, 0xe000, v22
	s_nop 1
	v_addc_co_u32_e32 v55, vcc, 0, v23, vcc
	global_load_dword v41, v[22:23], off nt
	global_load_dword v58, v[42:43], off nt
	global_load_dword v59, v[44:45], off nt
	global_load_dword v60, v[46:47], off nt
	global_load_dword v61, v[48:49], off nt
	global_load_dword v62, v[50:51], off nt
	global_load_dword v63, v[52:53], off nt
	global_load_dword v64, v[54:55], off nt
	v_add_co_u32_e32 v42, vcc, 0x10000, v22
	s_nop 1
	v_addc_co_u32_e32 v43, vcc, 0, v23, vcc
	v_add_co_u32_e32 v44, vcc, s29, v22
	s_nop 1
	v_addc_co_u32_e32 v45, vcc, 0, v23, vcc
	v_add_co_u32_e32 v46, vcc, 0x14000, v22
	s_nop 1
	v_addc_co_u32_e32 v47, vcc, 0, v23, vcc
	v_add_co_u32_e32 v48, vcc, 0x16000, v22
	s_nop 1
	v_addc_co_u32_e32 v49, vcc, 0, v23, vcc
	v_add_co_u32_e32 v50, vcc, s30, v22
	s_nop 1
	v_addc_co_u32_e32 v51, vcc, 0, v23, vcc
	v_add_co_u32_e32 v52, vcc, 0x1a000, v22
	s_nop 1
	v_addc_co_u32_e32 v53, vcc, 0, v23, vcc
	v_add_co_u32_e32 v54, vcc, 0x1c000, v22
	s_nop 1
	v_addc_co_u32_e32 v55, vcc, 0, v23, vcc
	v_add_co_u32_e32 v56, vcc, s31, v22
	s_nop 1
	v_addc_co_u32_e32 v57, vcc, 0, v23, vcc
	global_load_dword v65, v[42:43], off nt
	global_load_dword v66, v[44:45], off nt
	global_load_dword v67, v[46:47], off nt
	global_load_dword v68, v[48:49], off nt
	global_load_dword v69, v[50:51], off nt
	global_load_dword v70, v[52:53], off nt
	global_load_dword v71, v[54:55], off nt
	global_load_dword v72, v[56:57], off nt
	v_add_co_u32_e32 v42, vcc, 0x20000, v22
	s_nop 1
	v_addc_co_u32_e32 v43, vcc, 0, v23, vcc
	v_add_co_u32_e32 v44, vcc, 0x22000, v22
	s_nop 1
	v_addc_co_u32_e32 v45, vcc, 0, v23, vcc
	v_add_co_u32_e32 v46, vcc, s63, v22
	s_nop 1
	v_addc_co_u32_e32 v47, vcc, 0, v23, vcc
	v_add_co_u32_e32 v48, vcc, 0x26000, v22
	s_nop 1
	v_addc_co_u32_e32 v49, vcc, 0, v23, vcc
	v_add_co_u32_e32 v50, vcc, 0x28000, v22
	s_nop 1
	v_addc_co_u32_e32 v51, vcc, 0, v23, vcc
	v_add_co_u32_e32 v52, vcc, s64, v22
	s_nop 1
	v_addc_co_u32_e32 v53, vcc, 0, v23, vcc
	v_add_co_u32_e32 v54, vcc, 0x2c000, v22
	s_nop 1
	v_addc_co_u32_e32 v55, vcc, 0, v23, vcc
	v_add_co_u32_e32 v56, vcc, 0x2e000, v22
	s_nop 1
	v_addc_co_u32_e32 v57, vcc, 0, v23, vcc
	global_load_dword v73, v[42:43], off nt
	global_load_dword v74, v[44:45], off nt
	global_load_dword v75, v[46:47], off nt
	global_load_dword v76, v[48:49], off nt
	global_load_dword v77, v[50:51], off nt
	global_load_dword v78, v[52:53], off nt
	global_load_dword v79, v[54:55], off nt
	s_nop 0
	global_load_dword v56, v[56:57], off nt
	v_add_co_u32_e32 v42, vcc, s65, v22
	s_nop 1
	v_addc_co_u32_e32 v43, vcc, 0, v23, vcc
	v_add_co_u32_e32 v44, vcc, 0x32000, v22
	s_nop 1
	v_addc_co_u32_e32 v45, vcc, 0, v23, vcc
	v_add_co_u32_e32 v46, vcc, 0x34000, v22
	s_nop 1
	v_addc_co_u32_e32 v47, vcc, 0, v23, vcc
	v_add_co_u32_e32 v48, vcc, s66, v22
	s_nop 1
	v_addc_co_u32_e32 v49, vcc, 0, v23, vcc
	v_add_co_u32_e32 v50, vcc, 0x38000, v22
	s_nop 1
	v_addc_co_u32_e32 v51, vcc, 0, v23, vcc
	v_add_co_u32_e32 v52, vcc, 0x3a000, v22
	s_nop 1
	v_addc_co_u32_e32 v53, vcc, 0, v23, vcc
	v_add_co_u32_e32 v54, vcc, s67, v22
	s_nop 1
	v_addc_co_u32_e32 v55, vcc, 0, v23, vcc
	v_add_co_u32_e32 v22, vcc, 0x3e000, v22
	s_nop 1
	v_addc_co_u32_e32 v23, vcc, 0, v23, vcc
	global_load_dword v42, v[42:43], off nt
	s_nop 0
	global_load_dword v43, v[44:45], off nt
	s_nop 0
	global_load_dword v44, v[46:47], off nt
	global_load_dword v45, v[48:49], off nt
	s_nop 0
	global_load_dword v46, v[50:51], off nt
	global_load_dword v47, v[52:53], off nt
	global_load_dword v48, v[54:55], off nt
	s_nop 0
	global_load_dword v22, v[22:23], off nt
	s_waitcnt vmcnt(30)
	ds_write2_b32 v25, v41, v58 offset1:66
	s_waitcnt vmcnt(28)
	ds_write2_b32 v25, v59, v60 offset0:132 offset1:198
	s_waitcnt vmcnt(26)
	ds_write2_b32 v31, v61, v62 offset0:8 offset1:74
	s_waitcnt vmcnt(24)
	ds_write2_b32 v31, v63, v64 offset0:140 offset1:206
	s_waitcnt vmcnt(22)
	ds_write2_b32 v32, v65, v66 offset0:16 offset1:82
	s_waitcnt vmcnt(20)
	ds_write2_b32 v32, v67, v68 offset0:148 offset1:214
	s_waitcnt vmcnt(18)
	ds_write2_b32 v33, v69, v70 offset0:24 offset1:90
	s_waitcnt vmcnt(16)
	ds_write2_b32 v33, v71, v72 offset0:156 offset1:222
	s_waitcnt vmcnt(14)
	ds_write2_b32 v34, v73, v74 offset0:32 offset1:98
	s_waitcnt vmcnt(12)
	ds_write2_b32 v34, v75, v76 offset0:164 offset1:230
	s_waitcnt vmcnt(10)
	ds_write2_b32 v35, v77, v78 offset0:40 offset1:106
	s_waitcnt vmcnt(8)
	ds_write2_b32 v35, v79, v56 offset0:172 offset1:238
	s_waitcnt vmcnt(6)
	ds_write2_b32 v36, v42, v43 offset0:48 offset1:114
	s_waitcnt vmcnt(4)
	ds_write2_b32 v36, v44, v45 offset0:180 offset1:246
	s_waitcnt vmcnt(2)
	ds_write2_b32 v37, v46, v47 offset0:56 offset1:122
	s_waitcnt vmcnt(0)
	ds_write2_b32 v37, v48, v22 offset0:188 offset1:254
	s_waitcnt lgkmcnt(0)
	ds_read2_b32 v[42:43], v27 offset0:33 offset1:41
	ds_read2_b32 v[44:45], v27 offset0:66 offset1:74
	ds_read2_b32 v[46:47], v27 offset0:99 offset1:107
	ds_read2_b32 v[48:49], v27 offset1:8
	ds_read2_b32 v[50:51], v27 offset0:132 offset1:140
	ds_read2_b32 v[52:53], v27 offset0:165 offset1:173
	ds_read2_b32 v[54:55], v27 offset0:198 offset1:206
	ds_read2_b32 v[56:57], v27 offset0:231 offset1:239
	s_waitcnt lgkmcnt(4)
	v_mul_f32_e32 v41, 0x42800000, v48
	v_mul_f32_e32 v42, 0x42800000, v42
	v_mov_b32_e32 v58, v3
	v_cvt_pk_fp8_f32 v58, v41, v42
	v_mul_f32_e32 v41, 0x42800000, v44
	v_mul_f32_e32 v42, 0x42800000, v46
	s_waitcnt lgkmcnt(3)
	v_mul_f32_e32 v44, 0x42800000, v50
	s_waitcnt lgkmcnt(2)
	v_mul_f32_e32 v46, 0x42800000, v52
	v_mov_b32_e32 v59, v3
	v_cvt_pk_fp8_f32 v59, v44, v46
	v_cvt_pk_fp8_f32 v58, v41, v42 op_sel:[0,0,1]
	s_waitcnt lgkmcnt(1)
	v_mul_f32_e32 v41, 0x42800000, v54
	s_waitcnt lgkmcnt(0)
	v_mul_f32_e32 v42, 0x42800000, v56
	v_cvt_pk_fp8_f32 v59, v41, v42 op_sel:[0,0,1]
	v_lshl_add_u64 v[22:23], v[18:19], 0, s[6:7]
	v_mov_b32_e32 v41, v3
	v_lshl_add_u64 v[40:41], v[22:23], 0, v[40:41]
	global_store_dwordx2 v[40:41], v[58:59], off sc1
	v_mul_f32_e32 v41, 0x42800000, v49
	v_mul_f32_e32 v42, 0x42800000, v43
	v_mov_b32_e32 v40, v3
	v_cvt_pk_fp8_f32 v40, v41, v42
	v_mul_f32_e32 v42, 0x42800000, v45
	v_mul_f32_e32 v44, 0x42800000, v51
	v_mul_f32_e32 v45, 0x42800000, v53
	v_mov_b32_e32 v41, v3
	v_cvt_pk_fp8_f32 v41, v44, v45
	v_mul_f32_e32 v43, 0x42800000, v47
	v_cvt_pk_fp8_f32 v40, v42, v43 op_sel:[0,0,1]
	v_mul_f32_e32 v42, 0x42800000, v55
	v_mul_f32_e32 v43, 0x42800000, v57
	v_cvt_pk_fp8_f32 v41, v42, v43 op_sel:[0,0,1]
	v_mul_u32_u24_e32 v42, 0xb00, v39
	v_mov_b32_e32 v43, v3
	v_lshl_add_u64 v[42:43], v[22:23], 0, v[42:43]
	global_store_dwordx2 v[42:43], v[40:41], off sc1
	ds_read2_b32 v[40:41], v27 offset0:16 offset1:24
	ds_read2_b32 v[42:43], v27 offset0:49 offset1:57
	ds_read2_b32 v[44:45], v27 offset0:82 offset1:90
	ds_read2_b32 v[46:47], v27 offset0:115 offset1:123
	ds_read2_b32 v[48:49], v27 offset0:148 offset1:156
	ds_read2_b32 v[50:51], v27 offset0:181 offset1:189
	ds_read2_b32 v[52:53], v27 offset0:214 offset1:222
	ds_read2_b32 v[54:55], v27 offset0:247 offset1:255
	s_waitcnt lgkmcnt(7)
	v_mul_f32_e32 v39, 0x42800000, v40
	s_waitcnt lgkmcnt(6)
	v_mul_f32_e32 v40, 0x42800000, v42
	v_mov_b32_e32 v56, v3
	v_cvt_pk_fp8_f32 v56, v39, v40
	s_waitcnt lgkmcnt(5)
	v_mul_f32_e32 v39, 0x42800000, v44
	s_waitcnt lgkmcnt(3)
	v_mul_f32_e32 v42, 0x42800000, v48
	s_waitcnt lgkmcnt(2)
	v_mul_f32_e32 v44, 0x42800000, v50
	v_mov_b32_e32 v57, v3
	v_cvt_pk_fp8_f32 v57, v42, v44
	v_mul_f32_e32 v40, 0x42800000, v46
	v_cvt_pk_fp8_f32 v56, v39, v40 op_sel:[0,0,1]
	s_waitcnt lgkmcnt(1)
	v_mul_f32_e32 v39, 0x42800000, v52
	s_waitcnt lgkmcnt(0)
	v_mul_f32_e32 v40, 0x42800000, v54
	v_cvt_pk_fp8_f32 v57, v39, v40 op_sel:[0,0,1]
	v_mov_b32_e32 v39, v3
	v_lshl_add_u64 v[38:39], v[22:23], 0, v[38:39]
	v_mul_f32_e32 v40, 0x42800000, v43
	global_store_dwordx2 v[38:39], v[56:57], off sc1
	v_mul_f32_e32 v39, 0x42800000, v41
	v_mov_b32_e32 v38, v3
	v_cvt_pk_fp8_f32 v38, v39, v40
	v_mul_f32_e32 v42, 0x42800000, v49
	v_mul_f32_e32 v43, 0x42800000, v51
	v_mov_b32_e32 v39, v3
	v_cvt_pk_fp8_f32 v39, v42, v43
	v_mul_f32_e32 v40, 0x42800000, v45
	v_mul_f32_e32 v41, 0x42800000, v47
	v_cvt_pk_fp8_f32 v38, v40, v41 op_sel:[0,0,1]
	v_mul_f32_e32 v40, 0x42800000, v53
	v_mul_f32_e32 v41, 0x42800000, v55
	v_cvt_pk_fp8_f32 v39, v40, v41 op_sel:[0,0,1]
	v_mul_u32_u24_e32 v40, 0xb00, v21
	v_mov_b32_e32 v41, v3
	v_lshl_add_u64 v[22:23], v[22:23], 0, v[40:41]
	global_store_dwordx2 v[22:23], v[38:39], off sc1
	s_waitcnt lgkmcnt(0)

.LBB0_629:
	v_readlane_b32 s64, v254, 2
	s_and_b64 s[2:3], s[2:3], exec
	v_readlane_b32 s74, v254, 12
	v_readlane_b32 s75, v254, 13
	s_cselect_b32 s2, s29, 0x300000
	s_mov_b64 s[22:23], s[74:75]
	s_cselect_b32 s3, s51, s23
	s_cselect_b32 s6, s50, s22
	s_add_u32 s7, s58, s2
	s_addc_u32 s8, s59, 0
	s_lshl_b32 s2, s5, 6
	s_ashr_i32 s5, s4, 31
	s_lshl_b64 s[4:5], s[4:5], 2
	s_add_u32 s4, s6, s4
	s_addc_u32 s5, s3, s5
	v_or_b32_e32 v21, s2, v24
	v_lshl_add_u64 v[22:23], s[4:5], 0, v[2:3]
	v_mad_i64_i32 v[38:39], s[4:5], v21, s30, v[22:23]
	v_or_b32_e32 v40, 2, v21
	v_or_b32_e32 v42, 4, v21
	v_or_b32_e32 v44, 6, v21
	v_or_b32_e32 v46, 8, v21
	v_or_b32_e32 v48, 10, v21
	v_or_b32_e32 v50, 12, v21
	v_or_b32_e32 v52, 14, v21
	v_mad_i64_i32 v[40:41], s[4:5], v40, s30, v[22:23]
	v_mad_i64_i32 v[42:43], s[4:5], v42, s30, v[22:23]
	v_mad_i64_i32 v[44:45], s[4:5], v44, s30, v[22:23]
	v_mad_i64_i32 v[46:47], s[4:5], v46, s30, v[22:23]
	v_mad_i64_i32 v[48:49], s[4:5], v48, s30, v[22:23]
	v_mad_i64_i32 v[50:51], s[4:5], v50, s30, v[22:23]
	v_mad_i64_i32 v[52:53], s[4:5], v52, s30, v[22:23]
	global_load_dword v54, v[38:39], off nt
	global_load_dword v55, v[40:41], off nt
	global_load_dword v56, v[42:43], off nt
	global_load_dword v57, v[44:45], off nt
	global_load_dword v58, v[46:47], off nt
	global_load_dword v59, v[48:49], off nt
	global_load_dword v60, v[50:51], off nt
	global_load_dword v61, v[52:53], off nt
	v_or_b32_e32 v38, 16, v21
	v_mad_i64_i32 v[38:39], s[4:5], v38, s30, v[22:23]
	v_or_b32_e32 v40, 18, v21
	v_or_b32_e32 v42, 20, v21
	v_or_b32_e32 v44, 22, v21
	v_or_b32_e32 v46, 24, v21
	v_or_b32_e32 v48, 26, v21
	v_or_b32_e32 v50, 28, v21
	v_or_b32_e32 v52, 30, v21
	v_mad_i64_i32 v[40:41], s[4:5], v40, s30, v[22:23]
	v_mad_i64_i32 v[42:43], s[4:5], v42, s30, v[22:23]
	v_mad_i64_i32 v[44:45], s[4:5], v44, s30, v[22:23]
	v_mad_i64_i32 v[46:47], s[4:5], v46, s30, v[22:23]
	v_mad_i64_i32 v[48:49], s[4:5], v48, s30, v[22:23]
	v_mad_i64_i32 v[50:51], s[4:5], v50, s30, v[22:23]
	v_mad_i64_i32 v[52:53], s[4:5], v52, s30, v[22:23]
	global_load_dword v62, v[38:39], off nt
	global_load_dword v63, v[40:41], off nt
	global_load_dword v64, v[42:43], off nt
	global_load_dword v65, v[44:45], off nt
	global_load_dword v66, v[46:47], off nt
	global_load_dword v67, v[48:49], off nt
	global_load_dword v68, v[50:51], off nt
	global_load_dword v69, v[52:53], off nt
	v_or_b32_e32 v38, 32, v21
	v_mad_i64_i32 v[38:39], s[4:5], v38, s30, v[22:23]
	v_or_b32_e32 v40, 34, v21
	v_or_b32_e32 v42, 36, v21
	v_or_b32_e32 v44, 38, v21
	v_or_b32_e32 v46, 40, v21
	v_or_b32_e32 v48, 42, v21
	v_or_b32_e32 v50, 44, v21
	v_or_b32_e32 v52, 46, v21
	v_mad_i64_i32 v[40:41], s[4:5], v40, s30, v[22:23]
	v_mad_i64_i32 v[42:43], s[4:5], v42, s30, v[22:23]
	v_mad_i64_i32 v[44:45], s[4:5], v44, s30, v[22:23]
	v_mad_i64_i32 v[46:47], s[4:5], v46, s30, v[22:23]
	v_mad_i64_i32 v[48:49], s[4:5], v48, s30, v[22:23]
	v_mad_i64_i32 v[50:51], s[4:5], v50, s30, v[22:23]
	v_mad_i64_i32 v[52:53], s[4:5], v52, s30, v[22:23]
	global_load_dword v70, v[38:39], off nt
	global_load_dword v71, v[40:41], off nt
	global_load_dword v72, v[42:43], off nt
	global_load_dword v73, v[44:45], off nt
	global_load_dword v74, v[46:47], off nt
	global_load_dword v75, v[48:49], off nt
	global_load_dword v76, v[50:51], off nt
	global_load_dword v77, v[52:53], off nt
	v_or_b32_e32 v38, 48, v21
	v_mad_i64_i32 v[38:39], s[4:5], v38, s30, v[22:23]
	v_or_b32_e32 v40, 50, v21
	v_or_b32_e32 v42, 52, v21
	v_or_b32_e32 v44, 54, v21
	v_or_b32_e32 v46, 56, v21
	v_or_b32_e32 v48, 58, v21
	v_or_b32_e32 v50, 60, v21
	v_or_b32_e32 v21, 62, v21
	v_mad_i64_i32 v[40:41], s[4:5], v40, s30, v[22:23]
	v_mad_i64_i32 v[42:43], s[4:5], v42, s30, v[22:23]
	v_mad_i64_i32 v[44:45], s[4:5], v44, s30, v[22:23]
	v_mad_i64_i32 v[46:47], s[4:5], v46, s30, v[22:23]
	v_mad_i64_i32 v[48:49], s[4:5], v48, s30, v[22:23]
	v_mad_i64_i32 v[50:51], s[4:5], v50, s30, v[22:23]
	v_mad_i64_i32 v[22:23], s[4:5], v21, s30, v[22:23]
	global_load_dword v21, v[38:39], off nt
	global_load_dword v52, v[40:41], off nt
	global_load_dword v53, v[42:43], off nt
	global_load_dword v78, v[44:45], off nt
	global_load_dword v79, v[46:47], off nt
	global_load_dword v80, v[48:49], off nt
	global_load_dword v81, v[50:51], off nt
	global_load_dword v82, v[22:23], off nt
	s_waitcnt vmcnt(30)
	ds_write2_b32 v25, v54, v55 offset1:66
	s_waitcnt vmcnt(28)
	ds_write2_b32 v25, v56, v57 offset0:132 offset1:198
	s_waitcnt vmcnt(26)
	ds_write2_b32 v31, v58, v59 offset0:8 offset1:74
	s_waitcnt vmcnt(24)
	ds_write2_b32 v31, v60, v61 offset0:140 offset1:206
	s_waitcnt vmcnt(22)
	ds_write2_b32 v32, v62, v63 offset0:16 offset1:82
	s_waitcnt vmcnt(20)
	ds_write2_b32 v32, v64, v65 offset0:148 offset1:214
	s_waitcnt vmcnt(18)
	ds_write2_b32 v33, v66, v67 offset0:24 offset1:90
	s_waitcnt vmcnt(16)
	ds_write2_b32 v33, v68, v69 offset0:156 offset1:222
	s_waitcnt vmcnt(14)
	ds_write2_b32 v34, v70, v71 offset0:32 offset1:98
	s_waitcnt vmcnt(12)
	ds_write2_b32 v34, v72, v73 offset0:164 offset1:230
	s_waitcnt vmcnt(10)
	ds_write2_b32 v35, v74, v75 offset0:40 offset1:106
	s_waitcnt vmcnt(8)
	ds_write2_b32 v35, v76, v77 offset0:172 offset1:238
	s_waitcnt vmcnt(6)
	ds_write2_b32 v36, v21, v52 offset0:48 offset1:114
	s_waitcnt vmcnt(4)
	ds_write2_b32 v36, v53, v78 offset0:180 offset1:246
	s_waitcnt vmcnt(2)
	ds_write2_b32 v37, v79, v80 offset0:56 offset1:122
	s_waitcnt vmcnt(0)
	ds_write2_b32 v37, v81, v82 offset0:188 offset1:254
	s_waitcnt lgkmcnt(0)
	s_ashr_i32 s3, s2, 31
	ds_read2_b32 v[22:23], v27 offset0:33 offset1:41
	ds_read2_b32 v[42:43], v27 offset1:8
	ds_read2_b32 v[44:45], v27 offset0:66 offset1:74
	ds_read2_b32 v[46:47], v27 offset0:99 offset1:107
	ds_read2_b32 v[48:49], v27 offset0:132 offset1:140
	ds_read2_b32 v[50:51], v27 offset0:165 offset1:173
	ds_read2_b32 v[52:53], v27 offset0:198 offset1:206
	ds_read2_b32 v[54:55], v27 offset0:231 offset1:239
	s_lshl_b64 s[2:3], s[2:3], 1
	s_add_u32 s2, s7, s2
	v_add_u32_e32 v58, s0, v26
	s_addc_u32 s3, s8, s3
	v_mov_b32_e32 v21, v3
	v_ashrrev_i32_e32 v59, 31, v58
	v_lshl_add_u64 v[56:57], s[2:3], 0, v[20:21]
	v_lshlrev_b64 v[58:59], 11, v[58:59]
	s_waitcnt lgkmcnt(6)
	v_cvt_pk_bf16_f32 v38, v42, v22
	s_waitcnt lgkmcnt(4)
	v_cvt_pk_bf16_f32 v39, v44, v46
	s_waitcnt lgkmcnt(2)
	v_cvt_pk_bf16_f32 v40, v48, v50
	s_waitcnt lgkmcnt(0)
	v_cvt_pk_bf16_f32 v41, v52, v54
	v_lshl_add_u64 v[58:59], v[56:57], 0, v[58:59]
	v_add_u32_e32 v22, s0, v28
	global_store_dwordx4 v[58:59], v[38:41], off sc1
	v_readlane_b32 s65, v254, 3
	v_readlane_b32 s66, v254, 4
	v_cvt_pk_bf16_f32 v38, v43, v23
	v_ashrrev_i32_e32 v23, 31, v22
	v_cvt_pk_bf16_f32 v39, v45, v47
	v_cvt_pk_bf16_f32 v40, v49, v51
	v_cvt_pk_bf16_f32 v41, v53, v55
	v_lshlrev_b64 v[22:23], 11, v[22:23]
	ds_read2_b32 v[42:43], v27 offset0:49 offset1:57
	ds_read2_b32 v[44:45], v27 offset0:16 offset1:24
	ds_read2_b32 v[46:47], v27 offset0:82 offset1:90
	ds_read2_b32 v[48:49], v27 offset0:115 offset1:123
	ds_read2_b32 v[50:51], v27 offset0:148 offset1:156
	ds_read2_b32 v[52:53], v27 offset0:181 offset1:189
	ds_read2_b32 v[54:55], v27 offset0:214 offset1:222
	ds_read2_b32 v[58:59], v27 offset0:247 offset1:255
	v_lshl_add_u64 v[22:23], v[56:57], 0, v[22:23]
	global_store_dwordx4 v[22:23], v[38:41], off sc1
	v_add_u32_e32 v22, s0, v29
	v_ashrrev_i32_e32 v23, 31, v22
	v_lshlrev_b64 v[22:23], 11, v[22:23]
	s_waitcnt lgkmcnt(6)
	v_cvt_pk_bf16_f32 v38, v44, v42
	s_waitcnt lgkmcnt(4)
	v_cvt_pk_bf16_f32 v39, v46, v48
	s_waitcnt lgkmcnt(2)
	v_cvt_pk_bf16_f32 v40, v50, v52
	s_waitcnt lgkmcnt(0)
	v_cvt_pk_bf16_f32 v41, v54, v58
	v_lshl_add_u64 v[22:23], v[56:57], 0, v[22:23]
	global_store_dwordx4 v[22:23], v[38:41], off sc1
	v_add_u32_e32 v22, s0, v30
	v_ashrrev_i32_e32 v23, 31, v22
	v_lshlrev_b64 v[22:23], 11, v[22:23]
	v_cvt_pk_bf16_f32 v38, v45, v43
	v_cvt_pk_bf16_f32 v39, v47, v49
	v_cvt_pk_bf16_f32 v40, v51, v53
	v_cvt_pk_bf16_f32 v41, v55, v59
	v_lshl_add_u64 v[22:23], v[56:57], 0, v[22:23]
	global_store_dwordx4 v[22:23], v[38:41], off sc1
	s_waitcnt lgkmcnt(0)
	v_readlane_b32 s67, v254, 5
	v_readlane_b32 s68, v254, 6
	v_readlane_b32 s69, v254, 7
	v_readlane_b32 s70, v254, 8
	v_readlane_b32 s71, v254, 9
	v_readlane_b32 s72, v254, 10
	v_readlane_b32 s73, v254, 11
	v_readlane_b32 s76, v254, 14
	v_readlane_b32 s77, v254, 15
	v_readlane_b32 s78, v254, 16
	v_readlane_b32 s79, v254, 17

.LBB0_633:
	s_cmpk_gt_u32 s31, 0x107f
	s_cbranch_scc0 .LBB0_641
	s_cmpk_gt_u32 s31, 0x167f
	s_cbranch_scc0 .LBB0_636
	s_lshl_b32 s0, s31, 1
	s_and_b32 s0, s0, 0x7fffffc0
	s_add_i32 s6, s0, 0xffffd300
	s_and_b32 s8, s15, 0x3e0
	v_or_b32_e32 v22, s6, v24
	s_lshl_b32 s0, s8, 2
	v_mov_b32_e32 v23, v3
	v_lshl_add_u64 v[38:39], v[4:5], 0, s[0:1]
	v_lshlrev_b64 v[40:41], 12, v[22:23]
	v_or_b32_e32 v42, 2, v22
	v_mov_b32_e32 v43, v3
	v_or_b32_e32 v44, 4, v22
	v_mov_b32_e32 v45, v3
	v_or_b32_e32 v46, 6, v22
	v_mov_b32_e32 v47, v3
	v_or_b32_e32 v48, 8, v22
	v_mov_b32_e32 v49, v3
	v_or_b32_e32 v50, 10, v22
	v_mov_b32_e32 v51, v3
	v_or_b32_e32 v52, 12, v22
	v_mov_b32_e32 v53, v3
	v_or_b32_e32 v54, 14, v22
	v_mov_b32_e32 v55, v3
	v_lshl_add_u64 v[40:41], v[38:39], 0, v[40:41]
	v_lshlrev_b64 v[42:43], 12, v[42:43]
	v_lshlrev_b64 v[44:45], 12, v[44:45]
	v_lshlrev_b64 v[46:47], 12, v[46:47]
	v_lshlrev_b64 v[48:49], 12, v[48:49]
	v_lshlrev_b64 v[50:51], 12, v[50:51]
	v_lshlrev_b64 v[52:53], 12, v[52:53]
	v_lshlrev_b64 v[54:55], 12, v[54:55]
	v_lshl_add_u64 v[42:43], v[38:39], 0, v[42:43]
	v_lshl_add_u64 v[44:45], v[38:39], 0, v[44:45]
	v_lshl_add_u64 v[46:47], v[38:39], 0, v[46:47]
	v_lshl_add_u64 v[48:49], v[38:39], 0, v[48:49]
	v_lshl_add_u64 v[50:51], v[38:39], 0, v[50:51]
	v_lshl_add_u64 v[52:53], v[38:39], 0, v[52:53]
	v_lshl_add_u64 v[54:55], v[38:39], 0, v[54:55]
	global_load_dword v21, v[40:41], off nt
	global_load_dword v56, v[42:43], off nt
	global_load_dword v57, v[44:45], off nt
	global_load_dword v58, v[46:47], off nt
	global_load_dword v59, v[48:49], off nt
	global_load_dword v60, v[50:51], off nt
	global_load_dword v61, v[52:53], off nt
	global_load_dword v62, v[54:55], off nt
	v_or_b32_e32 v40, 16, v22
	v_mov_b32_e32 v41, v3
	v_lshlrev_b64 v[40:41], 12, v[40:41]
	v_or_b32_e32 v42, 18, v22
	v_mov_b32_e32 v43, v3
	v_or_b32_e32 v44, 20, v22
	v_mov_b32_e32 v45, v3
	v_or_b32_e32 v46, 22, v22
	v_mov_b32_e32 v47, v3
	v_or_b32_e32 v48, 24, v22
	v_mov_b32_e32 v49, v3
	v_or_b32_e32 v50, 26, v22
	v_mov_b32_e32 v51, v3
	v_or_b32_e32 v52, 28, v22
	v_mov_b32_e32 v53, v3
	v_or_b32_e32 v54, 30, v22
	v_mov_b32_e32 v55, v3
	v_lshl_add_u64 v[40:41], v[38:39], 0, v[40:41]
	v_lshlrev_b64 v[42:43], 12, v[42:43]
	v_lshlrev_b64 v[44:45], 12, v[44:45]
	v_lshlrev_b64 v[46:47], 12, v[46:47]
	v_lshlrev_b64 v[48:49], 12, v[48:49]
	v_lshlrev_b64 v[50:51], 12, v[50:51]
	v_lshlrev_b64 v[52:53], 12, v[52:53]
	v_lshlrev_b64 v[54:55], 12, v[54:55]
	v_lshl_add_u64 v[42:43], v[38:39], 0, v[42:43]
	v_lshl_add_u64 v[44:45], v[38:39], 0, v[44:45]
	v_lshl_add_u64 v[46:47], v[38:39], 0, v[46:47]
	v_lshl_add_u64 v[48:49], v[38:39], 0, v[48:49]
	v_lshl_add_u64 v[50:51], v[38:39], 0, v[50:51]
	v_lshl_add_u64 v[52:53], v[38:39], 0, v[52:53]
	v_lshl_add_u64 v[54:55], v[38:39], 0, v[54:55]
	global_load_dword v63, v[40:41], off nt
	global_load_dword v64, v[42:43], off nt
	global_load_dword v65, v[44:45], off nt
	global_load_dword v66, v[46:47], off nt
	global_load_dword v67, v[48:49], off nt
	global_load_dword v68, v[50:51], off nt
	global_load_dword v69, v[52:53], off nt
	global_load_dword v70, v[54:55], off nt
	v_or_b32_e32 v40, 32, v22
	v_mov_b32_e32 v41, v3
	v_lshlrev_b64 v[40:41], 12, v[40:41]
	v_or_b32_e32 v42, 34, v22
	v_mov_b32_e32 v43, v3
	v_or_b32_e32 v44, 36, v22
	v_mov_b32_e32 v45, v3
	v_or_b32_e32 v46, 38, v22
	v_mov_b32_e32 v47, v3
	v_or_b32_e32 v48, 40, v22
	v_mov_b32_e32 v49, v3
	v_or_b32_e32 v50, 42, v22
	v_mov_b32_e32 v51, v3
	v_or_b32_e32 v52, 44, v22
	v_mov_b32_e32 v53, v3
	v_or_b32_e32 v54, 46, v22
	v_mov_b32_e32 v55, v3
	v_lshl_add_u64 v[40:41], v[38:39], 0, v[40:41]
	v_lshlrev_b64 v[42:43], 12, v[42:43]
	v_lshlrev_b64 v[44:45], 12, v[44:45]
	v_lshlrev_b64 v[46:47], 12, v[46:47]
	v_lshlrev_b64 v[48:49], 12, v[48:49]
	v_lshlrev_b64 v[50:51], 12, v[50:51]
	v_lshlrev_b64 v[52:53], 12, v[52:53]
	v_lshlrev_b64 v[54:55], 12, v[54:55]
	v_lshl_add_u64 v[42:43], v[38:39], 0, v[42:43]
	v_lshl_add_u64 v[44:45], v[38:39], 0, v[44:45]
	v_lshl_add_u64 v[46:47], v[38:39], 0, v[46:47]
	v_lshl_add_u64 v[48:49], v[38:39], 0, v[48:49]
	v_lshl_add_u64 v[50:51], v[38:39], 0, v[50:51]
	v_lshl_add_u64 v[52:53], v[38:39], 0, v[52:53]
	v_lshl_add_u64 v[54:55], v[38:39], 0, v[54:55]
	global_load_dword v71, v[40:41], off nt
	global_load_dword v72, v[42:43], off nt
	global_load_dword v73, v[44:45], off nt
	global_load_dword v74, v[46:47], off nt
	global_load_dword v75, v[48:49], off nt
	global_load_dword v76, v[50:51], off nt
	global_load_dword v77, v[52:53], off nt
	global_load_dword v78, v[54:55], off nt
	v_or_b32_e32 v40, 48, v22
	v_mov_b32_e32 v41, v3
	v_lshlrev_b64 v[40:41], 12, v[40:41]
	v_or_b32_e32 v42, 50, v22
	v_mov_b32_e32 v43, v3
	v_or_b32_e32 v44, 52, v22
	v_mov_b32_e32 v45, v3
	v_or_b32_e32 v46, 54, v22
	v_mov_b32_e32 v47, v3
	v_or_b32_e32 v48, 56, v22
	v_mov_b32_e32 v49, v3
	v_or_b32_e32 v50, 58, v22
	v_mov_b32_e32 v51, v3
	v_or_b32_e32 v52, 60, v22
	v_mov_b32_e32 v53, v3
	v_or_b32_e32 v22, 62, v22
	v_lshl_add_u64 v[40:41], v[38:39], 0, v[40:41]
	v_lshlrev_b64 v[42:43], 12, v[42:43]
	v_lshlrev_b64 v[44:45], 12, v[44:45]
	v_lshlrev_b64 v[46:47], 12, v[46:47]
	v_lshlrev_b64 v[48:49], 12, v[48:49]
	v_lshlrev_b64 v[50:51], 12, v[50:51]
	v_lshlrev_b64 v[52:53], 12, v[52:53]
	v_lshlrev_b64 v[22:23], 12, v[22:23]
	v_lshl_add_u64 v[42:43], v[38:39], 0, v[42:43]
	v_lshl_add_u64 v[44:45], v[38:39], 0, v[44:45]
	v_lshl_add_u64 v[46:47], v[38:39], 0, v[46:47]
	v_lshl_add_u64 v[48:49], v[38:39], 0, v[48:49]
	v_lshl_add_u64 v[50:51], v[38:39], 0, v[50:51]
	v_lshl_add_u64 v[52:53], v[38:39], 0, v[52:53]
	v_lshl_add_u64 v[22:23], v[38:39], 0, v[22:23]
	global_load_dword v38, v[40:41], off nt
	global_load_dword v39, v[42:43], off nt
	global_load_dword v54, v[44:45], off nt
	global_load_dword v55, v[46:47], off nt
	global_load_dword v79, v[48:49], off nt
	global_load_dword v80, v[50:51], off nt
	global_load_dword v81, v[52:53], off nt
	global_load_dword v82, v[22:23], off nt
	s_waitcnt vmcnt(30)
	ds_write2_b32 v25, v21, v56 offset1:66
	s_waitcnt vmcnt(28)
	ds_write2_b32 v25, v57, v58 offset0:132 offset1:198
	s_waitcnt vmcnt(26)
	ds_write2_b32 v31, v59, v60 offset0:8 offset1:74
	s_waitcnt vmcnt(24)
	ds_write2_b32 v31, v61, v62 offset0:140 offset1:206
	s_waitcnt vmcnt(22)
	ds_write2_b32 v32, v63, v64 offset0:16 offset1:82
	s_waitcnt vmcnt(20)
	ds_write2_b32 v32, v65, v66 offset0:148 offset1:214
	s_waitcnt vmcnt(18)
	ds_write2_b32 v33, v67, v68 offset0:24 offset1:90
	s_waitcnt vmcnt(16)
	ds_write2_b32 v33, v69, v70 offset0:156 offset1:222
	s_waitcnt vmcnt(14)
	ds_write2_b32 v34, v71, v72 offset0:32 offset1:98
	s_waitcnt vmcnt(12)
	ds_write2_b32 v34, v73, v74 offset0:164 offset1:230
	s_waitcnt vmcnt(10)
	ds_write2_b32 v35, v75, v76 offset0:40 offset1:106
	s_waitcnt vmcnt(8)
	ds_write2_b32 v35, v77, v78 offset0:172 offset1:238
	s_waitcnt vmcnt(6)
	ds_write2_b32 v36, v38, v39 offset0:48 offset1:114
	s_waitcnt vmcnt(4)
	ds_write2_b32 v36, v54, v55 offset0:180 offset1:246
	s_waitcnt vmcnt(2)
	ds_write2_b32 v37, v79, v80 offset0:56 offset1:122
	s_waitcnt vmcnt(0)
	ds_write2_b32 v37, v81, v82 offset0:188 offset1:254
	s_waitcnt lgkmcnt(0)
	ds_read2_b32 v[22:23], v27 offset0:33 offset1:41
	ds_read2_b32 v[42:43], v27 offset1:8
	ds_read2_b32 v[44:45], v27 offset0:66 offset1:74
	ds_read2_b32 v[46:47], v27 offset0:99 offset1:107
	ds_read2_b32 v[48:49], v27 offset0:132 offset1:140
	ds_read2_b32 v[50:51], v27 offset0:165 offset1:173
	ds_read2_b32 v[52:53], v27 offset0:198 offset1:206
	ds_read2_b32 v[54:55], v27 offset0:231 offset1:239
	s_mov_b32 s7, s1
	v_or_b32_e32 v21, s8, v26
	v_lshl_add_u64 v[56:57], s[6:7], 1, v[12:13]
	v_lshlrev_b32_e32 v58, 11, v21
	v_mov_b32_e32 v59, v3
	s_waitcnt lgkmcnt(6)
	v_cvt_pk_bf16_f32 v38, v42, v22
	s_waitcnt lgkmcnt(4)
	v_cvt_pk_bf16_f32 v39, v44, v46
	s_waitcnt lgkmcnt(2)
	v_cvt_pk_bf16_f32 v40, v48, v50
	s_waitcnt lgkmcnt(0)
	v_cvt_pk_bf16_f32 v41, v52, v54
	v_lshl_add_u64 v[58:59], v[56:57], 0, v[58:59]
	global_store_dwordx4 v[58:59], v[38:41], off sc1
	v_or_b32_e32 v21, s8, v28
	v_lshlrev_b32_e32 v22, 11, v21
	v_cvt_pk_bf16_f32 v38, v43, v23
	v_cvt_pk_bf16_f32 v39, v45, v47
	v_cvt_pk_bf16_f32 v40, v49, v51
	v_cvt_pk_bf16_f32 v41, v53, v55
	ds_read2_b32 v[42:43], v27 offset0:49 offset1:57
	ds_read2_b32 v[44:45], v27 offset0:16 offset1:24
	ds_read2_b32 v[46:47], v27 offset0:82 offset1:90
	ds_read2_b32 v[48:49], v27 offset0:115 offset1:123
	ds_read2_b32 v[50:51], v27 offset0:148 offset1:156
	ds_read2_b32 v[52:53], v27 offset0:181 offset1:189
	ds_read2_b32 v[54:55], v27 offset0:214 offset1:222
	ds_read2_b32 v[58:59], v27 offset0:247 offset1:255
	v_mov_b32_e32 v23, v3
	v_lshl_add_u64 v[22:23], v[56:57], 0, v[22:23]
	v_or_b32_e32 v21, s8, v29
	global_store_dwordx4 v[22:23], v[38:41], off sc1
	v_lshlrev_b32_e32 v22, 11, v21
	v_mov_b32_e32 v23, v3
	s_waitcnt lgkmcnt(6)
	v_cvt_pk_bf16_f32 v38, v44, v42
	s_waitcnt lgkmcnt(4)
	v_cvt_pk_bf16_f32 v39, v46, v48
	s_waitcnt lgkmcnt(2)
	v_cvt_pk_bf16_f32 v40, v50, v52
	s_waitcnt lgkmcnt(0)
	v_cvt_pk_bf16_f32 v41, v54, v58
	v_lshl_add_u64 v[22:23], v[56:57], 0, v[22:23]
	v_or_b32_e32 v21, s8, v30
	global_store_dwordx4 v[22:23], v[38:41], off sc1
	v_lshlrev_b32_e32 v22, 11, v21
	v_mov_b32_e32 v23, v3
	v_cvt_pk_bf16_f32 v38, v45, v43
	v_cvt_pk_bf16_f32 v39, v47, v49
	v_cvt_pk_bf16_f32 v40, v51, v53
	v_cvt_pk_bf16_f32 v41, v55, v59
	v_lshl_add_u64 v[22:23], v[56:57], 0, v[22:23]
	global_store_dwordx4 v[22:23], v[38:41], off sc1
	s_waitcnt lgkmcnt(0)
	s_mov_b64 s[6:7], 0

.LBB0_639:
	s_lshl_b32 s0, s0, 6
	s_and_b32 s7, s0, 0xffc0
	v_or_b32_e32 v21, s7, v24
	s_lshl_b32 s0, s8, 2
	v_mul_u32_u24_e32 v21, 0xc10, v21
	v_lshl_add_u64 v[22:23], v[6:7], 0, s[0:1]
	v_lshlrev_b32_e32 v38, 2, v21
	v_mov_b32_e32 v39, v3
	v_lshl_add_u64 v[22:23], v[22:23], 0, v[38:39]
	v_add_co_u32_e32 v38, vcc, 0x6000, v22
	s_lshl_b32 s0, s7, 1
	s_nop 0
	v_addc_co_u32_e32 v39, vcc, 0, v23, vcc
	v_add_co_u32_e32 v40, vcc, 0xc000, v22
	s_nop 1
	v_addc_co_u32_e32 v41, vcc, 0, v23, vcc
	v_add_co_u32_e32 v42, vcc, 0x12000, v22
	s_nop 1
	v_addc_co_u32_e32 v43, vcc, 0, v23, vcc
	v_add_co_u32_e32 v44, vcc, 0x18000, v22
	s_nop 1
	v_addc_co_u32_e32 v45, vcc, 0, v23, vcc
	v_add_co_u32_e32 v46, vcc, 0x1e000, v22
	s_nop 1
	v_addc_co_u32_e32 v47, vcc, 0, v23, vcc
	v_add_co_u32_e32 v48, vcc, 0x24000, v22
	s_nop 1
	v_addc_co_u32_e32 v49, vcc, 0, v23, vcc
	v_add_co_u32_e32 v50, vcc, 0x2a000, v22
	s_nop 1
	v_addc_co_u32_e32 v51, vcc, 0, v23, vcc
	global_load_dword v21, v[22:23], off nt
	global_load_dword v54, v[38:39], off offset:128 nt
	global_load_dword v55, v[40:41], off offset:256 nt
	global_load_dword v56, v[42:43], off offset:384 nt
	global_load_dword v57, v[44:45], off offset:512 nt
	global_load_dword v58, v[46:47], off offset:640 nt
	global_load_dword v59, v[48:49], off offset:768 nt
	global_load_dword v60, v[50:51], off offset:896 nt
	v_add_co_u32_e32 v38, vcc, 0x30000, v22
	s_nop 1
	v_addc_co_u32_e32 v39, vcc, 0, v23, vcc
	v_add_co_u32_e32 v40, vcc, 0x36000, v22
	s_nop 1
	v_addc_co_u32_e32 v41, vcc, 0, v23, vcc
	v_add_co_u32_e32 v42, vcc, 0x3c000, v22
	s_nop 1
	v_addc_co_u32_e32 v43, vcc, 0, v23, vcc
	v_add_co_u32_e32 v44, vcc, 0x42000, v22
	s_nop 1
	v_addc_co_u32_e32 v45, vcc, 0, v23, vcc
	v_add_co_u32_e32 v46, vcc, 0x48000, v22
	s_nop 1
	v_addc_co_u32_e32 v47, vcc, 0, v23, vcc
	v_add_co_u32_e32 v48, vcc, 0x4e000, v22
	s_nop 1
	v_addc_co_u32_e32 v49, vcc, 0, v23, vcc
	v_add_co_u32_e32 v50, vcc, 0x54000, v22
	s_nop 1
	v_addc_co_u32_e32 v51, vcc, 0, v23, vcc
	v_add_co_u32_e32 v52, vcc, 0x5a000, v22
	s_nop 1
	v_addc_co_u32_e32 v53, vcc, 0, v23, vcc
	global_load_dword v61, v[38:39], off offset:1024 nt
	global_load_dword v62, v[40:41], off offset:1152 nt
	global_load_dword v63, v[42:43], off offset:1280 nt
	global_load_dword v64, v[44:45], off offset:1408 nt
	global_load_dword v65, v[46:47], off offset:1536 nt
	global_load_dword v66, v[48:49], off offset:1664 nt
	global_load_dword v67, v[50:51], off offset:1792 nt
	global_load_dword v68, v[52:53], off offset:1920 nt
	v_add_co_u32_e32 v38, vcc, 0x60000, v22
	s_nop 1
	v_addc_co_u32_e32 v39, vcc, 0, v23, vcc
	v_add_co_u32_e32 v40, vcc, 0x66000, v22
	s_nop 1
	v_addc_co_u32_e32 v41, vcc, 0, v23, vcc
	v_add_co_u32_e32 v42, vcc, 0x6c000, v22
	s_nop 1
	v_addc_co_u32_e32 v43, vcc, 0, v23, vcc
	v_add_co_u32_e32 v44, vcc, 0x72000, v22
	s_nop 1
	v_addc_co_u32_e32 v45, vcc, 0, v23, vcc
	v_add_co_u32_e32 v46, vcc, 0x78000, v22
	s_nop 1
	v_addc_co_u32_e32 v47, vcc, 0, v23, vcc
	v_add_co_u32_e32 v48, vcc, 0x7e000, v22
	s_nop 1
	v_addc_co_u32_e32 v49, vcc, 0, v23, vcc
	v_add_co_u32_e32 v50, vcc, 0x84000, v22
	s_nop 1
	v_addc_co_u32_e32 v51, vcc, 0, v23, vcc
	v_add_co_u32_e32 v52, vcc, 0x8a000, v22
	s_nop 1
	v_addc_co_u32_e32 v53, vcc, 0, v23, vcc
	global_load_dword v69, v[38:39], off offset:2048 nt
	global_load_dword v70, v[40:41], off offset:2176 nt
	global_load_dword v71, v[42:43], off offset:2304 nt
	global_load_dword v72, v[44:45], off offset:2432 nt
	global_load_dword v73, v[46:47], off offset:2560 nt
	global_load_dword v74, v[48:49], off offset:2688 nt
	global_load_dword v75, v[50:51], off offset:2816 nt
	global_load_dword v76, v[52:53], off offset:2944 nt
	v_add_co_u32_e32 v38, vcc, 0x90000, v22
	s_nop 1
	v_addc_co_u32_e32 v39, vcc, 0, v23, vcc
	v_add_co_u32_e32 v40, vcc, 0x96000, v22
	s_nop 1
	v_addc_co_u32_e32 v41, vcc, 0, v23, vcc
	v_add_co_u32_e32 v42, vcc, 0x9c000, v22
	s_nop 1
	v_addc_co_u32_e32 v43, vcc, 0, v23, vcc
	v_add_co_u32_e32 v44, vcc, 0xa2000, v22
	s_nop 1
	v_addc_co_u32_e32 v45, vcc, 0, v23, vcc
	v_add_co_u32_e32 v46, vcc, 0xa8000, v22
	s_nop 1
	v_addc_co_u32_e32 v47, vcc, 0, v23, vcc
	v_add_co_u32_e32 v48, vcc, 0xae000, v22
	s_nop 1
	v_addc_co_u32_e32 v49, vcc, 0, v23, vcc
	v_add_co_u32_e32 v50, vcc, 0xb4000, v22
	s_nop 1
	v_addc_co_u32_e32 v51, vcc, 0, v23, vcc
	v_add_co_u32_e32 v22, vcc, 0xba000, v22
	s_nop 1
	v_addc_co_u32_e32 v23, vcc, 0, v23, vcc
	global_load_dword v52, v[38:39], off offset:3072 nt
	global_load_dword v53, v[40:41], off offset:3200 nt
	global_load_dword v77, v[42:43], off offset:3328 nt
	global_load_dword v78, v[44:45], off offset:3456 nt
	global_load_dword v79, v[46:47], off offset:3584 nt
	global_load_dword v80, v[48:49], off offset:3712 nt
	global_load_dword v81, v[50:51], off offset:3840 nt
	global_load_dword v82, v[22:23], off offset:3968 nt
	s_waitcnt vmcnt(30)
	ds_write2_b32 v25, v21, v54 offset1:66
	s_waitcnt vmcnt(28)
	ds_write2_b32 v25, v55, v56 offset0:132 offset1:198
	s_waitcnt vmcnt(26)
	ds_write2_b32 v31, v57, v58 offset0:8 offset1:74
	s_waitcnt vmcnt(24)
	ds_write2_b32 v31, v59, v60 offset0:140 offset1:206
	s_waitcnt vmcnt(22)
	ds_write2_b32 v32, v61, v62 offset0:16 offset1:82
	s_waitcnt vmcnt(20)
	ds_write2_b32 v32, v63, v64 offset0:148 offset1:214
	s_waitcnt vmcnt(18)
	ds_write2_b32 v33, v65, v66 offset0:24 offset1:90
	s_waitcnt vmcnt(16)
	ds_write2_b32 v33, v67, v68 offset0:156 offset1:222
	s_waitcnt vmcnt(14)
	ds_write2_b32 v34, v69, v70 offset0:32 offset1:98
	s_waitcnt vmcnt(12)
	ds_write2_b32 v34, v71, v72 offset0:164 offset1:230
	s_waitcnt vmcnt(10)
	ds_write2_b32 v35, v73, v74 offset0:40 offset1:106
	s_waitcnt vmcnt(8)
	ds_write2_b32 v35, v75, v76 offset0:172 offset1:238
	s_waitcnt vmcnt(6)
	ds_write2_b32 v36, v52, v53 offset0:48 offset1:114
	s_waitcnt vmcnt(4)
	ds_write2_b32 v36, v77, v78 offset0:180 offset1:246
	s_waitcnt vmcnt(2)
	ds_write2_b32 v37, v79, v80 offset0:56 offset1:122
	s_waitcnt vmcnt(0)
	ds_write2_b32 v37, v81, v82 offset0:188 offset1:254
	s_waitcnt lgkmcnt(0)
	ds_read2_b32 v[22:23], v27 offset0:33 offset1:41
	ds_read2_b32 v[42:43], v27 offset1:8
	ds_read2_b32 v[44:45], v27 offset0:66 offset1:74
	ds_read2_b32 v[46:47], v27 offset0:99 offset1:107
	ds_read2_b32 v[48:49], v27 offset0:132 offset1:140
	ds_read2_b32 v[50:51], v27 offset0:165 offset1:173
	ds_read2_b32 v[52:53], v27 offset0:198 offset1:206
	ds_read2_b32 v[54:55], v27 offset0:231 offset1:239
	v_add_u32_e32 v58, s6, v26
	v_mov_b32_e32 v59, v3
	v_lshl_add_u64 v[56:57], v[14:15], 0, s[0:1]
	v_lshlrev_b64 v[58:59], 11, v[58:59]
	s_waitcnt lgkmcnt(6)
	v_cvt_pk_bf16_f32 v38, v42, v22
	s_waitcnt lgkmcnt(4)
	v_cvt_pk_bf16_f32 v39, v44, v46
	s_waitcnt lgkmcnt(2)
	v_cvt_pk_bf16_f32 v40, v48, v50
	s_waitcnt lgkmcnt(0)
	v_cvt_pk_bf16_f32 v41, v52, v54
	v_lshl_add_u64 v[58:59], v[56:57], 0, v[58:59]
	global_store_dwordx4 v[58:59], v[38:41], off sc1
	v_add_u32_e32 v22, s6, v28
	s_nop 0
	v_cvt_pk_bf16_f32 v38, v43, v23
	v_cvt_pk_bf16_f32 v39, v45, v47
	v_cvt_pk_bf16_f32 v40, v49, v51
	v_cvt_pk_bf16_f32 v41, v53, v55
	v_mov_b32_e32 v23, v3
	ds_read2_b32 v[42:43], v27 offset0:49 offset1:57
	ds_read2_b32 v[44:45], v27 offset0:16 offset1:24
	ds_read2_b32 v[46:47], v27 offset0:82 offset1:90
	ds_read2_b32 v[48:49], v27 offset0:115 offset1:123
	ds_read2_b32 v[50:51], v27 offset0:148 offset1:156
	ds_read2_b32 v[52:53], v27 offset0:181 offset1:189
	ds_read2_b32 v[54:55], v27 offset0:214 offset1:222
	ds_read2_b32 v[58:59], v27 offset0:247 offset1:255
	v_lshlrev_b64 v[22:23], 11, v[22:23]
	v_lshl_add_u64 v[22:23], v[56:57], 0, v[22:23]
	global_store_dwordx4 v[22:23], v[38:41], off sc1
	v_add_u32_e32 v22, s6, v29
	v_mov_b32_e32 v23, v3
	v_lshlrev_b64 v[22:23], 11, v[22:23]
	s_waitcnt lgkmcnt(6)
	v_cvt_pk_bf16_f32 v38, v44, v42
	s_waitcnt lgkmcnt(4)
	v_cvt_pk_bf16_f32 v39, v46, v48
	s_waitcnt lgkmcnt(2)
	v_cvt_pk_bf16_f32 v40, v50, v52
	s_waitcnt lgkmcnt(0)
	v_cvt_pk_bf16_f32 v41, v54, v58
	v_lshl_add_u64 v[22:23], v[56:57], 0, v[22:23]
	global_store_dwordx4 v[22:23], v[38:41], off sc1
	v_add_u32_e32 v22, s6, v30
	v_mov_b32_e32 v23, v3
	v_lshlrev_b64 v[22:23], 11, v[22:23]
	v_cvt_pk_bf16_f32 v38, v45, v43
	v_cvt_pk_bf16_f32 v39, v47, v49
	v_cvt_pk_bf16_f32 v40, v51, v53
	v_cvt_pk_bf16_f32 v41, v55, v59
	v_lshl_add_u64 v[22:23], v[56:57], 0, v[22:23]
	global_store_dwordx4 v[22:23], v[38:41], off sc1
	s_waitcnt lgkmcnt(0)

.LBB0_641:
	s_andn2_b64 vcc, exec, s[6:7]
	s_cbranch_vccnz .LBB0_646
	s_lshl_b32 s0, s31, 1
	s_and_b32 s0, s0, 0x3fc0
	s_add_i32 s6, s0, 0xffffea00
	s_and_b32 s8, s15, 0x3e0
	v_or_b32_e32 v22, s6, v24
	s_mov_b64 s[12:13], -1
	s_and_b64 vcc, exec, s[4:5]
	v_or_b32_e32 v40, s8, v26
	v_or_b32_e32 v39, s8, v28
	v_or_b32_e32 v38, s8, v29
	v_or_b32_e32 v21, s8, v30
	s_cbranch_vccz .LBB0_644
	s_lshl_b32 s0, s8, 2
	v_mov_b32_e32 v23, v3
	v_lshl_add_u64 v[42:43], v[8:9], 0, s[0:1]
	v_lshlrev_b64 v[44:45], 12, v[22:23]
	v_or_b32_e32 v46, 2, v22
	v_mov_b32_e32 v47, v3
	v_or_b32_e32 v48, 4, v22
	v_mov_b32_e32 v49, v3
	v_or_b32_e32 v50, 6, v22
	v_mov_b32_e32 v51, v3
	v_or_b32_e32 v52, 8, v22
	v_mov_b32_e32 v53, v3
	v_or_b32_e32 v54, 10, v22
	v_mov_b32_e32 v55, v3
	v_or_b32_e32 v56, 12, v22
	v_mov_b32_e32 v57, v3
	v_or_b32_e32 v58, 14, v22
	v_mov_b32_e32 v59, v3
	v_lshl_add_u64 v[44:45], v[42:43], 0, v[44:45]
	v_lshlrev_b64 v[46:47], 12, v[46:47]
	v_lshlrev_b64 v[48:49], 12, v[48:49]
	v_lshlrev_b64 v[50:51], 12, v[50:51]
	v_lshlrev_b64 v[52:53], 12, v[52:53]
	v_lshlrev_b64 v[54:55], 12, v[54:55]
	v_lshlrev_b64 v[56:57], 12, v[56:57]
	v_lshlrev_b64 v[58:59], 12, v[58:59]
	v_lshl_add_u64 v[46:47], v[42:43], 0, v[46:47]
	v_lshl_add_u64 v[48:49], v[42:43], 0, v[48:49]
	v_lshl_add_u64 v[50:51], v[42:43], 0, v[50:51]
	v_lshl_add_u64 v[52:53], v[42:43], 0, v[52:53]
	v_lshl_add_u64 v[54:55], v[42:43], 0, v[54:55]
	v_lshl_add_u64 v[56:57], v[42:43], 0, v[56:57]
	v_lshl_add_u64 v[58:59], v[42:43], 0, v[58:59]
	global_load_dword v23, v[44:45], off nt
	global_load_dword v41, v[46:47], off nt
	global_load_dword v60, v[48:49], off nt
	global_load_dword v61, v[50:51], off nt
	global_load_dword v62, v[52:53], off nt
	global_load_dword v63, v[54:55], off nt
	global_load_dword v64, v[56:57], off nt
	global_load_dword v65, v[58:59], off nt
	v_or_b32_e32 v44, 16, v22
	v_mov_b32_e32 v45, v3
	v_lshlrev_b64 v[44:45], 12, v[44:45]
	v_or_b32_e32 v46, 18, v22
	v_mov_b32_e32 v47, v3
	v_or_b32_e32 v48, 20, v22
	v_mov_b32_e32 v49, v3
	v_or_b32_e32 v50, 22, v22
	v_mov_b32_e32 v51, v3
	v_or_b32_e32 v52, 24, v22
	v_mov_b32_e32 v53, v3
	v_or_b32_e32 v54, 26, v22
	v_mov_b32_e32 v55, v3
	v_or_b32_e32 v56, 28, v22
	v_mov_b32_e32 v57, v3
	v_or_b32_e32 v58, 30, v22
	v_mov_b32_e32 v59, v3
	v_lshl_add_u64 v[44:45], v[42:43], 0, v[44:45]
	v_lshlrev_b64 v[46:47], 12, v[46:47]
	v_lshlrev_b64 v[48:49], 12, v[48:49]
	v_lshlrev_b64 v[50:51], 12, v[50:51]
	v_lshlrev_b64 v[52:53], 12, v[52:53]
	v_lshlrev_b64 v[54:55], 12, v[54:55]
	v_lshlrev_b64 v[56:57], 12, v[56:57]
	v_lshlrev_b64 v[58:59], 12, v[58:59]
	v_lshl_add_u64 v[46:47], v[42:43], 0, v[46:47]
	v_lshl_add_u64 v[48:49], v[42:43], 0, v[48:49]
	v_lshl_add_u64 v[50:51], v[42:43], 0, v[50:51]
	v_lshl_add_u64 v[52:53], v[42:43], 0, v[52:53]
	v_lshl_add_u64 v[54:55], v[42:43], 0, v[54:55]
	v_lshl_add_u64 v[56:57], v[42:43], 0, v[56:57]
	v_lshl_add_u64 v[58:59], v[42:43], 0, v[58:59]
	global_load_dword v66, v[44:45], off nt
	global_load_dword v67, v[46:47], off nt
	global_load_dword v68, v[48:49], off nt
	global_load_dword v69, v[50:51], off nt
	global_load_dword v70, v[52:53], off nt
	global_load_dword v71, v[54:55], off nt
	global_load_dword v72, v[56:57], off nt
	global_load_dword v73, v[58:59], off nt
	v_or_b32_e32 v44, 32, v22
	v_mov_b32_e32 v45, v3
	v_lshlrev_b64 v[44:45], 12, v[44:45]
	v_or_b32_e32 v46, 34, v22
	v_mov_b32_e32 v47, v3
	v_or_b32_e32 v48, 36, v22
	v_mov_b32_e32 v49, v3
	v_or_b32_e32 v50, 38, v22
	v_mov_b32_e32 v51, v3
	v_or_b32_e32 v52, 40, v22
	v_mov_b32_e32 v53, v3
	v_or_b32_e32 v54, 42, v22
	v_mov_b32_e32 v55, v3
	v_or_b32_e32 v56, 44, v22
	v_mov_b32_e32 v57, v3
	v_or_b32_e32 v58, 46, v22
	v_mov_b32_e32 v59, v3
	v_lshl_add_u64 v[44:45], v[42:43], 0, v[44:45]
	v_lshlrev_b64 v[46:47], 12, v[46:47]
	v_lshlrev_b64 v[48:49], 12, v[48:49]
	v_lshlrev_b64 v[50:51], 12, v[50:51]
	v_lshlrev_b64 v[52:53], 12, v[52:53]
	v_lshlrev_b64 v[54:55], 12, v[54:55]
	v_lshlrev_b64 v[56:57], 12, v[56:57]
	v_lshlrev_b64 v[58:59], 12, v[58:59]
	v_lshl_add_u64 v[46:47], v[42:43], 0, v[46:47]
	v_lshl_add_u64 v[48:49], v[42:43], 0, v[48:49]
	v_lshl_add_u64 v[50:51], v[42:43], 0, v[50:51]
	v_lshl_add_u64 v[52:53], v[42:43], 0, v[52:53]
	v_lshl_add_u64 v[54:55], v[42:43], 0, v[54:55]
	v_lshl_add_u64 v[56:57], v[42:43], 0, v[56:57]
	v_lshl_add_u64 v[58:59], v[42:43], 0, v[58:59]
	global_load_dword v74, v[44:45], off nt
	global_load_dword v75, v[46:47], off nt
	global_load_dword v76, v[48:49], off nt
	global_load_dword v77, v[50:51], off nt
	global_load_dword v78, v[52:53], off nt
	global_load_dword v79, v[54:55], off nt
	global_load_dword v80, v[56:57], off nt
	global_load_dword v81, v[58:59], off nt
	v_or_b32_e32 v44, 48, v22
	v_mov_b32_e32 v45, v3
	v_lshlrev_b64 v[44:45], 12, v[44:45]
	v_or_b32_e32 v46, 50, v22
	v_mov_b32_e32 v47, v3
	v_or_b32_e32 v48, 52, v22
	v_mov_b32_e32 v49, v3
	v_or_b32_e32 v50, 54, v22
	v_mov_b32_e32 v51, v3
	v_or_b32_e32 v52, 56, v22
	v_mov_b32_e32 v53, v3
	v_or_b32_e32 v54, 58, v22
	v_mov_b32_e32 v55, v3
	v_or_b32_e32 v56, 60, v22
	v_mov_b32_e32 v57, v3
	v_or_b32_e32 v58, 62, v22
	v_mov_b32_e32 v59, v3
	v_lshl_add_u64 v[44:45], v[42:43], 0, v[44:45]
	v_lshlrev_b64 v[46:47], 12, v[46:47]
	v_lshlrev_b64 v[48:49], 12, v[48:49]
	v_lshlrev_b64 v[50:51], 12, v[50:51]
	v_lshlrev_b64 v[52:53], 12, v[52:53]
	v_lshlrev_b64 v[54:55], 12, v[54:55]
	v_lshlrev_b64 v[56:57], 12, v[56:57]
	v_lshlrev_b64 v[58:59], 12, v[58:59]
	v_lshl_add_u64 v[46:47], v[42:43], 0, v[46:47]
	v_lshl_add_u64 v[48:49], v[42:43], 0, v[48:49]
	v_lshl_add_u64 v[50:51], v[42:43], 0, v[50:51]
	v_lshl_add_u64 v[52:53], v[42:43], 0, v[52:53]
	v_lshl_add_u64 v[54:55], v[42:43], 0, v[54:55]
	v_lshl_add_u64 v[56:57], v[42:43], 0, v[56:57]
	v_lshl_add_u64 v[42:43], v[42:43], 0, v[58:59]
	global_load_dword v58, v[44:45], off nt
	global_load_dword v59, v[46:47], off nt
	global_load_dword v82, v[48:49], off nt
	global_load_dword v83, v[50:51], off nt
	global_load_dword v84, v[52:53], off nt
	global_load_dword v85, v[54:55], off nt
	global_load_dword v86, v[56:57], off nt
	global_load_dword v87, v[42:43], off nt
	s_waitcnt vmcnt(30)
	ds_write2_b32 v25, v23, v41 offset1:66
	s_waitcnt vmcnt(28)
	ds_write2_b32 v25, v60, v61 offset0:132 offset1:198
	s_waitcnt vmcnt(26)
	ds_write2_b32 v31, v62, v63 offset0:8 offset1:74
	s_waitcnt vmcnt(24)
	ds_write2_b32 v31, v64, v65 offset0:140 offset1:206
	s_waitcnt vmcnt(22)
	ds_write2_b32 v32, v66, v67 offset0:16 offset1:82
	s_waitcnt vmcnt(20)
	ds_write2_b32 v32, v68, v69 offset0:148 offset1:214
	s_waitcnt vmcnt(18)
	ds_write2_b32 v33, v70, v71 offset0:24 offset1:90
	s_waitcnt vmcnt(16)
	ds_write2_b32 v33, v72, v73 offset0:156 offset1:222
	s_waitcnt vmcnt(14)
	ds_write2_b32 v34, v74, v75 offset0:32 offset1:98
	s_waitcnt vmcnt(12)
	ds_write2_b32 v34, v76, v77 offset0:164 offset1:230
	s_waitcnt vmcnt(10)
	ds_write2_b32 v35, v78, v79 offset0:40 offset1:106
	s_waitcnt vmcnt(8)
	ds_write2_b32 v35, v80, v81 offset0:172 offset1:238
	s_waitcnt vmcnt(6)
	ds_write2_b32 v36, v58, v59 offset0:48 offset1:114
	s_waitcnt vmcnt(4)
	ds_write2_b32 v36, v82, v83 offset0:180 offset1:246
	s_waitcnt vmcnt(2)
	ds_write2_b32 v37, v84, v85 offset0:56 offset1:122
	s_waitcnt vmcnt(0)
	ds_write2_b32 v37, v86, v87 offset0:188 offset1:254
	s_waitcnt lgkmcnt(0)
	ds_read2_b32 v[46:47], v27 offset0:33 offset1:41
	ds_read2_b32 v[48:49], v27 offset1:8
	ds_read2_b32 v[50:51], v27 offset0:66 offset1:74
	ds_read2_b32 v[52:53], v27 offset0:99 offset1:107
	ds_read2_b32 v[54:55], v27 offset0:132 offset1:140
	ds_read2_b32 v[56:57], v27 offset0:165 offset1:173
	ds_read2_b32 v[58:59], v27 offset0:198 offset1:206
	ds_read2_b32 v[60:61], v27 offset0:231 offset1:239
	s_mov_b32 s7, s1
	v_mul_u32_u24_e32 v23, 0xb00, v40
	v_lshl_add_u64 v[62:63], s[6:7], 1, v[16:17]
	v_lshlrev_b32_e32 v64, 1, v23
	v_mov_b32_e32 v65, v3
	s_waitcnt lgkmcnt(6)
	v_cvt_pk_bf16_f32 v42, v48, v46
	s_waitcnt lgkmcnt(4)
	v_cvt_pk_bf16_f32 v43, v50, v52
	s_waitcnt lgkmcnt(2)
	v_cvt_pk_bf16_f32 v44, v54, v56
	s_waitcnt lgkmcnt(0)
	v_cvt_pk_bf16_f32 v45, v58, v60
	v_lshl_add_u64 v[64:65], v[62:63], 0, v[64:65]
	global_store_dwordx4 v[64:65], v[42:45], off sc1
	v_mul_u32_u24_e32 v23, 0xb00, v39
	v_lshlrev_b32_e32 v46, 1, v23
	v_cvt_pk_bf16_f32 v42, v49, v47
	v_cvt_pk_bf16_f32 v43, v51, v53
	v_cvt_pk_bf16_f32 v44, v55, v57
	v_cvt_pk_bf16_f32 v45, v59, v61
	ds_read2_b32 v[48:49], v27 offset0:16 offset1:24
	ds_read2_b32 v[50:51], v27 offset0:49 offset1:57
	ds_read2_b32 v[52:53], v27 offset0:82 offset1:90
	ds_read2_b32 v[54:55], v27 offset0:115 offset1:123
	ds_read2_b32 v[56:57], v27 offset0:148 offset1:156
	ds_read2_b32 v[58:59], v27 offset0:181 offset1:189
	ds_read2_b32 v[60:61], v27 offset0:214 offset1:222
	ds_read2_b32 v[64:65], v27 offset0:247 offset1:255
	v_mov_b32_e32 v47, v3
	v_lshl_add_u64 v[46:47], v[62:63], 0, v[46:47]
	v_mul_u32_u24_e32 v23, 0xb00, v38
	global_store_dwordx4 v[46:47], v[42:45], off sc1
	v_lshlrev_b32_e32 v46, 1, v23
	v_mov_b32_e32 v47, v3
	s_waitcnt lgkmcnt(6)
	v_cvt_pk_bf16_f32 v42, v48, v50
	s_waitcnt lgkmcnt(4)
	v_cvt_pk_bf16_f32 v43, v52, v54
	s_waitcnt lgkmcnt(2)
	v_cvt_pk_bf16_f32 v44, v56, v58
	s_waitcnt lgkmcnt(0)
	v_cvt_pk_bf16_f32 v45, v60, v64
	v_lshl_add_u64 v[46:47], v[62:63], 0, v[46:47]
	v_mul_u32_u24_e32 v23, 0xb00, v21
	global_store_dwordx4 v[46:47], v[42:45], off sc1
	v_lshlrev_b32_e32 v46, 1, v23
	v_mov_b32_e32 v47, v3
	v_cvt_pk_bf16_f32 v42, v49, v51
	v_cvt_pk_bf16_f32 v43, v53, v55
	v_cvt_pk_bf16_f32 v44, v57, v59
	v_cvt_pk_bf16_f32 v45, v61, v65
	v_lshl_add_u64 v[46:47], v[62:63], 0, v[46:47]
	global_store_dwordx4 v[46:47], v[42:45], off sc1
	s_waitcnt lgkmcnt(0)
	s_mov_b64 s[12:13], 0
.LBB0_644:
	s_andn2_b64 vcc, exec, s[12:13]
	s_cbranch_vccnz .LBB0_646
	s_lshl_b32 s0, s8, 2
	v_lshl_add_u64 v[42:43], v[10:11], 0, s[0:1]
	v_lshlrev_b32_e32 v22, 10, v22
	v_mov_b32_e32 v23, v3
	v_lshl_add_u64 v[22:23], v[22:23], 2, v[42:43]
	v_add_co_u32_e32 v42, vcc, 0x2000, v22
	s_mov_b32 s7, s1
	s_nop 0
	v_addc_co_u32_e32 v43, vcc, 0, v23, vcc
	v_add_co_u32_e32 v44, vcc, 0x4000, v22
	v_mul_u32_u24_e32 v40, 0xb00, v40
	s_nop 0
	v_addc_co_u32_e32 v45, vcc, 0, v23, vcc
	v_add_co_u32_e32 v46, vcc, s17, v22
	v_mul_u32_u24_e32 v38, 0xb00, v38
	s_nop 0
	v_addc_co_u32_e32 v47, vcc, 0, v23, vcc
	v_add_co_u32_e32 v48, vcc, 0x8000, v22
	s_nop 1
	v_addc_co_u32_e32 v49, vcc, 0, v23, vcc
	v_add_co_u32_e32 v50, vcc, 0xa000, v22
	s_nop 1
	v_addc_co_u32_e32 v51, vcc, 0, v23, vcc
	v_add_co_u32_e32 v52, vcc, s18, v22
	s_nop 1
	v_addc_co_u32_e32 v53, vcc, 0, v23, vcc
	v_add_co_u32_e32 v54, vcc, 0xe000, v22
	s_nop 1
	v_addc_co_u32_e32 v55, vcc, 0, v23, vcc
	global_load_dword v41, v[22:23], off nt
	global_load_dword v58, v[42:43], off nt
	global_load_dword v59, v[44:45], off nt
	global_load_dword v60, v[46:47], off nt
	global_load_dword v61, v[48:49], off nt
	global_load_dword v62, v[50:51], off nt
	global_load_dword v63, v[52:53], off nt
	global_load_dword v64, v[54:55], off nt
	v_add_co_u32_e32 v42, vcc, 0x10000, v22
	s_nop 1
	v_addc_co_u32_e32 v43, vcc, 0, v23, vcc
	v_add_co_u32_e32 v44, vcc, s19, v22
	s_nop 1
	v_addc_co_u32_e32 v45, vcc, 0, v23, vcc
	v_add_co_u32_e32 v46, vcc, 0x14000, v22
	s_nop 1
	v_addc_co_u32_e32 v47, vcc, 0, v23, vcc
	v_add_co_u32_e32 v48, vcc, 0x16000, v22
	s_nop 1
	v_addc_co_u32_e32 v49, vcc, 0, v23, vcc
	v_add_co_u32_e32 v50, vcc, s20, v22
	s_nop 1
	v_addc_co_u32_e32 v51, vcc, 0, v23, vcc
	v_add_co_u32_e32 v52, vcc, 0x1a000, v22
	s_nop 1
	v_addc_co_u32_e32 v53, vcc, 0, v23, vcc
	v_add_co_u32_e32 v54, vcc, 0x1c000, v22
	s_nop 1
	v_addc_co_u32_e32 v55, vcc, 0, v23, vcc
	v_add_co_u32_e32 v56, vcc, s21, v22
	s_nop 1
	v_addc_co_u32_e32 v57, vcc, 0, v23, vcc
	global_load_dword v65, v[42:43], off nt
	global_load_dword v66, v[44:45], off nt
	global_load_dword v67, v[46:47], off nt
	global_load_dword v68, v[48:49], off nt
	global_load_dword v69, v[50:51], off nt
	global_load_dword v70, v[52:53], off nt
	global_load_dword v71, v[54:55], off nt
	global_load_dword v72, v[56:57], off nt
	v_add_co_u32_e32 v42, vcc, 0x20000, v22
	s_nop 1
	v_addc_co_u32_e32 v43, vcc, 0, v23, vcc
	v_add_co_u32_e32 v44, vcc, 0x22000, v22
	s_nop 1
	v_addc_co_u32_e32 v45, vcc, 0, v23, vcc
	v_add_co_u32_e32 v46, vcc, s24, v22
	s_nop 1
	v_addc_co_u32_e32 v47, vcc, 0, v23, vcc
	v_add_co_u32_e32 v48, vcc, 0x26000, v22
	s_nop 1
	v_addc_co_u32_e32 v49, vcc, 0, v23, vcc
	v_add_co_u32_e32 v50, vcc, 0x28000, v22
	s_nop 1
	v_addc_co_u32_e32 v51, vcc, 0, v23, vcc
	v_add_co_u32_e32 v52, vcc, s25, v22
	s_nop 1
	v_addc_co_u32_e32 v53, vcc, 0, v23, vcc
	v_add_co_u32_e32 v54, vcc, 0x2c000, v22
	s_nop 1
	v_addc_co_u32_e32 v55, vcc, 0, v23, vcc
	v_add_co_u32_e32 v56, vcc, 0x2e000, v22
	s_nop 1
	v_addc_co_u32_e32 v57, vcc, 0, v23, vcc
	global_load_dword v73, v[42:43], off nt
	global_load_dword v74, v[44:45], off nt
	global_load_dword v75, v[46:47], off nt
	global_load_dword v76, v[48:49], off nt
	global_load_dword v77, v[50:51], off nt
	global_load_dword v78, v[52:53], off nt
	global_load_dword v79, v[54:55], off nt
	global_load_dword v80, v[56:57], off nt
	v_add_co_u32_e32 v42, vcc, s26, v22
	s_nop 1
	v_addc_co_u32_e32 v43, vcc, 0, v23, vcc
	v_add_co_u32_e32 v44, vcc, 0x32000, v22
	s_nop 1
	v_addc_co_u32_e32 v45, vcc, 0, v23, vcc
	v_add_co_u32_e32 v46, vcc, 0x34000, v22
	s_nop 1
	v_addc_co_u32_e32 v47, vcc, 0, v23, vcc
	v_add_co_u32_e32 v48, vcc, s27, v22
	s_nop 1
	v_addc_co_u32_e32 v49, vcc, 0, v23, vcc
	v_add_co_u32_e32 v50, vcc, 0x38000, v22
	s_nop 1
	v_addc_co_u32_e32 v51, vcc, 0, v23, vcc
	v_add_co_u32_e32 v52, vcc, 0x3a000, v22
	s_nop 1
	v_addc_co_u32_e32 v53, vcc, 0, v23, vcc
	v_add_co_u32_e32 v54, vcc, s28, v22
	s_nop 1
	v_addc_co_u32_e32 v55, vcc, 0, v23, vcc
	v_add_co_u32_e32 v22, vcc, 0x3e000, v22
	s_nop 1
	v_addc_co_u32_e32 v23, vcc, 0, v23, vcc
	global_load_dword v56, v[42:43], off nt
	global_load_dword v57, v[44:45], off nt
	global_load_dword v81, v[46:47], off nt
	global_load_dword v82, v[48:49], off nt
	global_load_dword v83, v[50:51], off nt
	global_load_dword v84, v[52:53], off nt
	global_load_dword v85, v[54:55], off nt
	global_load_dword v86, v[22:23], off nt
	s_waitcnt vmcnt(30)
	ds_write2_b32 v25, v41, v58 offset1:66
	s_waitcnt vmcnt(28)
	ds_write2_b32 v25, v59, v60 offset0:132 offset1:198
	s_waitcnt vmcnt(26)
	ds_write2_b32 v31, v61, v62 offset0:8 offset1:74
	s_waitcnt vmcnt(24)
	ds_write2_b32 v31, v63, v64 offset0:140 offset1:206
	s_waitcnt vmcnt(22)
	ds_write2_b32 v32, v65, v66 offset0:16 offset1:82
	s_waitcnt vmcnt(20)
	ds_write2_b32 v32, v67, v68 offset0:148 offset1:214
	s_waitcnt vmcnt(18)
	ds_write2_b32 v33, v69, v70 offset0:24 offset1:90
	s_waitcnt vmcnt(16)
	ds_write2_b32 v33, v71, v72 offset0:156 offset1:222
	s_waitcnt vmcnt(14)
	ds_write2_b32 v34, v73, v74 offset0:32 offset1:98
	s_waitcnt vmcnt(12)
	ds_write2_b32 v34, v75, v76 offset0:164 offset1:230
	s_waitcnt vmcnt(10)
	ds_write2_b32 v35, v77, v78 offset0:40 offset1:106
	s_waitcnt vmcnt(8)
	ds_write2_b32 v35, v79, v80 offset0:172 offset1:238
	s_waitcnt vmcnt(6)
	ds_write2_b32 v36, v56, v57 offset0:48 offset1:114
	s_waitcnt vmcnt(4)
	ds_write2_b32 v36, v81, v82 offset0:180 offset1:246
	s_waitcnt vmcnt(2)
	ds_write2_b32 v37, v83, v84 offset0:56 offset1:122
	s_waitcnt vmcnt(0)
	ds_write2_b32 v37, v85, v86 offset0:188 offset1:254
	s_waitcnt lgkmcnt(0)
	ds_read2_b32 v[42:43], v27 offset0:33 offset1:41
	ds_read2_b32 v[44:45], v27 offset0:66 offset1:74
	ds_read2_b32 v[46:47], v27 offset0:99 offset1:107
	ds_read2_b32 v[48:49], v27 offset1:8
	ds_read2_b32 v[50:51], v27 offset0:132 offset1:140
	ds_read2_b32 v[52:53], v27 offset0:165 offset1:173
	ds_read2_b32 v[54:55], v27 offset0:198 offset1:206
	ds_read2_b32 v[56:57], v27 offset0:231 offset1:239
	s_waitcnt lgkmcnt(4)
	v_mul_f32_e32 v41, 0x42800000, v48
	v_mul_f32_e32 v42, 0x42800000, v42
	v_mov_b32_e32 v58, v3
	v_cvt_pk_fp8_f32 v58, v41, v42
	v_mul_f32_e32 v41, 0x42800000, v44
	v_mul_f32_e32 v42, 0x42800000, v46
	s_waitcnt lgkmcnt(3)
	v_mul_f32_e32 v44, 0x42800000, v50
	s_waitcnt lgkmcnt(2)
	v_mul_f32_e32 v46, 0x42800000, v52
	v_mov_b32_e32 v59, v3
	v_cvt_pk_fp8_f32 v59, v44, v46
	v_cvt_pk_fp8_f32 v58, v41, v42 op_sel:[0,0,1]
	s_waitcnt lgkmcnt(1)
	v_mul_f32_e32 v41, 0x42800000, v54
	s_waitcnt lgkmcnt(0)
	v_mul_f32_e32 v42, 0x42800000, v56
	v_cvt_pk_fp8_f32 v59, v41, v42 op_sel:[0,0,1]
	v_lshl_add_u64 v[22:23], v[18:19], 0, s[6:7]
	v_mov_b32_e32 v41, v3
	v_lshl_add_u64 v[40:41], v[22:23], 0, v[40:41]
	global_store_dwordx2 v[40:41], v[58:59], off sc1
	v_mul_f32_e32 v41, 0x42800000, v49
	v_mul_f32_e32 v42, 0x42800000, v43
	v_mov_b32_e32 v40, v3
	v_cvt_pk_fp8_f32 v40, v41, v42
	v_mul_f32_e32 v42, 0x42800000, v45
	v_mul_f32_e32 v44, 0x42800000, v51
	v_mul_f32_e32 v45, 0x42800000, v53
	v_mov_b32_e32 v41, v3
	v_cvt_pk_fp8_f32 v41, v44, v45
	v_mul_f32_e32 v43, 0x42800000, v47
	v_cvt_pk_fp8_f32 v40, v42, v43 op_sel:[0,0,1]
	v_mul_f32_e32 v42, 0x42800000, v55
	v_mul_f32_e32 v43, 0x42800000, v57
	v_cvt_pk_fp8_f32 v41, v42, v43 op_sel:[0,0,1]
	v_mul_u32_u24_e32 v42, 0xb00, v39
	v_mov_b32_e32 v43, v3
	v_lshl_add_u64 v[42:43], v[22:23], 0, v[42:43]
	global_store_dwordx2 v[42:43], v[40:41], off sc1
	ds_read2_b32 v[40:41], v27 offset0:16 offset1:24
	ds_read2_b32 v[42:43], v27 offset0:49 offset1:57
	ds_read2_b32 v[44:45], v27 offset0:82 offset1:90
	ds_read2_b32 v[46:47], v27 offset0:115 offset1:123
	ds_read2_b32 v[48:49], v27 offset0:148 offset1:156
	ds_read2_b32 v[50:51], v27 offset0:181 offset1:189
	ds_read2_b32 v[52:53], v27 offset0:214 offset1:222
	ds_read2_b32 v[54:55], v27 offset0:247 offset1:255
	s_waitcnt lgkmcnt(7)
	v_mul_f32_e32 v39, 0x42800000, v40
	s_waitcnt lgkmcnt(6)
	v_mul_f32_e32 v40, 0x42800000, v42
	v_mov_b32_e32 v56, v3
	v_cvt_pk_fp8_f32 v56, v39, v40
	s_waitcnt lgkmcnt(5)
	v_mul_f32_e32 v39, 0x42800000, v44
	s_waitcnt lgkmcnt(3)
	v_mul_f32_e32 v42, 0x42800000, v48
	s_waitcnt lgkmcnt(2)
	v_mul_f32_e32 v44, 0x42800000, v50
	v_mov_b32_e32 v57, v3
	v_cvt_pk_fp8_f32 v57, v42, v44
	v_mul_f32_e32 v40, 0x42800000, v46
	v_cvt_pk_fp8_f32 v56, v39, v40 op_sel:[0,0,1]
	s_waitcnt lgkmcnt(1)
	v_mul_f32_e32 v39, 0x42800000, v52
	s_waitcnt lgkmcnt(0)
	v_mul_f32_e32 v40, 0x42800000, v54
	v_cvt_pk_fp8_f32 v57, v39, v40 op_sel:[0,0,1]
	v_mov_b32_e32 v39, v3
	v_lshl_add_u64 v[38:39], v[22:23], 0, v[38:39]
	v_mul_f32_e32 v40, 0x42800000, v43
	global_store_dwordx2 v[38:39], v[56:57], off sc1
	v_mul_f32_e32 v39, 0x42800000, v41
	v_mov_b32_e32 v38, v3
	v_cvt_pk_fp8_f32 v38, v39, v40
	v_mul_f32_e32 v42, 0x42800000, v49
	v_mul_f32_e32 v43, 0x42800000, v51
	v_mov_b32_e32 v39, v3
	v_cvt_pk_fp8_f32 v39, v42, v43
	v_mul_f32_e32 v40, 0x42800000, v45
	v_mul_f32_e32 v41, 0x42800000, v47
	v_cvt_pk_fp8_f32 v38, v40, v41 op_sel:[0,0,1]
	v_mul_f32_e32 v40, 0x42800000, v53
	v_mul_f32_e32 v41, 0x42800000, v55
	v_cvt_pk_fp8_f32 v39, v40, v41 op_sel:[0,0,1]
	v_mul_u32_u24_e32 v40, 0xb00, v21
	v_mov_b32_e32 v41, v3
	v_lshl_add_u64 v[22:23], v[22:23], 0, v[40:41]
	global_store_dwordx2 v[22:23], v[38:39], off sc1
	s_waitcnt lgkmcnt(0)
